# v15 + write-through (sc1) stores in the residual epilogues so that the grid barrier's L2 write-back has little to flush
# baseline (speedup 1.0000x reference)
;     static __device__ __forceinline__ void run(const f32x4 (&acc)[2][2][4][2], const Unit& u, int wr, int wc, int fr, int fq, const float* xin, float* xout, const float* gate, float gs, const float* lazy_ssq, const float* lazy_g, ...
;     ...
;             for (int m = 0; m < 4; ++m) { rl[ai][m] = LAZY ? __builtin_amdgcn_rsqf(lazy_ssq[row0 + ai * HALF + m * 16] * (1.0f / 1024.0f) + 1e-6f) : 1.0f; sq[ai][m] = 0.f; sqb[ai][m] = 0.f; }
; #pragma unroll
;         for (int bj = 0; bj < 2; ++bj) {
;             const unsigned col = col0 + bj * HALF;
;             f32x4 gv[2], lg[2], wv[2], w2[2];
; #pragma unroll
;             for (int n = 0; n < 2; ++n) {
;                 gv[n] = *(const f32x4*)(gate + (b * 9216u + col + 4 * n)) * gs;
;                 lg[n] = (f32x4){1.f, 1.f, 1.f, 1.f}; if (LAZY) lg[n] = *(const f32x4*)(lazy_g + col + 4 * n);
;                 wv[n] = (f32x4){0.f, 0.f, 0.f, 0.f}; w2[n] = (f32x4){1.f, 1.f, 1.f, 1.f};
;                 if (aout) { wv[n] = *(const f32x4*)(wg + col + 4 * n) * (*(const f32x4*)(wsc + (b * 9216u + col + 4 * n)) + 1.0f); if (WG2) { w2[n] = *(const f32x4*)(wg2 + col + 4 * n); wv[n] = wv[n] * w2[n]; } }
;             }
;             f32x4 xq[2][2][2];
;     ...
;             constexpr bool DEEP = !LAZY && !WG2;
;             if (DEEP) RES_LD(0, 0);
; #pragma unroll
;             for (int pp = 0; pp < 4; ++pp) {
;                 if (DEEP) { if (pp < 3) RES_LD((pp + 1) & 1, pp + 1); } else RES_LD(pp & 1, pp);
; #pragma unroll
;                 for (int j = 0; j < 2; ++j) { const int i_ = 2 * pp + j, ai = i_ >> 2, m = i_ & 3; const unsigned off = (row0 + ai * HALF + m * 16) * 1024u + col;
;                     const f32x4 xi0 = xq[pp & 1][j][0], xi1 = xq[pp & 1][j][1];
;                     f32x4 xo0 = gv[0] * acc[ai][bj][m][0], xo1 = gv[1] * acc[ai][bj][m][1];
;                     if (LAZY) { xo0 = xo0 + xi0 * lg[0] * rl[ai][m]; xo1 = xo1 + xi1 * lg[1] * rl[ai][m]; } else { xo0 = xo0 + xi0; xo1 = xo1 + xi1; }
;                     *(f32x4*)(xout + off) = xo0; *(f32x4*)(xout + off + 4) = xo1;
;                     if (aout) { const f32x4 a0 = xo0 * wv[0], a1 = xo1 * wv[1]; u32x4 w; w.x = cvt_pk_bf16(a0[0], a0[1]); w.y = cvt_pk_bf16(a0[2], a0[3]); w.z = cvt_pk_bf16(a1[0], a1[1]); w.w = cvt_pk_bf16(a1[2], a1[3]);
;                         *(u32x4*)(aout + off) = w;
.LBB0_319:
	v_lshlrev_b32_e32 v175, 10, v172
	v_add_u32_e32 v176, v184, v175
	v_lshlrev_b64 v[208:209], 2, v[176:177]
	s_waitcnt vmcnt(0)
	v_pk_mul_f32 v[204:205], s[36:37], v[136:137] op_sel_hi:[0,1]
	v_lshl_add_u64 v[136:137], s[34:35], 0, v[208:209]
	v_pk_mul_f32 v[200:201], s[36:37], v[140:141] op_sel_hi:[0,1]
	v_fmamk_f32 v140, v146, 0x3a800000, v222
	global_load_dwordx4 v[148:151], v[136:137], off offset:16
	global_load_dwordx4 v[144:147], v[136:137], off
	v_add_u32_e32 v190, 0x4000, v176
	v_mov_b32_e32 v191, v177
	v_rsq_f32_e32 v174, v140
	v_lshl_add_u64 v[140:141], v[190:191], 2, s[34:35]
	v_pk_mul_f32 v[198:199], s[36:37], v[142:143] op_sel_hi:[0,1]
	v_pk_mul_f32 v[202:203], s[36:37], v[138:139] op_sel_hi:[0,1]
	global_load_dwordx4 v[136:139], v[140:141], off offset:16
	s_nop 0
	global_load_dwordx4 v[140:143], v[140:141], off
	v_lshl_add_u64 v[208:209], s[30:31], 0, v[208:209]
	v_mov_b32_e32 v231, 0
	s_and_b64 vcc, exec, s[8:9]
	v_mov_b32_e32 v232, 0
	s_waitcnt vmcnt(3)
	v_pk_mul_f32 v[150:151], v[134:135], v[150:151]
	s_waitcnt vmcnt(2)
	v_pk_mul_f32 v[146:147], v[130:131], v[146:147]
	v_pk_mul_f32 v[144:145], v[128:129], v[144:145]
	v_pk_mul_f32 v[148:149], v[132:133], v[148:149]
	v_pk_mul_f32 v[146:147], v[174:175], v[146:147] op_sel_hi:[0,1]
	v_pk_mul_f32 v[144:145], v[174:175], v[144:145] op_sel_hi:[0,1]
	v_pk_mul_f32 v[150:151], v[174:175], v[150:151] op_sel_hi:[0,1]
	v_pk_mul_f32 v[148:149], v[174:175], v[148:149] op_sel_hi:[0,1]
	v_pk_fma_f32 v[144:145], v[124:125], v[204:205], v[144:145]
	v_pk_fma_f32 v[146:147], v[126:127], v[202:203], v[146:147]
	v_pk_fma_f32 v[148:149], v[120:121], v[200:201], v[148:149]
	v_pk_fma_f32 v[150:151], v[122:123], v[198:199], v[150:151]
	global_store_dwordx4 v[208:209], v[144:147], off sc1
	global_store_dwordx4 v[208:209], v[148:151], off offset:16 sc1
	s_cbranch_vccnz .LBB0_321
	v_pk_mul_f32 v[208:209], v[188:189], v[146:147]
	v_pk_mul_f32 v[214:215], v[186:187], v[144:145]
	v_pk_mul_f32 v[234:235], v[192:193], v[148:149]
	v_cvt_pk_bf16_f32 v232, v214, v215
	v_cvt_pk_bf16_f32 v233, v208, v209
	v_lshl_add_u64 v[208:209], v[176:177], 1, s[28:29]
	v_pk_mul_f32 v[236:237], v[194:195], v[150:151]
	v_cvt_pk_bf16_f32 v234, v234, v235
	s_nop 0
	v_cvt_pk_bf16_f32 v235, v236, v237
	global_store_dwordx4 v[208:209], v[232:235], off sc1
	v_mov_b32_e32 v209, v148
	v_mov_b32_e32 v148, v145
	v_mov_b32_e32 v208, v144
	v_pk_mul_f32 v[144:145], v[148:149], v[148:149]
	v_mov_b32_e32 v149, v150
	v_mov_b32_e32 v150, v147
	v_mov_b32_e32 v148, v146
	v_pk_mul_f32 v[146:147], v[150:151], v[150:151]
	v_pk_fma_f32 v[144:145], v[208:209], v[208:209], v[144:145]
	v_pk_fma_f32 v[146:147], v[148:149], v[148:149], v[146:147]
	s_nop 0
	v_pk_add_f32 v[144:145], v[144:145], v[146:147]
	s_nop 0
	v_add_f32_e32 v232, v144, v145
.LBB0_321:
	v_fmamk_f32 v144, v196, 0x3a800000, v222
	v_rsq_f32_e32 v196, v144
	s_waitcnt vmcnt(2)
	v_pk_mul_f32 v[142:143], v[130:131], v[142:143]
	v_pk_mul_f32 v[140:141], v[128:129], v[140:141]
	v_pk_mul_f32 v[138:139], v[134:135], v[138:139]
	v_pk_mul_f32 v[136:137], v[132:133], v[136:137]
	v_pk_mul_f32 v[142:143], v[196:197], v[142:143] op_sel_hi:[0,1]
	v_pk_mul_f32 v[140:141], v[196:197], v[140:141] op_sel_hi:[0,1]
	v_pk_mul_f32 v[138:139], v[196:197], v[138:139] op_sel_hi:[0,1]
	v_pk_mul_f32 v[136:137], v[196:197], v[136:137] op_sel_hi:[0,1]
	v_pk_fma_f32 v[142:143], v[110:111], v[202:203], v[142:143]
	v_pk_fma_f32 v[140:141], v[108:109], v[204:205], v[140:141]
	v_pk_fma_f32 v[138:139], v[106:107], v[198:199], v[138:139]
	v_pk_fma_f32 v[136:137], v[104:105], v[200:201], v[136:137]
	v_lshl_add_u64 v[144:145], v[190:191], 2, s[30:31]
	s_and_b64 vcc, exec, s[8:9]
	global_store_dwordx4 v[144:145], v[140:143], off sc1
	global_store_dwordx4 v[144:145], v[136:139], off offset:16 sc1
	s_cbranch_vccnz .LBB0_323
	v_pk_mul_f32 v[146:147], v[188:189], v[142:143]
	v_pk_mul_f32 v[144:145], v[186:187], v[140:141]
	v_pk_mul_f32 v[148:149], v[194:195], v[138:139]
	v_pk_mul_f32 v[150:151], v[192:193], v[136:137]
	v_cvt_pk_bf16_f32 v144, v144, v145
	v_cvt_pk_bf16_f32 v145, v146, v147
	s_nop 0
	v_cvt_pk_bf16_f32 v146, v150, v151
	v_cvt_pk_bf16_f32 v147, v148, v149
	v_lshl_add_u64 v[148:149], v[190:191], 1, s[28:29]
	global_store_dwordx4 v[148:149], v[144:147], off sc1
	s_nop 1
	v_mov_b32_e32 v145, v136
	v_mov_b32_e32 v136, v141
	v_mov_b32_e32 v141, v138
	v_mov_b32_e32 v138, v143
	v_mov_b32_e32 v144, v140
	v_pk_mul_f32 v[136:137], v[136:137], v[136:137]
	v_mov_b32_e32 v140, v142
	v_pk_mul_f32 v[138:139], v[138:139], v[138:139]
	v_pk_fma_f32 v[136:137], v[144:145], v[144:145], v[136:137]
	v_pk_fma_f32 v[138:139], v[140:141], v[140:141], v[138:139]
	s_nop 0
	v_pk_add_f32 v[136:137], v[136:137], v[138:139]
	s_nop 0
	v_add_f32_e32 v231, v136, v137
;     static __device__ __forceinline__ void run(const f32x4 (&acc)[2][2][4][2], const Unit& u, int wr, int wc, int fr, int fq, const float* xin, float* xout, const float* gate, float gs, const float* lazy_ssq, const float* lazy_g, ...
;     ...
;             for (int m = 0; m < 4; ++m) { rl[ai][m] = LAZY ? __builtin_amdgcn_rsqf(lazy_ssq[row0 + ai * HALF + m * 16] * (1.0f / 1024.0f) + 1e-6f) : 1.0f; sq[ai][m] = 0.f; sqb[ai][m] = 0.f; }
; #pragma unroll
;         for (int bj = 0; bj < 2; ++bj) {
;             const unsigned col = col0 + bj * HALF;
;             f32x4 gv[2], lg[2], wv[2], w2[2];
; #pragma unroll
;             for (int n = 0; n < 2; ++n) {
;                 gv[n] = *(const f32x4*)(gate + (b * 9216u + col + 4 * n)) * gs;
;                 lg[n] = (f32x4){1.f, 1.f, 1.f, 1.f}; if (LAZY) lg[n] = *(const f32x4*)(lazy_g + col + 4 * n);
;                 wv[n] = (f32x4){0.f, 0.f, 0.f, 0.f}; w2[n] = (f32x4){1.f, 1.f, 1.f, 1.f};
;                 if (aout) { wv[n] = *(const f32x4*)(wg + col + 4 * n) * (*(const f32x4*)(wsc + (b * 9216u + col + 4 * n)) + 1.0f); if (WG2) { w2[n] = *(const f32x4*)(wg2 + col + 4 * n); wv[n] = wv[n] * w2[n]; } }
;             }
;             f32x4 xq[2][2][2];
;     ...
;             constexpr bool DEEP = !LAZY && !WG2;
;             if (DEEP) RES_LD(0, 0);
; #pragma unroll
;             for (int pp = 0; pp < 4; ++pp) {
;                 if (DEEP) { if (pp < 3) RES_LD((pp + 1) & 1, pp + 1); } else RES_LD(pp & 1, pp);
; #pragma unroll
;                 for (int j = 0; j < 2; ++j) { const int i_ = 2 * pp + j, ai = i_ >> 2, m = i_ & 3; const unsigned off = (row0 + ai * HALF + m * 16) * 1024u + col;
;                     const f32x4 xi0 = xq[pp & 1][j][0], xi1 = xq[pp & 1][j][1];
;                     f32x4 xo0 = gv[0] * acc[ai][bj][m][0], xo1 = gv[1] * acc[ai][bj][m][1];
;                     if (LAZY) { xo0 = xo0 + xi0 * lg[0] * rl[ai][m]; xo1 = xo1 + xi1 * lg[1] * rl[ai][m]; } else { xo0 = xo0 + xi0; xo1 = xo1 + xi1; }
;                     *(f32x4*)(xout + off) = xo0; *(f32x4*)(xout + off + 4) = xo1;
;                     if (aout) { const f32x4 a0 = xo0 * wv[0], a1 = xo1 * wv[1]; u32x4 w; w.x = cvt_pk_bf16(a0[0], a0[1]); w.y = cvt_pk_bf16(a0[2], a0[3]); w.z = cvt_pk_bf16(a1[0], a1[1]); w.w = cvt_pk_bf16(a1[2], a1[3]);
;                         *(u32x4*)(aout + off) = w;
.LBB0_323:
	v_add_u32_e32 v208, 0x8000, v176
	v_mov_b32_e32 v209, v177
	v_fmamk_f32 v136, v206, 0x3a800000, v222
	v_lshlrev_b64 v[214:215], 2, v[208:209]
	v_rsq_f32_e32 v190, v136
	v_lshl_add_u64 v[136:137], s[34:35], 0, v[214:215]
	global_load_dwordx4 v[148:151], v[136:137], off offset:16
	global_load_dwordx4 v[144:147], v[136:137], off
	v_add_u32_e32 v206, 0xc000, v176
	v_mov_b32_e32 v207, v177
	v_lshl_add_u64 v[140:141], v[206:207], 2, s[34:35]
	global_load_dwordx4 v[136:139], v[140:141], off offset:16
	s_nop 0
	global_load_dwordx4 v[140:143], v[140:141], off
	v_lshl_add_u64 v[214:215], s[30:31], 0, v[214:215]
	v_mov_b32_e32 v233, 0
	s_and_b64 vcc, exec, s[8:9]
	v_mov_b32_e32 v234, 0
	s_waitcnt vmcnt(3)
	v_pk_mul_f32 v[150:151], v[134:135], v[150:151]
	s_waitcnt vmcnt(2)
	v_pk_mul_f32 v[146:147], v[130:131], v[146:147]
	v_pk_mul_f32 v[144:145], v[128:129], v[144:145]
	v_pk_mul_f32 v[148:149], v[132:133], v[148:149]
	v_pk_mul_f32 v[146:147], v[190:191], v[146:147] op_sel_hi:[0,1]
	v_pk_mul_f32 v[144:145], v[190:191], v[144:145] op_sel_hi:[0,1]
	v_pk_mul_f32 v[150:151], v[190:191], v[150:151] op_sel_hi:[0,1]
	v_pk_mul_f32 v[148:149], v[190:191], v[148:149] op_sel_hi:[0,1]
	v_pk_fma_f32 v[146:147], v[94:95], v[202:203], v[146:147]
	v_pk_fma_f32 v[144:145], v[92:93], v[204:205], v[144:145]
	v_pk_fma_f32 v[150:151], v[90:91], v[198:199], v[150:151]
	v_pk_fma_f32 v[148:149], v[88:89], v[200:201], v[148:149]
	global_store_dwordx4 v[214:215], v[144:147], off sc1
	global_store_dwordx4 v[214:215], v[148:151], off offset:16 sc1
	s_cbranch_vccnz .LBB0_325
	v_pk_mul_f32 v[234:235], v[186:187], v[144:145]
	v_pk_mul_f32 v[236:237], v[192:193], v[148:149]
	v_lshl_add_u64 v[208:209], v[208:209], 1, s[28:29]
	v_pk_mul_f32 v[214:215], v[188:189], v[146:147]
	v_pk_mul_f32 v[238:239], v[194:195], v[150:151]
	v_cvt_pk_bf16_f32 v234, v234, v235
	v_cvt_pk_bf16_f32 v235, v214, v215
	v_cvt_pk_bf16_f32 v236, v236, v237
	s_nop 0
	v_cvt_pk_bf16_f32 v237, v238, v239
	global_store_dwordx4 v[208:209], v[234:237], off sc1
	v_mov_b32_e32 v209, v148
	v_mov_b32_e32 v148, v145
	v_mov_b32_e32 v208, v144
	v_pk_mul_f32 v[144:145], v[148:149], v[148:149]
	v_mov_b32_e32 v149, v150
	v_mov_b32_e32 v150, v147
	v_mov_b32_e32 v148, v146
	v_pk_mul_f32 v[146:147], v[150:151], v[150:151]
	v_pk_fma_f32 v[144:145], v[208:209], v[208:209], v[144:145]
	v_pk_fma_f32 v[146:147], v[148:149], v[148:149], v[146:147]
	s_nop 0
	v_pk_add_f32 v[144:145], v[144:145], v[146:147]
	s_nop 0
	v_add_f32_e32 v234, v144, v145
.LBB0_325:
	v_fmamk_f32 v144, v210, 0x3a800000, v222
	v_rsq_f32_e32 v210, v144
	s_waitcnt vmcnt(2)
	v_pk_mul_f32 v[142:143], v[130:131], v[142:143]
	v_pk_mul_f32 v[140:141], v[128:129], v[140:141]
	v_pk_mul_f32 v[138:139], v[134:135], v[138:139]
	v_pk_mul_f32 v[136:137], v[132:133], v[136:137]
	v_pk_mul_f32 v[142:143], v[210:211], v[142:143] op_sel_hi:[0,1]
	v_pk_mul_f32 v[140:141], v[210:211], v[140:141] op_sel_hi:[0,1]
	v_pk_mul_f32 v[138:139], v[210:211], v[138:139] op_sel_hi:[0,1]
	v_pk_mul_f32 v[136:137], v[210:211], v[136:137] op_sel_hi:[0,1]
	v_pk_fma_f32 v[142:143], v[78:79], v[202:203], v[142:143]
	v_pk_fma_f32 v[140:141], v[76:77], v[204:205], v[140:141]
	v_pk_fma_f32 v[138:139], v[74:75], v[198:199], v[138:139]
	v_pk_fma_f32 v[136:137], v[72:73], v[200:201], v[136:137]
	v_lshl_add_u64 v[144:145], v[206:207], 2, s[30:31]
	s_and_b64 vcc, exec, s[8:9]
	global_store_dwordx4 v[144:145], v[140:143], off sc1
	global_store_dwordx4 v[144:145], v[136:139], off offset:16 sc1
	s_cbranch_vccnz .LBB0_327
	v_pk_mul_f32 v[146:147], v[188:189], v[142:143]
	v_pk_mul_f32 v[144:145], v[186:187], v[140:141]
	v_pk_mul_f32 v[148:149], v[194:195], v[138:139]
	v_pk_mul_f32 v[150:151], v[192:193], v[136:137]
	v_cvt_pk_bf16_f32 v144, v144, v145
	v_cvt_pk_bf16_f32 v145, v146, v147
	s_nop 0
	v_cvt_pk_bf16_f32 v146, v150, v151
	v_cvt_pk_bf16_f32 v147, v148, v149
	v_lshl_add_u64 v[148:149], v[206:207], 1, s[28:29]
	global_store_dwordx4 v[148:149], v[144:147], off sc1
	s_nop 1
	v_mov_b32_e32 v145, v136
	v_mov_b32_e32 v136, v141
	v_mov_b32_e32 v141, v138
	v_mov_b32_e32 v138, v143
	v_mov_b32_e32 v144, v140
	v_pk_mul_f32 v[136:137], v[136:137], v[136:137]
	v_mov_b32_e32 v140, v142
	v_pk_mul_f32 v[138:139], v[138:139], v[138:139]
	v_pk_fma_f32 v[136:137], v[144:145], v[144:145], v[136:137]
	v_pk_fma_f32 v[138:139], v[140:141], v[140:141], v[138:139]
	s_nop 0
	v_pk_add_f32 v[136:137], v[136:137], v[138:139]
	s_nop 0
	v_add_f32_e32 v233, v136, v137
;     static __device__ __forceinline__ void run(const f32x4 (&acc)[2][2][4][2], const Unit& u, int wr, int wc, int fr, int fq, const float* xin, float* xout, const float* gate, float gs, const float* lazy_ssq, const float* lazy_g, ...
;     ...
;             for (int m = 0; m < 4; ++m) { rl[ai][m] = LAZY ? __builtin_amdgcn_rsqf(lazy_ssq[row0 + ai * HALF + m * 16] * (1.0f / 1024.0f) + 1e-6f) : 1.0f; sq[ai][m] = 0.f; sqb[ai][m] = 0.f; }
; #pragma unroll
;         for (int bj = 0; bj < 2; ++bj) {
;             const unsigned col = col0 + bj * HALF;
;             f32x4 gv[2], lg[2], wv[2], w2[2];
; #pragma unroll
;             for (int n = 0; n < 2; ++n) {
;                 gv[n] = *(const f32x4*)(gate + (b * 9216u + col + 4 * n)) * gs;
;                 lg[n] = (f32x4){1.f, 1.f, 1.f, 1.f}; if (LAZY) lg[n] = *(const f32x4*)(lazy_g + col + 4 * n);
;                 wv[n] = (f32x4){0.f, 0.f, 0.f, 0.f}; w2[n] = (f32x4){1.f, 1.f, 1.f, 1.f};
;                 if (aout) { wv[n] = *(const f32x4*)(wg + col + 4 * n) * (*(const f32x4*)(wsc + (b * 9216u + col + 4 * n)) + 1.0f); if (WG2) { w2[n] = *(const f32x4*)(wg2 + col + 4 * n); wv[n] = wv[n] * w2[n]; } }
;             }
;             f32x4 xq[2][2][2];
;     ...
;             constexpr bool DEEP = !LAZY && !WG2;
;             if (DEEP) RES_LD(0, 0);
; #pragma unroll
;             for (int pp = 0; pp < 4; ++pp) {
;                 if (DEEP) { if (pp < 3) RES_LD((pp + 1) & 1, pp + 1); } else RES_LD(pp & 1, pp);
; #pragma unroll
;                 for (int j = 0; j < 2; ++j) { const int i_ = 2 * pp + j, ai = i_ >> 2, m = i_ & 3; const unsigned off = (row0 + ai * HALF + m * 16) * 1024u + col;
;                     const f32x4 xi0 = xq[pp & 1][j][0], xi1 = xq[pp & 1][j][1];
;                     f32x4 xo0 = gv[0] * acc[ai][bj][m][0], xo1 = gv[1] * acc[ai][bj][m][1];
;                     if (LAZY) { xo0 = xo0 + xi0 * lg[0] * rl[ai][m]; xo1 = xo1 + xi1 * lg[1] * rl[ai][m]; } else { xo0 = xo0 + xi0; xo1 = xo1 + xi1; }
;                     *(f32x4*)(xout + off) = xo0; *(f32x4*)(xout + off + 4) = xo1;
;                     if (aout) { const f32x4 a0 = xo0 * wv[0], a1 = xo1 * wv[1]; u32x4 w; w.x = cvt_pk_bf16(a0[0], a0[1]); w.y = cvt_pk_bf16(a0[2], a0[3]); w.z = cvt_pk_bf16(a1[0], a1[1]); w.w = cvt_pk_bf16(a1[2], a1[3]);
;                         *(u32x4*)(aout + off) = w;
.LBB0_327:
	s_nop 0
	v_fmamk_f32 v136, v213, 0x3a800000, v222
	v_lshlrev_b32_e32 v213, 10, v158
	v_add_u32_e32 v214, v213, v184
	v_mov_b32_e32 v215, v177
	v_rsq_f32_e32 v206, v136
	v_lshl_add_u64 v[136:137], v[214:215], 2, s[34:35]
	global_load_dwordx4 v[148:151], v[136:137], off offset:16
	global_load_dwordx4 v[144:147], v[136:137], off
	v_add_u32_e32 v136, 0x4000, v214
	v_mov_b32_e32 v137, v177
	v_lshl_add_u64 v[140:141], v[136:137], 2, s[34:35]
	global_load_dwordx4 v[136:139], v[140:141], off offset:16
	s_nop 0
	global_load_dwordx4 v[140:143], v[140:141], off
	v_add_u32_e32 v208, 0x20000, v176
	v_mov_b32_e32 v209, v177
	v_lshl_add_u64 v[236:237], v[208:209], 2, s[30:31]
	v_mov_b32_e32 v235, 0
	s_and_b64 vcc, exec, s[8:9]
	s_waitcnt vmcnt(3)
	v_pk_mul_f32 v[150:151], v[134:135], v[150:151]
	s_waitcnt vmcnt(2)
	v_pk_mul_f32 v[146:147], v[130:131], v[146:147]
	v_pk_mul_f32 v[144:145], v[128:129], v[144:145]
	v_pk_mul_f32 v[146:147], v[206:207], v[146:147] op_sel_hi:[0,1]
	v_pk_mul_f32 v[144:145], v[206:207], v[144:145] op_sel_hi:[0,1]
	v_pk_mul_f32 v[148:149], v[132:133], v[148:149]
	v_pk_fma_f32 v[146:147], v[62:63], v[202:203], v[146:147]
	v_pk_fma_f32 v[144:145], v[60:61], v[204:205], v[144:145]
	v_pk_mul_f32 v[150:151], v[206:207], v[150:151] op_sel_hi:[0,1]
	v_pk_mul_f32 v[148:149], v[206:207], v[148:149] op_sel_hi:[0,1]
	v_pk_fma_f32 v[150:151], v[58:59], v[198:199], v[150:151]
	v_pk_fma_f32 v[148:149], v[56:57], v[200:201], v[148:149]
	global_store_dwordx4 v[236:237], v[144:147], off sc1
	global_store_dwordx4 v[236:237], v[148:151], off offset:16 sc1
	v_mov_b32_e32 v236, 0
	s_cbranch_vccnz .LBB0_329
	v_pk_mul_f32 v[238:239], v[188:189], v[146:147]
	v_pk_mul_f32 v[236:237], v[186:187], v[144:145]
	v_lshl_add_u64 v[208:209], v[208:209], 1, s[28:29]
	v_pk_mul_f32 v[240:241], v[194:195], v[150:151]
	v_pk_mul_f32 v[242:243], v[192:193], v[148:149]
	v_cvt_pk_bf16_f32 v236, v236, v237
	v_cvt_pk_bf16_f32 v237, v238, v239
	s_nop 0
	v_cvt_pk_bf16_f32 v238, v242, v243
	v_cvt_pk_bf16_f32 v239, v240, v241
	global_store_dwordx4 v[208:209], v[236:239], off sc1
	v_mov_b32_e32 v209, v148
	v_mov_b32_e32 v148, v145
	v_mov_b32_e32 v208, v144
	v_pk_mul_f32 v[144:145], v[148:149], v[148:149]
	v_mov_b32_e32 v149, v150
	v_mov_b32_e32 v150, v147
	v_mov_b32_e32 v148, v146
	v_pk_mul_f32 v[146:147], v[150:151], v[150:151]
	v_pk_fma_f32 v[144:145], v[208:209], v[208:209], v[144:145]
	v_pk_fma_f32 v[146:147], v[148:149], v[148:149], v[146:147]
	s_nop 0
	v_pk_add_f32 v[144:145], v[144:145], v[146:147]
	s_nop 0
	v_add_f32_e32 v236, v144, v145
.LBB0_329:
	v_fmamk_f32 v144, v212, 0x3a800000, v222
	v_rsq_f32_e32 v212, v144
	s_waitcnt vmcnt(2)
	v_pk_mul_f32 v[142:143], v[130:131], v[142:143]
	v_pk_mul_f32 v[140:141], v[128:129], v[140:141]
	v_pk_mul_f32 v[138:139], v[134:135], v[138:139]
	v_pk_mul_f32 v[136:137], v[132:133], v[136:137]
	v_add_u32_e32 v144, 0x24000, v176
	v_pk_mul_f32 v[142:143], v[212:213], v[142:143] op_sel_hi:[0,1]
	v_pk_mul_f32 v[140:141], v[212:213], v[140:141] op_sel_hi:[0,1]
	v_pk_mul_f32 v[138:139], v[212:213], v[138:139] op_sel_hi:[0,1]
	v_pk_mul_f32 v[136:137], v[212:213], v[136:137] op_sel_hi:[0,1]
	v_mov_b32_e32 v145, v177
	v_pk_fma_f32 v[142:143], v[46:47], v[202:203], v[142:143]
	v_pk_fma_f32 v[140:141], v[44:45], v[204:205], v[140:141]
	v_pk_fma_f32 v[138:139], v[42:43], v[198:199], v[138:139]
	v_pk_fma_f32 v[136:137], v[40:41], v[200:201], v[136:137]
	v_lshl_add_u64 v[146:147], v[144:145], 2, s[30:31]
	s_and_b64 vcc, exec, s[8:9]
	global_store_dwordx4 v[146:147], v[140:143], off sc1
	global_store_dwordx4 v[146:147], v[136:139], off offset:16 sc1
	s_cbranch_vccnz .LBB0_331
	v_pk_mul_f32 v[148:149], v[188:189], v[142:143]
	v_pk_mul_f32 v[146:147], v[186:187], v[140:141]
	v_lshl_add_u64 v[144:145], v[144:145], 1, s[28:29]
	v_pk_mul_f32 v[150:151], v[194:195], v[138:139]
	v_pk_mul_f32 v[208:209], v[192:193], v[136:137]
	v_cvt_pk_bf16_f32 v146, v146, v147
	v_cvt_pk_bf16_f32 v147, v148, v149
	s_nop 0
	v_cvt_pk_bf16_f32 v148, v208, v209
	v_cvt_pk_bf16_f32 v149, v150, v151
	global_store_dwordx4 v[144:145], v[146:149], off sc1
	v_mov_b32_e32 v145, v136
	v_mov_b32_e32 v136, v141
	v_mov_b32_e32 v141, v138
	v_mov_b32_e32 v138, v143
	v_mov_b32_e32 v144, v140
	v_pk_mul_f32 v[136:137], v[136:137], v[136:137]
	v_mov_b32_e32 v140, v142
	v_pk_mul_f32 v[138:139], v[138:139], v[138:139]
	v_pk_fma_f32 v[136:137], v[144:145], v[144:145], v[136:137]
	v_pk_fma_f32 v[138:139], v[140:141], v[140:141], v[138:139]
	s_nop 0
	v_pk_add_f32 v[136:137], v[136:137], v[138:139]
	s_nop 0
	v_add_f32_e32 v235, v136, v137
;     static __device__ __forceinline__ void run(const f32x4 (&acc)[2][2][4][2], const Unit& u, int wr, int wc, int fr, int fq, const float* xin, float* xout, const float* gate, float gs, const float* lazy_ssq, const float* lazy_g, ...
;     ...
;             for (int m = 0; m < 4; ++m) { rl[ai][m] = LAZY ? __builtin_amdgcn_rsqf(lazy_ssq[row0 + ai * HALF + m * 16] * (1.0f / 1024.0f) + 1e-6f) : 1.0f; sq[ai][m] = 0.f; sqb[ai][m] = 0.f; }
; #pragma unroll
;         for (int bj = 0; bj < 2; ++bj) {
;             const unsigned col = col0 + bj * HALF;
;             f32x4 gv[2], lg[2], wv[2], w2[2];
; #pragma unroll
;             for (int n = 0; n < 2; ++n) {
;                 gv[n] = *(const f32x4*)(gate + (b * 9216u + col + 4 * n)) * gs;
;                 lg[n] = (f32x4){1.f, 1.f, 1.f, 1.f}; if (LAZY) lg[n] = *(const f32x4*)(lazy_g + col + 4 * n);
;                 wv[n] = (f32x4){0.f, 0.f, 0.f, 0.f}; w2[n] = (f32x4){1.f, 1.f, 1.f, 1.f};
;                 if (aout) { wv[n] = *(const f32x4*)(wg + col + 4 * n) * (*(const f32x4*)(wsc + (b * 9216u + col + 4 * n)) + 1.0f); if (WG2) { w2[n] = *(const f32x4*)(wg2 + col + 4 * n); wv[n] = wv[n] * w2[n]; } }
;             }
;             f32x4 xq[2][2][2];
;     ...
;             constexpr bool DEEP = !LAZY && !WG2;
;             if (DEEP) RES_LD(0, 0);
; #pragma unroll
;             for (int pp = 0; pp < 4; ++pp) {
;                 if (DEEP) { if (pp < 3) RES_LD((pp + 1) & 1, pp + 1); } else RES_LD(pp & 1, pp);
; #pragma unroll
;                 for (int j = 0; j < 2; ++j) { const int i_ = 2 * pp + j, ai = i_ >> 2, m = i_ & 3; const unsigned off = (row0 + ai * HALF + m * 16) * 1024u + col;
;                     const f32x4 xi0 = xq[pp & 1][j][0], xi1 = xq[pp & 1][j][1];
;                     f32x4 xo0 = gv[0] * acc[ai][bj][m][0], xo1 = gv[1] * acc[ai][bj][m][1];
;                     if (LAZY) { xo0 = xo0 + xi0 * lg[0] * rl[ai][m]; xo1 = xo1 + xi1 * lg[1] * rl[ai][m]; } else { xo0 = xo0 + xi0; xo1 = xo1 + xi1; }
;                     *(f32x4*)(xout + off) = xo0; *(f32x4*)(xout + off + 4) = xo1;
;                     if (aout) { const f32x4 a0 = xo0 * wv[0], a1 = xo1 * wv[1]; u32x4 w; w.x = cvt_pk_bf16(a0[0], a0[1]); w.y = cvt_pk_bf16(a0[2], a0[3]); w.z = cvt_pk_bf16(a1[0], a1[1]); w.w = cvt_pk_bf16(a1[2], a1[3]);
;                         *(u32x4*)(aout + off) = w;
.LBB0_331:
	s_nop 0
	v_fmamk_f32 v136, v211, 0x3a800000, v222
	v_rsq_f32_e32 v208, v136
	v_add_u32_e32 v136, 0x8000, v214
	v_mov_b32_e32 v137, v177
	v_lshl_add_u64 v[136:137], v[136:137], 2, s[34:35]
	global_load_dwordx4 v[148:151], v[136:137], off offset:16
	global_load_dwordx4 v[144:147], v[136:137], off
	v_add_u32_e32 v136, 0xc000, v214
	v_mov_b32_e32 v137, v177
	v_lshl_add_u64 v[140:141], v[136:137], 2, s[34:35]
	global_load_dwordx4 v[136:139], v[140:141], off offset:16
	s_nop 0
	global_load_dwordx4 v[140:143], v[140:141], off
	v_add_u32_e32 v214, 0x28000, v176
	v_mov_b32_e32 v215, v177
	v_lshl_add_u64 v[238:239], v[214:215], 2, s[30:31]
	v_mov_b32_e32 v237, 0
	s_and_b64 vcc, exec, s[8:9]
	s_waitcnt vmcnt(3)
	v_pk_mul_f32 v[150:151], v[134:135], v[150:151]
	s_waitcnt vmcnt(2)
	v_pk_mul_f32 v[146:147], v[130:131], v[146:147]
	v_pk_mul_f32 v[144:145], v[128:129], v[144:145]
	v_pk_mul_f32 v[146:147], v[208:209], v[146:147] op_sel_hi:[0,1]
	v_pk_mul_f32 v[144:145], v[208:209], v[144:145] op_sel_hi:[0,1]
	v_pk_mul_f32 v[148:149], v[132:133], v[148:149]
	v_pk_fma_f32 v[146:147], v[30:31], v[202:203], v[146:147]
	v_pk_fma_f32 v[144:145], v[28:29], v[204:205], v[144:145]
	v_pk_mul_f32 v[150:151], v[208:209], v[150:151] op_sel_hi:[0,1]
	v_pk_mul_f32 v[148:149], v[208:209], v[148:149] op_sel_hi:[0,1]
	v_pk_fma_f32 v[150:151], v[26:27], v[198:199], v[150:151]
	v_pk_fma_f32 v[148:149], v[24:25], v[200:201], v[148:149]
	global_store_dwordx4 v[238:239], v[144:147], off sc1
	global_store_dwordx4 v[238:239], v[148:151], off offset:16 sc1
	v_mov_b32_e32 v238, 0
	s_cbranch_vccnz .LBB0_333
	v_pk_mul_f32 v[240:241], v[188:189], v[146:147]
	v_pk_mul_f32 v[238:239], v[186:187], v[144:145]
	v_lshl_add_u64 v[214:215], v[214:215], 1, s[28:29]
	v_pk_mul_f32 v[242:243], v[194:195], v[150:151]
	v_pk_mul_f32 v[244:245], v[192:193], v[148:149]
	v_cvt_pk_bf16_f32 v238, v238, v239
	v_cvt_pk_bf16_f32 v239, v240, v241
	s_nop 0
	v_cvt_pk_bf16_f32 v240, v244, v245
	v_cvt_pk_bf16_f32 v241, v242, v243
	global_store_dwordx4 v[214:215], v[238:241], off sc1
	v_mov_b32_e32 v215, v148
	v_mov_b32_e32 v148, v145
	v_mov_b32_e32 v214, v144
	v_pk_mul_f32 v[144:145], v[148:149], v[148:149]
	v_mov_b32_e32 v149, v150
	v_mov_b32_e32 v150, v147
	v_mov_b32_e32 v148, v146
	v_pk_mul_f32 v[146:147], v[150:151], v[150:151]
	v_pk_fma_f32 v[144:145], v[214:215], v[214:215], v[144:145]
	v_pk_fma_f32 v[146:147], v[148:149], v[148:149], v[146:147]
	s_nop 0
	v_pk_add_f32 v[144:145], v[144:145], v[146:147]
	s_nop 0
	v_add_f32_e32 v238, v144, v145
.LBB0_333:
	v_fmamk_f32 v144, v197, 0x3a800000, v222
	v_rsq_f32_e32 v214, v144
	s_waitcnt vmcnt(2)
	v_pk_mul_f32 v[130:131], v[130:131], v[142:143]
	v_pk_mul_f32 v[128:129], v[128:129], v[140:141]
	v_pk_mul_f32 v[134:135], v[134:135], v[138:139]
	v_pk_mul_f32 v[132:133], v[132:133], v[136:137]
	v_add_u32_e32 v176, 0x2c000, v176
	v_pk_mul_f32 v[130:131], v[214:215], v[130:131] op_sel_hi:[0,1]
	v_pk_mul_f32 v[128:129], v[214:215], v[128:129] op_sel_hi:[0,1]
	v_pk_mul_f32 v[134:135], v[214:215], v[134:135] op_sel_hi:[0,1]
	v_pk_mul_f32 v[132:133], v[214:215], v[132:133] op_sel_hi:[0,1]
	v_pk_fma_f32 v[130:131], v[14:15], v[202:203], v[130:131]
	v_pk_fma_f32 v[128:129], v[12:13], v[204:205], v[128:129]
	v_pk_fma_f32 v[134:135], v[10:11], v[198:199], v[134:135]
	v_pk_fma_f32 v[132:133], v[8:9], v[200:201], v[132:133]
	v_lshl_add_u64 v[136:137], v[176:177], 2, s[30:31]
	s_and_b64 vcc, exec, s[8:9]
	global_store_dwordx4 v[136:137], v[128:131], off sc1
	global_store_dwordx4 v[136:137], v[132:135], off offset:16 sc1
	s_cbranch_vccnz .LBB0_335
	v_pk_mul_f32 v[138:139], v[188:189], v[130:131]
	v_pk_mul_f32 v[136:137], v[186:187], v[128:129]
	v_pk_mul_f32 v[140:141], v[194:195], v[134:135]
	v_pk_mul_f32 v[142:143], v[192:193], v[132:133]
	v_cvt_pk_bf16_f32 v136, v136, v137
	v_cvt_pk_bf16_f32 v137, v138, v139
	s_nop 0
	v_cvt_pk_bf16_f32 v138, v142, v143
	v_cvt_pk_bf16_f32 v139, v140, v141
	v_lshl_add_u64 v[140:141], v[176:177], 1, s[28:29]
	global_store_dwordx4 v[140:141], v[136:139], off sc1
	s_nop 1
	v_mov_b32_e32 v137, v132
	v_mov_b32_e32 v132, v129
	v_mov_b32_e32 v136, v128
	v_pk_mul_f32 v[128:129], v[132:133], v[132:133]
	v_mov_b32_e32 v133, v134
	v_mov_b32_e32 v134, v131
	v_mov_b32_e32 v132, v130
	v_pk_mul_f32 v[130:131], v[134:135], v[134:135]
	v_pk_fma_f32 v[128:129], v[136:137], v[136:137], v[128:129]
	v_pk_fma_f32 v[130:131], v[132:133], v[132:133], v[130:131]
	s_nop 0
	v_pk_add_f32 v[128:129], v[128:129], v[130:131]
	s_nop 0
	v_add_f32_e32 v237, v128, v129

;     static __device__ __forceinline__ void run(const f32x4 (&acc)[2][2][4][2], const Unit& u, int wr, int wc, int fr, int fq, const float* xin, float* xout, const float* gate, float gs, const float* lazy_ssq, const float* lazy_g, ...
;     ...
;                 gv[n] = *(const f32x4*)(gate + (b * 9216u + col + 4 * n)) * gs;
;                 lg[n] = (f32x4){1.f, 1.f, 1.f, 1.f}; if (LAZY) lg[n] = *(const f32x4*)(lazy_g + col + 4 * n);
;                 wv[n] = (f32x4){0.f, 0.f, 0.f, 0.f}; w2[n] = (f32x4){1.f, 1.f, 1.f, 1.f};
;                 if (aout) { wv[n] = *(const f32x4*)(wg + col + 4 * n) * (*(const f32x4*)(wsc + (b * 9216u + col + 4 * n)) + 1.0f); if (WG2) { w2[n] = *(const f32x4*)(wg2 + col + 4 * n); wv[n] = wv[n] * w2[n]; } }
;             }
;             f32x4 xq[2][2][2];
;     ...
;             constexpr bool DEEP = !LAZY && !WG2;
;             if (DEEP) RES_LD(0, 0);
; #pragma unroll
;             for (int pp = 0; pp < 4; ++pp) {
;                 if (DEEP) { if (pp < 3) RES_LD((pp + 1) & 1, pp + 1); } else RES_LD(pp & 1, pp);
; #pragma unroll
;                 for (int j = 0; j < 2; ++j) { const int i_ = 2 * pp + j, ai = i_ >> 2, m = i_ & 3; const unsigned off = (row0 + ai * HALF + m * 16) * 1024u + col;
;                     const f32x4 xi0 = xq[pp & 1][j][0], xi1 = xq[pp & 1][j][1];
;                     f32x4 xo0 = gv[0] * acc[ai][bj][m][0], xo1 = gv[1] * acc[ai][bj][m][1];
;                     if (LAZY) { xo0 = xo0 + xi0 * lg[0] * rl[ai][m]; xo1 = xo1 + xi1 * lg[1] * rl[ai][m]; } else { xo0 = xo0 + xi0; xo1 = xo1 + xi1; }
;                     *(f32x4*)(xout + off) = xo0; *(f32x4*)(xout + off + 4) = xo1;
;                     if (aout) { const f32x4 a0 = xo0 * wv[0], a1 = xo1 * wv[1]; u32x4 w; w.x = cvt_pk_bf16(a0[0], a0[1]); w.y = cvt_pk_bf16(a0[2], a0[3]); w.z = cvt_pk_bf16(a1[0], a1[1]); w.w = cvt_pk_bf16(a1[2], a1[3]);
;                         *(u32x4*)(aout + off) = w;
;                         sq[ai][m] += ((xo0[0] * xo0[0] + xo0[1] * xo0[1]) + (xo0[2] * xo0[2] + xo0[3] * xo0[3])) + ((xo1[0] * xo1[0] + xo1[1] * xo1[1]) + (xo1[2] * xo1[2] + xo1[3] * xo1[3]));
;                         if (WG2) { const f32x4 b0 = xo0 * w2[0], b1 = xo1 * w2[1]; sqb[ai][m] += ((b0[0] * b0[0] + b0[1] * b0[1]) + (b0[2] * b0[2] + b0[3] * b0[3])) + ((b1[0] * b1[0] + b1[1] * b1[1]) + (b1[2] * b1[2] + b1[3] * b1[3])); } } }
.LBB0_339:
	v_add_u32_e32 v176, v202, v175
	v_lshlrev_b64 v[204:205], 2, v[176:177]
	v_lshl_add_u64 v[136:137], s[34:35], 0, v[204:205]
	global_load_dwordx4 v[240:243], v[136:137], off
	global_load_dwordx4 v[244:247], v[136:137], off offset:16
	v_mov_b32_e32 v201, v177
	v_add_u32_e32 v200, 0x4000, v176
	v_lshl_add_u64 v[144:145], v[200:201], 2, s[34:35]
	global_load_dwordx4 v[136:139], v[144:145], off offset:16
	s_nop 0
	global_load_dwordx4 v[144:147], v[144:145], off
	s_mov_b32 s37, s36
	s_mov_b32 s38, s36
	s_mov_b32 s39, s36
	v_mov_b32_e32 v175, v174
	v_mov_b32_e32 v248, v174
	v_mov_b32_e32 v249, v174
	s_waitcnt vmcnt(5)
	v_pk_mul_f32 v[182:183], s[38:39], v[150:151]
	v_pk_mul_f32 v[192:193], s[36:37], v[148:149]
	v_pk_mul_f32 v[194:195], s[38:39], v[142:143]
	v_pk_mul_f32 v[198:199], s[36:37], v[140:141]
	s_and_b64 vcc, exec, s[8:9]
	v_lshl_add_u64 v[204:205], s[30:31], 0, v[204:205]
	s_waitcnt vmcnt(3)
	v_pk_mul_f32 v[140:141], v[130:131], v[242:243]
	v_pk_mul_f32 v[142:143], v[128:129], v[240:241]
	s_waitcnt vmcnt(2)
	v_pk_mul_f32 v[148:149], v[134:135], v[246:247]
	v_pk_mul_f32 v[150:151], v[132:133], v[244:245]
	v_pk_mul_f32 v[140:141], v[248:249], v[140:141]
	v_pk_mul_f32 v[142:143], v[174:175], v[142:143]
	v_pk_mul_f32 v[240:241], v[248:249], v[148:149]
	v_pk_mul_f32 v[174:175], v[174:175], v[150:151]
	v_pk_fma_f32 v[150:151], v[118:119], v[194:195], v[140:141]
	v_pk_fma_f32 v[148:149], v[116:117], v[198:199], v[142:143]
	v_pk_fma_f32 v[142:143], v[114:115], v[182:183], v[240:241]
	v_pk_fma_f32 v[140:141], v[112:113], v[192:193], v[174:175]
	global_store_dwordx4 v[204:205], v[148:151], off sc1
	global_store_dwordx4 v[204:205], v[140:143], off offset:16 sc1
	s_cbranch_vccnz .LBB0_341
	v_pk_mul_f32 v[174:175], v[188:189], v[150:151]
	v_pk_mul_f32 v[204:205], v[186:187], v[148:149]
	v_pk_mul_f32 v[242:243], v[184:185], v[140:141]
	v_cvt_pk_bf16_f32 v240, v204, v205
	v_cvt_pk_bf16_f32 v241, v174, v175
	v_lshl_add_u64 v[174:175], v[176:177], 1, s[28:29]
	v_pk_mul_f32 v[244:245], v[180:181], v[142:143]
	v_cvt_pk_bf16_f32 v242, v242, v243
	s_nop 0
	v_cvt_pk_bf16_f32 v243, v244, v245
	global_store_dwordx4 v[174:175], v[240:243], off sc1
	v_mov_b32_e32 v175, v140
	v_mov_b32_e32 v140, v149
	v_mov_b32_e32 v149, v142
	v_mov_b32_e32 v142, v151
	v_mov_b32_e32 v174, v148
	v_pk_mul_f32 v[140:141], v[140:141], v[140:141]
	v_mov_b32_e32 v148, v150
	v_pk_mul_f32 v[142:143], v[142:143], v[142:143]
	v_pk_fma_f32 v[140:141], v[174:175], v[174:175], v[140:141]
	v_pk_fma_f32 v[142:143], v[148:149], v[148:149], v[142:143]
	s_nop 0
	v_pk_add_f32 v[140:141], v[140:141], v[142:143]
	s_nop 0
	v_add_f32_e32 v140, v140, v141
	v_add_f32_e32 v232, v232, v140
.LBB0_341:
	v_mov_b32_e32 v197, v196
	s_waitcnt vmcnt(2)
	v_pk_mul_f32 v[140:141], v[130:131], v[146:147]
	v_pk_mul_f32 v[142:143], v[128:129], v[144:145]
	v_mov_b32_e32 v144, v196
	v_mov_b32_e32 v145, v196
	v_pk_mul_f32 v[138:139], v[134:135], v[138:139]
	v_pk_mul_f32 v[136:137], v[132:133], v[136:137]
	v_pk_mul_f32 v[140:141], v[144:145], v[140:141]
	v_pk_mul_f32 v[146:147], v[196:197], v[142:143]
	v_pk_mul_f32 v[138:139], v[144:145], v[138:139]
	v_pk_mul_f32 v[136:137], v[196:197], v[136:137]
	v_pk_fma_f32 v[142:143], v[102:103], v[194:195], v[140:141]
	v_pk_fma_f32 v[140:141], v[100:101], v[198:199], v[146:147]
	v_pk_fma_f32 v[138:139], v[98:99], v[182:183], v[138:139]
	v_pk_fma_f32 v[136:137], v[96:97], v[192:193], v[136:137]
	v_lshl_add_u64 v[144:145], v[200:201], 2, s[30:31]
	s_and_b64 vcc, exec, s[8:9]
	global_store_dwordx4 v[144:145], v[140:143], off sc1
	global_store_dwordx4 v[144:145], v[136:139], off offset:16 sc1
	s_cbranch_vccnz .LBB0_343
	v_pk_mul_f32 v[146:147], v[188:189], v[142:143]
	v_pk_mul_f32 v[144:145], v[186:187], v[140:141]
	v_pk_mul_f32 v[148:149], v[180:181], v[138:139]
	v_pk_mul_f32 v[150:151], v[184:185], v[136:137]
	v_cvt_pk_bf16_f32 v144, v144, v145
	v_cvt_pk_bf16_f32 v145, v146, v147
	s_nop 0
	v_cvt_pk_bf16_f32 v146, v150, v151
	v_cvt_pk_bf16_f32 v147, v148, v149
	v_lshl_add_u64 v[148:149], v[200:201], 1, s[28:29]
	global_store_dwordx4 v[148:149], v[144:147], off sc1
	s_nop 1
	v_mov_b32_e32 v145, v136
	v_mov_b32_e32 v136, v141
	v_mov_b32_e32 v141, v138
	v_mov_b32_e32 v138, v143
	v_mov_b32_e32 v144, v140
	v_pk_mul_f32 v[136:137], v[136:137], v[136:137]
	v_mov_b32_e32 v140, v142
	v_pk_mul_f32 v[138:139], v[138:139], v[138:139]
	v_pk_fma_f32 v[136:137], v[144:145], v[144:145], v[136:137]
	v_pk_fma_f32 v[138:139], v[140:141], v[140:141], v[138:139]
	s_nop 0
	v_pk_add_f32 v[136:137], v[136:137], v[138:139]
	s_nop 0
	v_add_f32_e32 v136, v136, v137
	v_add_f32_e32 v231, v231, v136
;     static __device__ __forceinline__ void run(const f32x4 (&acc)[2][2][4][2], const Unit& u, int wr, int wc, int fr, int fq, const float* xin, float* xout, const float* gate, float gs, const float* lazy_ssq, const float* lazy_g, ...
;     ...
;                 gv[n] = *(const f32x4*)(gate + (b * 9216u + col + 4 * n)) * gs;
;                 lg[n] = (f32x4){1.f, 1.f, 1.f, 1.f}; if (LAZY) lg[n] = *(const f32x4*)(lazy_g + col + 4 * n);
;                 wv[n] = (f32x4){0.f, 0.f, 0.f, 0.f}; w2[n] = (f32x4){1.f, 1.f, 1.f, 1.f};
;                 if (aout) { wv[n] = *(const f32x4*)(wg + col + 4 * n) * (*(const f32x4*)(wsc + (b * 9216u + col + 4 * n)) + 1.0f); if (WG2) { w2[n] = *(const f32x4*)(wg2 + col + 4 * n); wv[n] = wv[n] * w2[n]; } }
;             }
;             f32x4 xq[2][2][2];
;     ...
;             constexpr bool DEEP = !LAZY && !WG2;
;             if (DEEP) RES_LD(0, 0);
; #pragma unroll
;             for (int pp = 0; pp < 4; ++pp) {
;                 if (DEEP) { if (pp < 3) RES_LD((pp + 1) & 1, pp + 1); } else RES_LD(pp & 1, pp);
; #pragma unroll
;                 for (int j = 0; j < 2; ++j) { const int i_ = 2 * pp + j, ai = i_ >> 2, m = i_ & 3; const unsigned off = (row0 + ai * HALF + m * 16) * 1024u + col;
;                     const f32x4 xi0 = xq[pp & 1][j][0], xi1 = xq[pp & 1][j][1];
;                     f32x4 xo0 = gv[0] * acc[ai][bj][m][0], xo1 = gv[1] * acc[ai][bj][m][1];
;                     if (LAZY) { xo0 = xo0 + xi0 * lg[0] * rl[ai][m]; xo1 = xo1 + xi1 * lg[1] * rl[ai][m]; } else { xo0 = xo0 + xi0; xo1 = xo1 + xi1; }
;                     *(f32x4*)(xout + off) = xo0; *(f32x4*)(xout + off + 4) = xo1;
;                     if (aout) { const f32x4 a0 = xo0 * wv[0], a1 = xo1 * wv[1]; u32x4 w; w.x = cvt_pk_bf16(a0[0], a0[1]); w.y = cvt_pk_bf16(a0[2], a0[3]); w.z = cvt_pk_bf16(a1[0], a1[1]); w.w = cvt_pk_bf16(a1[2], a1[3]);
;                         *(u32x4*)(aout + off) = w;
;                         sq[ai][m] += ((xo0[0] * xo0[0] + xo0[1] * xo0[1]) + (xo0[2] * xo0[2] + xo0[3] * xo0[3])) + ((xo1[0] * xo1[0] + xo1[1] * xo1[1]) + (xo1[2] * xo1[2] + xo1[3] * xo1[3]));
;                         if (WG2) { const f32x4 b0 = xo0 * w2[0], b1 = xo1 * w2[1]; sqb[ai][m] += ((b0[0] * b0[0] + b0[1] * b0[1]) + (b0[2] * b0[2] + b0[3] * b0[3])) + ((b1[0] * b1[0] + b1[1] * b1[1]) + (b1[2] * b1[2] + b1[3] * b1[3])); } } }
.LBB0_343:
	v_add_u32_e32 v196, 0x8000, v176
	v_mov_b32_e32 v197, v177
	v_lshlrev_b64 v[200:201], 2, v[196:197]
	v_lshl_add_u64 v[136:137], s[34:35], 0, v[200:201]
	global_load_dwordx4 v[144:147], v[136:137], off
	global_load_dwordx4 v[148:151], v[136:137], off offset:16
	v_add_u32_e32 v174, 0xc000, v176
	v_mov_b32_e32 v175, v177
	v_lshl_add_u64 v[140:141], v[174:175], 2, s[34:35]
	global_load_dwordx4 v[136:139], v[140:141], off offset:16
	s_nop 0
	global_load_dwordx4 v[140:143], v[140:141], off
	v_mov_b32_e32 v191, v190
	v_mov_b32_e32 v204, v190
	v_mov_b32_e32 v205, v190
	s_and_b64 vcc, exec, s[8:9]
	v_lshl_add_u64 v[200:201], s[30:31], 0, v[200:201]
	s_waitcnt vmcnt(3)
	v_pk_mul_f32 v[146:147], v[130:131], v[146:147]
	v_pk_mul_f32 v[144:145], v[128:129], v[144:145]
	s_waitcnt vmcnt(2)
	v_pk_mul_f32 v[150:151], v[134:135], v[150:151]
	v_pk_mul_f32 v[148:149], v[132:133], v[148:149]
	v_pk_mul_f32 v[146:147], v[204:205], v[146:147]
	v_pk_mul_f32 v[144:145], v[190:191], v[144:145]
	v_pk_mul_f32 v[204:205], v[204:205], v[150:151]
	v_pk_mul_f32 v[190:191], v[190:191], v[148:149]
	v_pk_fma_f32 v[150:151], v[86:87], v[194:195], v[146:147]
	v_pk_fma_f32 v[148:149], v[84:85], v[198:199], v[144:145]
	v_pk_fma_f32 v[146:147], v[82:83], v[182:183], v[204:205]
	v_pk_fma_f32 v[144:145], v[80:81], v[192:193], v[190:191]
	global_store_dwordx4 v[200:201], v[148:151], off sc1
	global_store_dwordx4 v[200:201], v[144:147], off offset:16 sc1
	s_cbranch_vccnz .LBB0_345
	v_pk_mul_f32 v[190:191], v[188:189], v[150:151]
	v_pk_mul_f32 v[200:201], v[186:187], v[148:149]
	v_pk_mul_f32 v[242:243], v[184:185], v[144:145]
	v_cvt_pk_bf16_f32 v240, v200, v201
	v_cvt_pk_bf16_f32 v241, v190, v191
	v_lshl_add_u64 v[190:191], v[196:197], 1, s[28:29]
	v_pk_mul_f32 v[204:205], v[180:181], v[146:147]
	v_cvt_pk_bf16_f32 v242, v242, v243
	s_nop 0
	v_cvt_pk_bf16_f32 v243, v204, v205
	global_store_dwordx4 v[190:191], v[240:243], off sc1
	v_mov_b32_e32 v191, v144
	v_mov_b32_e32 v144, v149
	v_mov_b32_e32 v149, v146
	v_mov_b32_e32 v146, v151
	v_mov_b32_e32 v190, v148
	v_pk_mul_f32 v[144:145], v[144:145], v[144:145]
	v_mov_b32_e32 v148, v150
	v_pk_mul_f32 v[146:147], v[146:147], v[146:147]
	v_pk_fma_f32 v[144:145], v[190:191], v[190:191], v[144:145]
	v_pk_fma_f32 v[146:147], v[148:149], v[148:149], v[146:147]
	s_nop 0
	v_pk_add_f32 v[144:145], v[144:145], v[146:147]
	s_nop 0
	v_add_f32_e32 v144, v144, v145
	v_add_f32_e32 v234, v234, v144
.LBB0_345:
	v_mov_b32_e32 v211, v210
	s_waitcnt vmcnt(2)
	v_pk_mul_f32 v[142:143], v[130:131], v[142:143]
	v_pk_mul_f32 v[140:141], v[128:129], v[140:141]
	v_mov_b32_e32 v144, v210
	v_mov_b32_e32 v145, v210
	v_pk_mul_f32 v[138:139], v[134:135], v[138:139]
	v_pk_mul_f32 v[136:137], v[132:133], v[136:137]
	v_pk_mul_f32 v[142:143], v[144:145], v[142:143]
	v_pk_mul_f32 v[140:141], v[210:211], v[140:141]
	v_pk_mul_f32 v[138:139], v[144:145], v[138:139]
	v_pk_mul_f32 v[136:137], v[210:211], v[136:137]
	v_pk_fma_f32 v[142:143], v[70:71], v[194:195], v[142:143]
	v_pk_fma_f32 v[140:141], v[68:69], v[198:199], v[140:141]
	v_pk_fma_f32 v[138:139], v[66:67], v[182:183], v[138:139]
	v_pk_fma_f32 v[136:137], v[64:65], v[192:193], v[136:137]
	v_lshl_add_u64 v[144:145], v[174:175], 2, s[30:31]
	s_and_b64 vcc, exec, s[8:9]
	global_store_dwordx4 v[144:145], v[140:143], off sc1
	global_store_dwordx4 v[144:145], v[136:139], off offset:16 sc1
	s_cbranch_vccnz .LBB0_347
	v_pk_mul_f32 v[146:147], v[188:189], v[142:143]
	v_pk_mul_f32 v[144:145], v[186:187], v[140:141]
	v_pk_mul_f32 v[148:149], v[180:181], v[138:139]
	v_pk_mul_f32 v[150:151], v[184:185], v[136:137]
	v_cvt_pk_bf16_f32 v144, v144, v145
	v_cvt_pk_bf16_f32 v145, v146, v147
	s_nop 0
	v_cvt_pk_bf16_f32 v146, v150, v151
	v_cvt_pk_bf16_f32 v147, v148, v149
	v_lshl_add_u64 v[148:149], v[174:175], 1, s[28:29]
	global_store_dwordx4 v[148:149], v[144:147], off sc1
	s_nop 1
	v_mov_b32_e32 v145, v136
	v_mov_b32_e32 v136, v141
	v_mov_b32_e32 v141, v138
	v_mov_b32_e32 v138, v143
	v_mov_b32_e32 v144, v140
	v_pk_mul_f32 v[136:137], v[136:137], v[136:137]
	v_mov_b32_e32 v140, v142
	v_pk_mul_f32 v[138:139], v[138:139], v[138:139]
	v_pk_fma_f32 v[136:137], v[144:145], v[144:145], v[136:137]
	v_pk_fma_f32 v[138:139], v[140:141], v[140:141], v[138:139]
	s_nop 0
	v_pk_add_f32 v[136:137], v[136:137], v[138:139]
	s_nop 0
	v_add_f32_e32 v136, v136, v137
	v_add_f32_e32 v233, v233, v136
.LBB0_347:
	v_add_u32_e32 v174, v213, v202
	v_mov_b32_e32 v175, v177
	v_lshl_add_u64 v[136:137], v[174:175], 2, s[34:35]
	global_load_dwordx4 v[148:151], v[136:137], off offset:16
	global_load_dwordx4 v[144:147], v[136:137], off
	v_add_u32_e32 v136, 0x4000, v174
	v_mov_b32_e32 v137, v177
	v_lshl_add_u64 v[140:141], v[136:137], 2, s[34:35]
	global_load_dwordx4 v[136:139], v[140:141], off offset:16
	s_nop 0
	global_load_dwordx4 v[140:143], v[140:141], off
	v_mov_b32_e32 v207, v206
	v_mov_b32_e32 v196, v206
	v_mov_b32_e32 v197, v206
	v_add_u32_e32 v190, 0x20000, v176
	v_mov_b32_e32 v191, v177
	s_and_b64 vcc, exec, s[8:9]
	s_waitcnt vmcnt(3)
	v_pk_mul_f32 v[150:151], v[134:135], v[150:151]
	s_waitcnt vmcnt(2)
	v_pk_mul_f32 v[146:147], v[130:131], v[146:147]
	v_pk_mul_f32 v[144:145], v[128:129], v[144:145]
	v_pk_mul_f32 v[148:149], v[132:133], v[148:149]
	v_pk_mul_f32 v[146:147], v[196:197], v[146:147]
	v_pk_mul_f32 v[144:145], v[206:207], v[144:145]
	v_pk_mul_f32 v[150:151], v[196:197], v[150:151]
	v_pk_mul_f32 v[148:149], v[206:207], v[148:149]
	v_pk_fma_f32 v[146:147], v[54:55], v[194:195], v[146:147]
	v_pk_fma_f32 v[144:145], v[52:53], v[198:199], v[144:145]
	v_pk_fma_f32 v[150:151], v[50:51], v[182:183], v[150:151]
	v_pk_fma_f32 v[148:149], v[48:49], v[192:193], v[148:149]
	v_lshl_add_u64 v[196:197], v[190:191], 2, s[30:31]
	global_store_dwordx4 v[196:197], v[144:147], off sc1
	global_store_dwordx4 v[196:197], v[148:151], off offset:16 sc1
	s_cbranch_vccnz .LBB0_349
	v_pk_mul_f32 v[200:201], v[186:187], v[144:145]
	v_pk_mul_f32 v[202:203], v[184:185], v[148:149]
	v_lshl_add_u64 v[190:191], v[190:191], 1, s[28:29]
	v_pk_mul_f32 v[196:197], v[188:189], v[146:147]
	v_pk_mul_f32 v[204:205], v[180:181], v[150:151]
	v_cvt_pk_bf16_f32 v200, v200, v201
	v_cvt_pk_bf16_f32 v201, v196, v197
	v_cvt_pk_bf16_f32 v202, v202, v203
	s_nop 0
	v_cvt_pk_bf16_f32 v203, v204, v205
	global_store_dwordx4 v[190:191], v[200:203], off sc1
	v_mov_b32_e32 v191, v148
	v_mov_b32_e32 v148, v145
	v_mov_b32_e32 v190, v144
	v_pk_mul_f32 v[144:145], v[148:149], v[148:149]
	v_mov_b32_e32 v149, v150
	v_mov_b32_e32 v150, v147
	v_mov_b32_e32 v148, v146
	v_pk_mul_f32 v[146:147], v[150:151], v[150:151]
	v_pk_fma_f32 v[144:145], v[190:191], v[190:191], v[144:145]
	v_pk_fma_f32 v[146:147], v[148:149], v[148:149], v[146:147]
	s_nop 0
	v_pk_add_f32 v[144:145], v[144:145], v[146:147]
	s_nop 0
	v_add_f32_e32 v144, v144, v145
	v_add_f32_e32 v236, v236, v144
;     static __device__ __forceinline__ void run(const f32x4 (&acc)[2][2][4][2], const Unit& u, int wr, int wc, int fr, int fq, const float* xin, float* xout, const float* gate, float gs, const float* lazy_ssq, const float* lazy_g, ...
;     ...
;                 gv[n] = *(const f32x4*)(gate + (b * 9216u + col + 4 * n)) * gs;
;                 lg[n] = (f32x4){1.f, 1.f, 1.f, 1.f}; if (LAZY) lg[n] = *(const f32x4*)(lazy_g + col + 4 * n);
;                 wv[n] = (f32x4){0.f, 0.f, 0.f, 0.f}; w2[n] = (f32x4){1.f, 1.f, 1.f, 1.f};
;                 if (aout) { wv[n] = *(const f32x4*)(wg + col + 4 * n) * (*(const f32x4*)(wsc + (b * 9216u + col + 4 * n)) + 1.0f); if (WG2) { w2[n] = *(const f32x4*)(wg2 + col + 4 * n); wv[n] = wv[n] * w2[n]; } }
;             }
;             f32x4 xq[2][2][2];
;     ...
;             constexpr bool DEEP = !LAZY && !WG2;
;             if (DEEP) RES_LD(0, 0);
; #pragma unroll
;             for (int pp = 0; pp < 4; ++pp) {
;                 if (DEEP) { if (pp < 3) RES_LD((pp + 1) & 1, pp + 1); } else RES_LD(pp & 1, pp);
; #pragma unroll
;                 for (int j = 0; j < 2; ++j) { const int i_ = 2 * pp + j, ai = i_ >> 2, m = i_ & 3; const unsigned off = (row0 + ai * HALF + m * 16) * 1024u + col;
;                     const f32x4 xi0 = xq[pp & 1][j][0], xi1 = xq[pp & 1][j][1];
;                     f32x4 xo0 = gv[0] * acc[ai][bj][m][0], xo1 = gv[1] * acc[ai][bj][m][1];
;                     if (LAZY) { xo0 = xo0 + xi0 * lg[0] * rl[ai][m]; xo1 = xo1 + xi1 * lg[1] * rl[ai][m]; } else { xo0 = xo0 + xi0; xo1 = xo1 + xi1; }
;                     *(f32x4*)(xout + off) = xo0; *(f32x4*)(xout + off + 4) = xo1;
;                     if (aout) { const f32x4 a0 = xo0 * wv[0], a1 = xo1 * wv[1]; u32x4 w; w.x = cvt_pk_bf16(a0[0], a0[1]); w.y = cvt_pk_bf16(a0[2], a0[3]); w.z = cvt_pk_bf16(a1[0], a1[1]); w.w = cvt_pk_bf16(a1[2], a1[3]);
;                         *(u32x4*)(aout + off) = w;
;                         sq[ai][m] += ((xo0[0] * xo0[0] + xo0[1] * xo0[1]) + (xo0[2] * xo0[2] + xo0[3] * xo0[3])) + ((xo1[0] * xo1[0] + xo1[1] * xo1[1]) + (xo1[2] * xo1[2] + xo1[3] * xo1[3]));
;                         if (WG2) { const f32x4 b0 = xo0 * w2[0], b1 = xo1 * w2[1]; sqb[ai][m] += ((b0[0] * b0[0] + b0[1] * b0[1]) + (b0[2] * b0[2] + b0[3] * b0[3])) + ((b1[0] * b1[0] + b1[1] * b1[1]) + (b1[2] * b1[2] + b1[3] * b1[3])); } } }
.LBB0_349:
	v_mov_b32_e32 v213, v212
	s_waitcnt vmcnt(2)
	v_pk_mul_f32 v[142:143], v[130:131], v[142:143]
	v_pk_mul_f32 v[140:141], v[128:129], v[140:141]
	v_mov_b32_e32 v146, v212
	v_mov_b32_e32 v147, v212
	v_pk_mul_f32 v[138:139], v[134:135], v[138:139]
	v_pk_mul_f32 v[136:137], v[132:133], v[136:137]
	v_add_u32_e32 v144, 0x24000, v176
	v_pk_mul_f32 v[142:143], v[146:147], v[142:143]
	v_pk_mul_f32 v[140:141], v[212:213], v[140:141]
	v_pk_mul_f32 v[138:139], v[146:147], v[138:139]
	v_pk_mul_f32 v[136:137], v[212:213], v[136:137]
	v_mov_b32_e32 v145, v177
	v_pk_fma_f32 v[142:143], v[38:39], v[194:195], v[142:143]
	v_pk_fma_f32 v[140:141], v[36:37], v[198:199], v[140:141]
	v_pk_fma_f32 v[138:139], v[34:35], v[182:183], v[138:139]
	v_pk_fma_f32 v[136:137], v[32:33], v[192:193], v[136:137]
	v_lshl_add_u64 v[146:147], v[144:145], 2, s[30:31]
	s_and_b64 vcc, exec, s[8:9]
	global_store_dwordx4 v[146:147], v[140:143], off sc1
	global_store_dwordx4 v[146:147], v[136:139], off offset:16 sc1
	s_cbranch_vccnz .LBB0_351
	v_pk_mul_f32 v[148:149], v[188:189], v[142:143]
	v_pk_mul_f32 v[146:147], v[186:187], v[140:141]
	v_lshl_add_u64 v[144:145], v[144:145], 1, s[28:29]
	v_pk_mul_f32 v[150:151], v[180:181], v[138:139]
	v_pk_mul_f32 v[190:191], v[184:185], v[136:137]
	v_cvt_pk_bf16_f32 v146, v146, v147
	v_cvt_pk_bf16_f32 v147, v148, v149
	s_nop 0
	v_cvt_pk_bf16_f32 v148, v190, v191
	v_cvt_pk_bf16_f32 v149, v150, v151
	global_store_dwordx4 v[144:145], v[146:149], off sc1
	v_mov_b32_e32 v145, v136
	v_mov_b32_e32 v136, v141
	v_mov_b32_e32 v141, v138
	v_mov_b32_e32 v138, v143
	v_mov_b32_e32 v144, v140
	v_pk_mul_f32 v[136:137], v[136:137], v[136:137]
	v_mov_b32_e32 v140, v142
	v_pk_mul_f32 v[138:139], v[138:139], v[138:139]
	v_pk_fma_f32 v[136:137], v[144:145], v[144:145], v[136:137]
	v_pk_fma_f32 v[138:139], v[140:141], v[140:141], v[138:139]
	s_nop 0
	v_pk_add_f32 v[136:137], v[136:137], v[138:139]
	s_nop 0
	v_add_f32_e32 v136, v136, v137
	v_add_f32_e32 v235, v235, v136
.LBB0_351:
	s_nop 0
	v_add_u32_e32 v136, 0x8000, v174
	v_mov_b32_e32 v137, v177
	v_lshl_add_u64 v[136:137], v[136:137], 2, s[34:35]
	global_load_dwordx4 v[148:151], v[136:137], off offset:16
	global_load_dwordx4 v[144:147], v[136:137], off
	v_add_u32_e32 v136, 0xc000, v174
	v_mov_b32_e32 v137, v177
	v_lshl_add_u64 v[140:141], v[136:137], 2, s[34:35]
	global_load_dwordx4 v[136:139], v[140:141], off offset:16
	s_nop 0
	global_load_dwordx4 v[140:143], v[140:141], off
	v_mov_b32_e32 v209, v208
	v_mov_b32_e32 v190, v208
	v_mov_b32_e32 v191, v208
	v_add_u32_e32 v174, 0x28000, v176
	v_mov_b32_e32 v175, v177
	s_and_b64 vcc, exec, s[8:9]
	s_waitcnt vmcnt(3)
	v_pk_mul_f32 v[150:151], v[134:135], v[150:151]
	s_waitcnt vmcnt(2)
	v_pk_mul_f32 v[146:147], v[130:131], v[146:147]
	v_pk_mul_f32 v[144:145], v[128:129], v[144:145]
	v_pk_mul_f32 v[148:149], v[132:133], v[148:149]
	v_pk_mul_f32 v[146:147], v[190:191], v[146:147]
	v_pk_mul_f32 v[144:145], v[208:209], v[144:145]
	v_pk_mul_f32 v[150:151], v[190:191], v[150:151]
	v_pk_mul_f32 v[148:149], v[208:209], v[148:149]
	v_pk_fma_f32 v[146:147], v[22:23], v[194:195], v[146:147]
	v_pk_fma_f32 v[144:145], v[20:21], v[198:199], v[144:145]
	v_pk_fma_f32 v[150:151], v[18:19], v[182:183], v[150:151]
	v_pk_fma_f32 v[148:149], v[16:17], v[192:193], v[148:149]
	v_lshl_add_u64 v[190:191], v[174:175], 2, s[30:31]
	global_store_dwordx4 v[190:191], v[144:147], off sc1
	global_store_dwordx4 v[190:191], v[148:151], off offset:16 sc1
	s_cbranch_vccnz .LBB0_353
	v_pk_mul_f32 v[202:203], v[184:185], v[148:149]
	v_lshl_add_u64 v[174:175], v[174:175], 1, s[28:29]
	v_pk_mul_f32 v[190:191], v[188:189], v[146:147]
	v_pk_mul_f32 v[196:197], v[186:187], v[144:145]
	v_pk_mul_f32 v[204:205], v[180:181], v[150:151]
	v_cvt_pk_bf16_f32 v200, v196, v197
	v_cvt_pk_bf16_f32 v201, v190, v191
	v_cvt_pk_bf16_f32 v202, v202, v203
	s_nop 0
	v_cvt_pk_bf16_f32 v203, v204, v205
	global_store_dwordx4 v[174:175], v[200:203], off sc1
	v_mov_b32_e32 v175, v148
	v_mov_b32_e32 v148, v145
	v_mov_b32_e32 v174, v144
	v_pk_mul_f32 v[144:145], v[148:149], v[148:149]
	v_mov_b32_e32 v149, v150
	v_mov_b32_e32 v150, v147
	v_mov_b32_e32 v148, v146
	v_pk_mul_f32 v[146:147], v[150:151], v[150:151]
	v_pk_fma_f32 v[144:145], v[174:175], v[174:175], v[144:145]
	v_pk_fma_f32 v[146:147], v[148:149], v[148:149], v[146:147]
	s_nop 0
	v_pk_add_f32 v[144:145], v[144:145], v[146:147]
	s_nop 0
	v_add_f32_e32 v144, v144, v145
	v_add_f32_e32 v238, v238, v144
.LBB0_353:
	v_mov_b32_e32 v215, v214
	s_waitcnt vmcnt(2)
	v_pk_mul_f32 v[130:131], v[130:131], v[142:143]
	v_pk_mul_f32 v[128:129], v[128:129], v[140:141]
	v_mov_b32_e32 v140, v214
	v_mov_b32_e32 v141, v214
	v_pk_mul_f32 v[134:135], v[134:135], v[138:139]
	v_pk_mul_f32 v[132:133], v[132:133], v[136:137]
	v_add_u32_e32 v176, 0x2c000, v176
	v_pk_mul_f32 v[130:131], v[140:141], v[130:131]
	v_pk_mul_f32 v[128:129], v[214:215], v[128:129]
	v_pk_mul_f32 v[134:135], v[140:141], v[134:135]
	v_pk_mul_f32 v[132:133], v[214:215], v[132:133]
	v_pk_fma_f32 v[130:131], v[6:7], v[194:195], v[130:131]
	v_pk_fma_f32 v[128:129], v[4:5], v[198:199], v[128:129]
	v_pk_fma_f32 v[134:135], v[2:3], v[182:183], v[134:135]
	v_pk_fma_f32 v[132:133], v[0:1], v[192:193], v[132:133]
	v_lshl_add_u64 v[136:137], v[176:177], 2, s[30:31]
	s_and_b64 vcc, exec, s[8:9]
	global_store_dwordx4 v[136:137], v[128:131], off sc1
	global_store_dwordx4 v[136:137], v[132:135], off offset:16 sc1
	s_cbranch_vccnz .LBB0_355
	v_pk_mul_f32 v[138:139], v[188:189], v[130:131]
	v_pk_mul_f32 v[136:137], v[186:187], v[128:129]
	v_pk_mul_f32 v[140:141], v[180:181], v[134:135]
	v_pk_mul_f32 v[142:143], v[184:185], v[132:133]
	v_cvt_pk_bf16_f32 v136, v136, v137
	v_cvt_pk_bf16_f32 v137, v138, v139
	s_nop 0
	v_cvt_pk_bf16_f32 v138, v142, v143
	v_cvt_pk_bf16_f32 v139, v140, v141
	v_lshl_add_u64 v[140:141], v[176:177], 1, s[28:29]
	global_store_dwordx4 v[140:141], v[136:139], off sc1
	s_nop 1
	v_mov_b32_e32 v137, v132
	v_mov_b32_e32 v132, v129
	v_mov_b32_e32 v136, v128
	v_pk_mul_f32 v[128:129], v[132:133], v[132:133]
	v_mov_b32_e32 v133, v134
	v_mov_b32_e32 v134, v131
	v_mov_b32_e32 v132, v130
	v_pk_mul_f32 v[130:131], v[134:135], v[134:135]
	v_pk_fma_f32 v[128:129], v[136:137], v[136:137], v[128:129]
	v_pk_fma_f32 v[130:131], v[132:133], v[132:133], v[130:131]
	s_nop 0
	v_pk_add_f32 v[128:129], v[128:129], v[130:131]
	s_nop 0
	v_add_f32_e32 v128, v128, v129
	v_add_f32_e32 v237, v237, v128

;     static __device__ __forceinline__ void run(const f32x4 (&acc)[2][2][4][2], const Unit& u, int wr, int wc, int fr, int fq, const float* xin, float* xout, const float* gate, float gs, const float* lazy_ssq, const float* lazy_g, ...
;     ...
;                 gv[n] = *(const f32x4*)(gate + (b * 9216u + col + 4 * n)) * gs;
;                 lg[n] = (f32x4){1.f, 1.f, 1.f, 1.f}; if (LAZY) lg[n] = *(const f32x4*)(lazy_g + col + 4 * n);
;                 wv[n] = (f32x4){0.f, 0.f, 0.f, 0.f}; w2[n] = (f32x4){1.f, 1.f, 1.f, 1.f};
;                 if (aout) { wv[n] = *(const f32x4*)(wg + col + 4 * n) * (*(const f32x4*)(wsc + (b * 9216u + col + 4 * n)) + 1.0f); if (WG2) { w2[n] = *(const f32x4*)(wg2 + col + 4 * n); wv[n] = wv[n] * w2[n]; } }
;             }
;             f32x4 xq[2][2][2];
;     ...
;             constexpr bool DEEP = !LAZY && !WG2;
;             if (DEEP) RES_LD(0, 0);
; #pragma unroll
;             for (int pp = 0; pp < 4; ++pp) {
;                 if (DEEP) { if (pp < 3) RES_LD((pp + 1) & 1, pp + 1); } else RES_LD(pp & 1, pp);
; #pragma unroll
;                 for (int j = 0; j < 2; ++j) { const int i_ = 2 * pp + j, ai = i_ >> 2, m = i_ & 3; const unsigned off = (row0 + ai * HALF + m * 16) * 1024u + col;
;                     const f32x4 xi0 = xq[pp & 1][j][0], xi1 = xq[pp & 1][j][1];
;                     f32x4 xo0 = gv[0] * acc[ai][bj][m][0], xo1 = gv[1] * acc[ai][bj][m][1];
;                     if (LAZY) { xo0 = xo0 + xi0 * lg[0] * rl[ai][m]; xo1 = xo1 + xi1 * lg[1] * rl[ai][m]; } else { xo0 = xo0 + xi0; xo1 = xo1 + xi1; }
;                     *(f32x4*)(xout + off) = xo0; *(f32x4*)(xout + off + 4) = xo1;
;                     if (aout) { const f32x4 a0 = xo0 * wv[0], a1 = xo1 * wv[1]; u32x4 w; w.x = cvt_pk_bf16(a0[0], a0[1]); w.y = cvt_pk_bf16(a0[2], a0[3]); w.z = cvt_pk_bf16(a1[0], a1[1]); w.w = cvt_pk_bf16(a1[2], a1[3]);
;                         *(u32x4*)(aout + off) = w;
;                         sq[ai][m] += ((xo0[0] * xo0[0] + xo0[1] * xo0[1]) + (xo0[2] * xo0[2] + xo0[3] * xo0[3])) + ((xo1[0] * xo1[0] + xo1[1] * xo1[1]) + (xo1[2] * xo1[2] + xo1[3] * xo1[3]));
;                         if (WG2) { const f32x4 b0 = xo0 * w2[0], b1 = xo1 * w2[1]; sqb[ai][m] += ((b0[0] * b0[0] + b0[1] * b0[1]) + (b0[2] * b0[2] + b0[3] * b0[3])) + ((b1[0] * b1[0] + b1[1] * b1[1]) + (b1[2] * b1[2] + b1[3] * b1[3])); } } }
.LBB0_381:
	s_lshl_b32 s67, s63, 8
	s_lshl_b32 s68, s65, 6
	s_add_i32 s68, s68, s67
	v_or_b32_e32 v152, s68, v230
	v_lshlrev_b32_e32 v153, 10, v152
	v_add_u32_e32 v176, v192, v153
	v_lshlrev_b64 v[154:155], 2, v[176:177]
	v_lshl_add_u64 v[140:141], s[38:39], 0, v[154:155]
	v_add_u32_e32 v156, 0x4000, v176
	v_mov_b32_e32 v157, v177
	global_load_dwordx4 v[172:175], v[140:141], off
	global_load_dwordx4 v[180:183], v[140:141], off offset:16
	v_lshl_add_u64 v[148:149], v[156:157], 2, s[38:39]
	global_load_dwordx4 v[140:143], v[148:149], off offset:16
	s_nop 0
	global_load_dwordx4 v[148:151], v[148:149], off
	s_waitcnt vmcnt(0)
	v_pk_mul_f32 v[202:203], s[40:41], v[146:147] op_sel_hi:[0,1]
	v_pk_mul_f32 v[200:201], s[40:41], v[144:145] op_sel_hi:[0,1]
	v_pk_mul_f32 v[204:205], s[40:41], v[138:139] op_sel_hi:[0,1]
	v_pk_mul_f32 v[206:207], s[40:41], v[136:137] op_sel_hi:[0,1]
	s_and_b64 vcc, exec, s[8:9]
	v_lshl_add_u64 v[154:155], s[36:37], 0, v[154:155]
	v_pk_fma_f32 v[146:147], v[126:127], v[204:205], v[174:175]
	v_pk_fma_f32 v[144:145], v[124:125], v[206:207], v[172:173]
	v_pk_fma_f32 v[138:139], v[122:123], v[202:203], v[182:183]
	v_pk_fma_f32 v[136:137], v[120:121], v[200:201], v[180:181]
	global_store_dwordx4 v[154:155], v[144:147], off sc1
	global_store_dwordx4 v[154:155], v[136:139], off offset:16 sc1
	s_cbranch_vccnz .LBB0_383
	v_pk_mul_f32 v[154:155], v[194:195], v[146:147]
	v_pk_mul_f32 v[158:159], v[186:187], v[144:145]
	v_pk_mul_f32 v[180:181], v[198:199], v[138:139]
	v_pk_mul_f32 v[174:175], v[196:197], v[136:137]
	v_cvt_pk_bf16_f32 v172, v158, v159
	v_cvt_pk_bf16_f32 v173, v154, v155
	v_lshl_add_u64 v[154:155], v[176:177], 1, s[34:35]
	v_pk_mul_f32 v[158:159], v[132:133], v[144:145]
	v_cvt_pk_bf16_f32 v174, v174, v175
	v_cvt_pk_bf16_f32 v175, v180, v181
	global_store_dwordx4 v[154:155], v[172:175], off sc1
	v_pk_mul_f32 v[154:155], v[134:135], v[146:147]
	v_mov_b32_e32 v181, v158
	v_mov_b32_e32 v158, v145
	v_mov_b32_e32 v180, v144
	v_pk_mul_f32 v[144:145], v[158:159], v[158:159]
	v_mov_b32_e32 v159, v154
	v_mov_b32_e32 v154, v147
	v_mov_b32_e32 v158, v146
	v_pk_mul_f32 v[146:147], v[154:155], v[154:155]
	v_pk_mul_f32 v[174:175], v[128:129], v[136:137]
	v_pk_fma_f32 v[144:145], v[180:181], v[180:181], v[144:145]
	v_pk_fma_f32 v[146:147], v[158:159], v[158:159], v[146:147]
	v_pk_mul_f32 v[172:173], v[130:131], v[138:139]
	v_pk_add_f32 v[144:145], v[144:145], v[146:147]
	v_mov_b32_e32 v147, v174
	v_mov_b32_e32 v174, v137
	v_mov_b32_e32 v146, v136
	v_pk_mul_f32 v[136:137], v[174:175], v[174:175]
	s_nop 0
	v_pk_fma_f32 v[136:137], v[146:147], v[146:147], v[136:137]
	v_mov_b32_e32 v147, v172
	v_mov_b32_e32 v172, v139
	v_mov_b32_e32 v146, v138
	v_pk_mul_f32 v[138:139], v[172:173], v[172:173]
	s_nop 0
	v_pk_fma_f32 v[138:139], v[146:147], v[146:147], v[138:139]
	s_nop 0
	v_pk_add_f32 v[136:137], v[136:137], v[138:139]
	s_nop 0
	v_pk_add_f32 v[154:155], v[144:145], v[136:137]
	s_branch .LBB0_384

;     static __device__ __forceinline__ void run(const f32x4 (&acc)[2][2][4][2], const Unit& u, int wr, int wc, int fr, int fq, const float* xin, float* xout, const float* gate, float gs, const float* lazy_ssq, const float* lazy_g, ...
;     ...
;                 gv[n] = *(const f32x4*)(gate + (b * 9216u + col + 4 * n)) * gs;
;                 lg[n] = (f32x4){1.f, 1.f, 1.f, 1.f}; if (LAZY) lg[n] = *(const f32x4*)(lazy_g + col + 4 * n);
;                 wv[n] = (f32x4){0.f, 0.f, 0.f, 0.f}; w2[n] = (f32x4){1.f, 1.f, 1.f, 1.f};
;                 if (aout) { wv[n] = *(const f32x4*)(wg + col + 4 * n) * (*(const f32x4*)(wsc + (b * 9216u + col + 4 * n)) + 1.0f); if (WG2) { w2[n] = *(const f32x4*)(wg2 + col + 4 * n); wv[n] = wv[n] * w2[n]; } }
;             }
;             f32x4 xq[2][2][2];
;     ...
;             constexpr bool DEEP = !LAZY && !WG2;
;             if (DEEP) RES_LD(0, 0);
; #pragma unroll
;             for (int pp = 0; pp < 4; ++pp) {
;                 if (DEEP) { if (pp < 3) RES_LD((pp + 1) & 1, pp + 1); } else RES_LD(pp & 1, pp);
; #pragma unroll
;                 for (int j = 0; j < 2; ++j) { const int i_ = 2 * pp + j, ai = i_ >> 2, m = i_ & 3; const unsigned off = (row0 + ai * HALF + m * 16) * 1024u + col;
;                     const f32x4 xi0 = xq[pp & 1][j][0], xi1 = xq[pp & 1][j][1];
;                     f32x4 xo0 = gv[0] * acc[ai][bj][m][0], xo1 = gv[1] * acc[ai][bj][m][1];
;                     if (LAZY) { xo0 = xo0 + xi0 * lg[0] * rl[ai][m]; xo1 = xo1 + xi1 * lg[1] * rl[ai][m]; } else { xo0 = xo0 + xi0; xo1 = xo1 + xi1; }
;                     *(f32x4*)(xout + off) = xo0; *(f32x4*)(xout + off + 4) = xo1;
;                     if (aout) { const f32x4 a0 = xo0 * wv[0], a1 = xo1 * wv[1]; u32x4 w; w.x = cvt_pk_bf16(a0[0], a0[1]); w.y = cvt_pk_bf16(a0[2], a0[3]); w.z = cvt_pk_bf16(a1[0], a1[1]); w.w = cvt_pk_bf16(a1[2], a1[3]);
;                         *(u32x4*)(aout + off) = w;
;                         sq[ai][m] += ((xo0[0] * xo0[0] + xo0[1] * xo0[1]) + (xo0[2] * xo0[2] + xo0[3] * xo0[3])) + ((xo1[0] * xo1[0] + xo1[1] * xo1[1]) + (xo1[2] * xo1[2] + xo1[3] * xo1[3]));
;                         if (WG2) { const f32x4 b0 = xo0 * w2[0], b1 = xo1 * w2[1]; sqb[ai][m] += ((b0[0] * b0[0] + b0[1] * b0[1]) + (b0[2] * b0[2] + b0[3] * b0[3])) + ((b1[0] * b1[0] + b1[1] * b1[1]) + (b1[2] * b1[2] + b1[3] * b1[3])); } } }
.LBB0_384:
	v_pk_fma_f32 v[146:147], v[110:111], v[204:205], v[150:151]
	v_pk_fma_f32 v[144:145], v[108:109], v[206:207], v[148:149]
	v_pk_fma_f32 v[138:139], v[106:107], v[202:203], v[142:143]
	v_pk_fma_f32 v[136:137], v[104:105], v[200:201], v[140:141]
	v_lshl_add_u64 v[140:141], v[156:157], 2, s[36:37]
	s_and_b64 vcc, exec, s[8:9]
	global_store_dwordx4 v[140:141], v[144:147], off sc1
	global_store_dwordx4 v[140:141], v[136:139], off offset:16 sc1
	s_cbranch_vccnz .LBB0_386
	v_pk_mul_f32 v[142:143], v[194:195], v[146:147]
	v_pk_mul_f32 v[140:141], v[186:187], v[144:145]
	v_pk_mul_f32 v[148:149], v[198:199], v[138:139]
	v_pk_mul_f32 v[150:151], v[196:197], v[136:137]
	v_cvt_pk_bf16_f32 v140, v140, v141
	v_cvt_pk_bf16_f32 v141, v142, v143
	s_nop 0
	v_cvt_pk_bf16_f32 v142, v150, v151
	v_cvt_pk_bf16_f32 v143, v148, v149
	v_lshl_add_u64 v[148:149], v[156:157], 1, s[34:35]
	global_store_dwordx4 v[148:149], v[140:143], off sc1
	v_mov_b32_e32 v156, v144
	v_pk_mul_f32 v[150:151], v[128:129], v[136:137]
	v_pk_mul_f32 v[140:141], v[134:135], v[146:147]
	v_pk_mul_f32 v[142:143], v[132:133], v[144:145]
	v_mov_b32_e32 v144, v146
	v_mov_b32_e32 v157, v142
	v_mov_b32_e32 v142, v145
	v_mov_b32_e32 v145, v140
	v_mov_b32_e32 v140, v147
	v_pk_mul_f32 v[142:143], v[142:143], v[142:143]
	v_pk_mul_f32 v[140:141], v[140:141], v[140:141]
	v_pk_fma_f32 v[142:143], v[156:157], v[156:157], v[142:143]
	v_pk_fma_f32 v[140:141], v[144:145], v[144:145], v[140:141]
	v_pk_mul_f32 v[148:149], v[130:131], v[138:139]
	v_pk_add_f32 v[140:141], v[142:143], v[140:141]
	v_mov_b32_e32 v143, v150
	v_mov_b32_e32 v150, v137
	v_mov_b32_e32 v142, v136
	v_pk_mul_f32 v[136:137], v[150:151], v[150:151]
	s_nop 0
	v_pk_fma_f32 v[136:137], v[142:143], v[142:143], v[136:137]
	v_mov_b32_e32 v143, v148
	v_mov_b32_e32 v148, v139
	v_mov_b32_e32 v142, v138
	v_pk_mul_f32 v[138:139], v[148:149], v[148:149]
	s_nop 0
	v_pk_fma_f32 v[138:139], v[142:143], v[142:143], v[138:139]
	s_nop 0
	v_pk_add_f32 v[136:137], v[136:137], v[138:139]
	s_nop 0
	v_pk_add_f32 v[156:157], v[140:141], v[136:137]
	s_branch .LBB0_387

;     static __device__ __forceinline__ void run(const f32x4 (&acc)[2][2][4][2], const Unit& u, int wr, int wc, int fr, int fq, const float* xin, float* xout, const float* gate, float gs, const float* lazy_ssq, const float* lazy_g, ...
;     ...
;                 gv[n] = *(const f32x4*)(gate + (b * 9216u + col + 4 * n)) * gs;
;                 lg[n] = (f32x4){1.f, 1.f, 1.f, 1.f}; if (LAZY) lg[n] = *(const f32x4*)(lazy_g + col + 4 * n);
;                 wv[n] = (f32x4){0.f, 0.f, 0.f, 0.f}; w2[n] = (f32x4){1.f, 1.f, 1.f, 1.f};
;                 if (aout) { wv[n] = *(const f32x4*)(wg + col + 4 * n) * (*(const f32x4*)(wsc + (b * 9216u + col + 4 * n)) + 1.0f); if (WG2) { w2[n] = *(const f32x4*)(wg2 + col + 4 * n); wv[n] = wv[n] * w2[n]; } }
;             }
;             f32x4 xq[2][2][2];
;     ...
;             constexpr bool DEEP = !LAZY && !WG2;
;             if (DEEP) RES_LD(0, 0);
; #pragma unroll
;             for (int pp = 0; pp < 4; ++pp) {
;                 if (DEEP) { if (pp < 3) RES_LD((pp + 1) & 1, pp + 1); } else RES_LD(pp & 1, pp);
; #pragma unroll
;                 for (int j = 0; j < 2; ++j) { const int i_ = 2 * pp + j, ai = i_ >> 2, m = i_ & 3; const unsigned off = (row0 + ai * HALF + m * 16) * 1024u + col;
;                     const f32x4 xi0 = xq[pp & 1][j][0], xi1 = xq[pp & 1][j][1];
;                     f32x4 xo0 = gv[0] * acc[ai][bj][m][0], xo1 = gv[1] * acc[ai][bj][m][1];
;                     if (LAZY) { xo0 = xo0 + xi0 * lg[0] * rl[ai][m]; xo1 = xo1 + xi1 * lg[1] * rl[ai][m]; } else { xo0 = xo0 + xi0; xo1 = xo1 + xi1; }
;                     *(f32x4*)(xout + off) = xo0; *(f32x4*)(xout + off + 4) = xo1;
;                     if (aout) { const f32x4 a0 = xo0 * wv[0], a1 = xo1 * wv[1]; u32x4 w; w.x = cvt_pk_bf16(a0[0], a0[1]); w.y = cvt_pk_bf16(a0[2], a0[3]); w.z = cvt_pk_bf16(a1[0], a1[1]); w.w = cvt_pk_bf16(a1[2], a1[3]);
;                         *(u32x4*)(aout + off) = w;
;                         sq[ai][m] += ((xo0[0] * xo0[0] + xo0[1] * xo0[1]) + (xo0[2] * xo0[2] + xo0[3] * xo0[3])) + ((xo1[0] * xo1[0] + xo1[1] * xo1[1]) + (xo1[2] * xo1[2] + xo1[3] * xo1[3]));
;                         if (WG2) { const f32x4 b0 = xo0 * w2[0], b1 = xo1 * w2[1]; sqb[ai][m] += ((b0[0] * b0[0] + b0[1] * b0[1]) + (b0[2] * b0[2] + b0[3] * b0[3])) + ((b1[0] * b1[0] + b1[1] * b1[1]) + (b1[2] * b1[2] + b1[3] * b1[3])); } } }
.LBB0_387:
	v_add_u32_e32 v158, 0x8000, v176
	v_mov_b32_e32 v159, v177
	v_lshlrev_b64 v[148:149], 2, v[158:159]
	v_lshl_add_u64 v[136:137], s[38:39], 0, v[148:149]
	v_add_u32_e32 v172, 0xc000, v176
	v_mov_b32_e32 v173, v177
	global_load_dwordx4 v[144:147], v[136:137], off
	global_load_dwordx4 v[180:183], v[136:137], off offset:16
	v_lshl_add_u64 v[140:141], v[172:173], 2, s[38:39]
	global_load_dwordx4 v[136:139], v[140:141], off offset:16
	s_nop 0
	global_load_dwordx4 v[140:143], v[140:141], off
	s_and_b64 vcc, exec, s[8:9]
	v_lshl_add_u64 v[174:175], s[36:37], 0, v[148:149]
	s_waitcnt vmcnt(3)
	v_pk_fma_f32 v[150:151], v[94:95], v[204:205], v[146:147]
	v_pk_fma_f32 v[148:149], v[92:93], v[206:207], v[144:145]
	s_waitcnt vmcnt(2)
	v_pk_fma_f32 v[146:147], v[90:91], v[202:203], v[182:183]
	v_pk_fma_f32 v[144:145], v[88:89], v[200:201], v[180:181]
	global_store_dwordx4 v[174:175], v[148:151], off sc1
	global_store_dwordx4 v[174:175], v[144:147], off offset:16 sc1
	s_cbranch_vccnz .LBB0_389
	v_pk_mul_f32 v[174:175], v[194:195], v[150:151]
	v_pk_mul_f32 v[180:181], v[186:187], v[148:149]
	v_pk_mul_f32 v[184:185], v[198:199], v[146:147]
	v_pk_mul_f32 v[182:183], v[196:197], v[144:145]
	v_cvt_pk_bf16_f32 v180, v180, v181
	v_cvt_pk_bf16_f32 v181, v174, v175
	v_lshl_add_u64 v[158:159], v[158:159], 1, s[34:35]
	v_pk_mul_f32 v[174:175], v[132:133], v[148:149]
	v_cvt_pk_bf16_f32 v182, v182, v183
	v_cvt_pk_bf16_f32 v183, v184, v185
	global_store_dwordx4 v[158:159], v[180:183], off sc1
	v_pk_mul_f32 v[158:159], v[134:135], v[150:151]
	v_mov_b32_e32 v185, v174
	v_mov_b32_e32 v174, v149
	v_mov_b32_e32 v184, v148
	v_pk_mul_f32 v[148:149], v[174:175], v[174:175]
	v_mov_b32_e32 v175, v158
	v_mov_b32_e32 v158, v151
	v_mov_b32_e32 v174, v150
	v_pk_mul_f32 v[150:151], v[158:159], v[158:159]
	v_pk_mul_f32 v[182:183], v[128:129], v[144:145]
	v_pk_fma_f32 v[148:149], v[184:185], v[184:185], v[148:149]
	v_pk_fma_f32 v[150:151], v[174:175], v[174:175], v[150:151]
	v_pk_mul_f32 v[180:181], v[130:131], v[146:147]
	v_pk_add_f32 v[148:149], v[148:149], v[150:151]
	v_mov_b32_e32 v151, v182
	v_mov_b32_e32 v182, v145
	v_mov_b32_e32 v150, v144
	v_pk_mul_f32 v[144:145], v[182:183], v[182:183]
	s_nop 0
	v_pk_fma_f32 v[144:145], v[150:151], v[150:151], v[144:145]
	v_mov_b32_e32 v151, v180
	v_mov_b32_e32 v180, v147
	v_mov_b32_e32 v150, v146
	v_pk_mul_f32 v[146:147], v[180:181], v[180:181]
	s_nop 0
	v_pk_fma_f32 v[146:147], v[150:151], v[150:151], v[146:147]
	s_nop 0
	v_pk_add_f32 v[144:145], v[144:145], v[146:147]
	s_nop 0
	v_pk_add_f32 v[158:159], v[148:149], v[144:145]
	s_branch .LBB0_390

;     static __device__ __forceinline__ void run(const f32x4 (&acc)[2][2][4][2], const Unit& u, int wr, int wc, int fr, int fq, const float* xin, float* xout, const float* gate, float gs, const float* lazy_ssq, const float* lazy_g, ...
;     ...
;                 gv[n] = *(const f32x4*)(gate + (b * 9216u + col + 4 * n)) * gs;
;                 lg[n] = (f32x4){1.f, 1.f, 1.f, 1.f}; if (LAZY) lg[n] = *(const f32x4*)(lazy_g + col + 4 * n);
;                 wv[n] = (f32x4){0.f, 0.f, 0.f, 0.f}; w2[n] = (f32x4){1.f, 1.f, 1.f, 1.f};
;                 if (aout) { wv[n] = *(const f32x4*)(wg + col + 4 * n) * (*(const f32x4*)(wsc + (b * 9216u + col + 4 * n)) + 1.0f); if (WG2) { w2[n] = *(const f32x4*)(wg2 + col + 4 * n); wv[n] = wv[n] * w2[n]; } }
;             }
;             f32x4 xq[2][2][2];
;     ...
;             constexpr bool DEEP = !LAZY && !WG2;
;             if (DEEP) RES_LD(0, 0);
; #pragma unroll
;             for (int pp = 0; pp < 4; ++pp) {
;                 if (DEEP) { if (pp < 3) RES_LD((pp + 1) & 1, pp + 1); } else RES_LD(pp & 1, pp);
; #pragma unroll
;                 for (int j = 0; j < 2; ++j) { const int i_ = 2 * pp + j, ai = i_ >> 2, m = i_ & 3; const unsigned off = (row0 + ai * HALF + m * 16) * 1024u + col;
;                     const f32x4 xi0 = xq[pp & 1][j][0], xi1 = xq[pp & 1][j][1];
;                     f32x4 xo0 = gv[0] * acc[ai][bj][m][0], xo1 = gv[1] * acc[ai][bj][m][1];
;                     if (LAZY) { xo0 = xo0 + xi0 * lg[0] * rl[ai][m]; xo1 = xo1 + xi1 * lg[1] * rl[ai][m]; } else { xo0 = xo0 + xi0; xo1 = xo1 + xi1; }
;                     *(f32x4*)(xout + off) = xo0; *(f32x4*)(xout + off + 4) = xo1;
;                     if (aout) { const f32x4 a0 = xo0 * wv[0], a1 = xo1 * wv[1]; u32x4 w; w.x = cvt_pk_bf16(a0[0], a0[1]); w.y = cvt_pk_bf16(a0[2], a0[3]); w.z = cvt_pk_bf16(a1[0], a1[1]); w.w = cvt_pk_bf16(a1[2], a1[3]);
;                         *(u32x4*)(aout + off) = w;
;                         sq[ai][m] += ((xo0[0] * xo0[0] + xo0[1] * xo0[1]) + (xo0[2] * xo0[2] + xo0[3] * xo0[3])) + ((xo1[0] * xo1[0] + xo1[1] * xo1[1]) + (xo1[2] * xo1[2] + xo1[3] * xo1[3]));
;                         if (WG2) { const f32x4 b0 = xo0 * w2[0], b1 = xo1 * w2[1]; sqb[ai][m] += ((b0[0] * b0[0] + b0[1] * b0[1]) + (b0[2] * b0[2] + b0[3] * b0[3])) + ((b1[0] * b1[0] + b1[1] * b1[1]) + (b1[2] * b1[2] + b1[3] * b1[3])); } } }
.LBB0_390:
	s_waitcnt vmcnt(2)
	v_pk_fma_f32 v[142:143], v[78:79], v[204:205], v[142:143]
	v_pk_fma_f32 v[140:141], v[76:77], v[206:207], v[140:141]
	v_pk_fma_f32 v[138:139], v[74:75], v[202:203], v[138:139]
	v_pk_fma_f32 v[136:137], v[72:73], v[200:201], v[136:137]
	v_lshl_add_u64 v[144:145], v[172:173], 2, s[36:37]
	s_and_b64 vcc, exec, s[8:9]
	global_store_dwordx4 v[144:145], v[140:143], off sc1
	global_store_dwordx4 v[144:145], v[136:139], off offset:16 sc1
	s_cbranch_vccnz .LBB0_392
	v_pk_mul_f32 v[146:147], v[194:195], v[142:143]
	v_pk_mul_f32 v[144:145], v[186:187], v[140:141]
	v_pk_mul_f32 v[148:149], v[198:199], v[138:139]
	v_pk_mul_f32 v[150:151], v[196:197], v[136:137]
	v_cvt_pk_bf16_f32 v144, v144, v145
	v_cvt_pk_bf16_f32 v145, v146, v147
	s_nop 0
	v_cvt_pk_bf16_f32 v146, v150, v151
	v_cvt_pk_bf16_f32 v147, v148, v149
	v_lshl_add_u64 v[148:149], v[172:173], 1, s[34:35]
	global_store_dwordx4 v[148:149], v[144:147], off sc1
	v_mov_b32_e32 v172, v140
	v_pk_mul_f32 v[150:151], v[128:129], v[136:137]
	v_pk_mul_f32 v[146:147], v[132:133], v[140:141]
	v_pk_mul_f32 v[144:145], v[134:135], v[142:143]
	v_mov_b32_e32 v173, v146
	v_mov_b32_e32 v146, v141
	v_pk_mul_f32 v[140:141], v[146:147], v[146:147]
	v_mov_b32_e32 v147, v144
	v_mov_b32_e32 v144, v143
	v_mov_b32_e32 v146, v142
	v_pk_mul_f32 v[142:143], v[144:145], v[144:145]
	v_pk_fma_f32 v[140:141], v[172:173], v[172:173], v[140:141]
	v_pk_fma_f32 v[142:143], v[146:147], v[146:147], v[142:143]
	v_pk_mul_f32 v[148:149], v[130:131], v[138:139]
	v_pk_add_f32 v[140:141], v[140:141], v[142:143]
	v_mov_b32_e32 v143, v150
	v_mov_b32_e32 v150, v137
	v_mov_b32_e32 v142, v136
	v_pk_mul_f32 v[136:137], v[150:151], v[150:151]
	s_nop 0
	v_pk_fma_f32 v[136:137], v[142:143], v[142:143], v[136:137]
	v_mov_b32_e32 v143, v148
	v_mov_b32_e32 v148, v139
	v_mov_b32_e32 v142, v138
	v_pk_mul_f32 v[138:139], v[148:149], v[148:149]
	s_nop 0
	v_pk_fma_f32 v[138:139], v[142:143], v[142:143], v[138:139]
	s_nop 0
	v_pk_add_f32 v[136:137], v[136:137], v[138:139]
	s_nop 0
	v_pk_add_f32 v[174:175], v[140:141], v[136:137]
	s_branch .LBB0_393

;     static __device__ __forceinline__ void run(const f32x4 (&acc)[2][2][4][2], const Unit& u, int wr, int wc, int fr, int fq, const float* xin, float* xout, const float* gate, float gs, const float* lazy_ssq, const float* lazy_g, ...
;     ...
;                 gv[n] = *(const f32x4*)(gate + (b * 9216u + col + 4 * n)) * gs;
;                 lg[n] = (f32x4){1.f, 1.f, 1.f, 1.f}; if (LAZY) lg[n] = *(const f32x4*)(lazy_g + col + 4 * n);
;                 wv[n] = (f32x4){0.f, 0.f, 0.f, 0.f}; w2[n] = (f32x4){1.f, 1.f, 1.f, 1.f};
;                 if (aout) { wv[n] = *(const f32x4*)(wg + col + 4 * n) * (*(const f32x4*)(wsc + (b * 9216u + col + 4 * n)) + 1.0f); if (WG2) { w2[n] = *(const f32x4*)(wg2 + col + 4 * n); wv[n] = wv[n] * w2[n]; } }
;             }
;             f32x4 xq[2][2][2];
;     ...
;             constexpr bool DEEP = !LAZY && !WG2;
;             if (DEEP) RES_LD(0, 0);
; #pragma unroll
;             for (int pp = 0; pp < 4; ++pp) {
;                 if (DEEP) { if (pp < 3) RES_LD((pp + 1) & 1, pp + 1); } else RES_LD(pp & 1, pp);
; #pragma unroll
;                 for (int j = 0; j < 2; ++j) { const int i_ = 2 * pp + j, ai = i_ >> 2, m = i_ & 3; const unsigned off = (row0 + ai * HALF + m * 16) * 1024u + col;
;                     const f32x4 xi0 = xq[pp & 1][j][0], xi1 = xq[pp & 1][j][1];
;                     f32x4 xo0 = gv[0] * acc[ai][bj][m][0], xo1 = gv[1] * acc[ai][bj][m][1];
;                     if (LAZY) { xo0 = xo0 + xi0 * lg[0] * rl[ai][m]; xo1 = xo1 + xi1 * lg[1] * rl[ai][m]; } else { xo0 = xo0 + xi0; xo1 = xo1 + xi1; }
;                     *(f32x4*)(xout + off) = xo0; *(f32x4*)(xout + off + 4) = xo1;
;                     if (aout) { const f32x4 a0 = xo0 * wv[0], a1 = xo1 * wv[1]; u32x4 w; w.x = cvt_pk_bf16(a0[0], a0[1]); w.y = cvt_pk_bf16(a0[2], a0[3]); w.z = cvt_pk_bf16(a1[0], a1[1]); w.w = cvt_pk_bf16(a1[2], a1[3]);
;                         *(u32x4*)(aout + off) = w;
;                         sq[ai][m] += ((xo0[0] * xo0[0] + xo0[1] * xo0[1]) + (xo0[2] * xo0[2] + xo0[3] * xo0[3])) + ((xo1[0] * xo1[0] + xo1[1] * xo1[1]) + (xo1[2] * xo1[2] + xo1[3] * xo1[3]));
;                         if (WG2) { const f32x4 b0 = xo0 * w2[0], b1 = xo1 * w2[1]; sqb[ai][m] += ((b0[0] * b0[0] + b0[1] * b0[1]) + (b0[2] * b0[2] + b0[3] * b0[3])) + ((b1[0] * b1[0] + b1[1] * b1[1]) + (b1[2] * b1[2] + b1[3] * b1[3])); } } }
.LBB0_393:
	v_add_u32_e32 v172, 0x80, v152
	v_lshlrev_b32_e32 v173, 10, v172
	v_add_u32_e32 v184, v173, v192
	v_mov_b32_e32 v185, v177
	v_lshl_add_u64 v[136:137], v[184:185], 2, s[38:39]
	global_load_dwordx4 v[144:147], v[136:137], off offset:16
	global_load_dwordx4 v[148:151], v[136:137], off
	v_add_u32_e32 v136, 0x4000, v184
	v_mov_b32_e32 v137, v177
	v_lshl_add_u64 v[140:141], v[136:137], 2, s[38:39]
	global_load_dwordx4 v[136:139], v[140:141], off offset:16
	s_nop 0
	global_load_dwordx4 v[140:143], v[140:141], off
	v_add_u32_e32 v180, 0x20000, v176
	v_mov_b32_e32 v181, v177
	v_lshl_add_u64 v[182:183], v[180:181], 2, s[36:37]
	s_and_b64 vcc, exec, s[8:9]
	s_waitcnt vmcnt(3)
	v_pk_fma_f32 v[146:147], v[58:59], v[202:203], v[146:147]
	s_waitcnt vmcnt(2)
	v_pk_fma_f32 v[150:151], v[62:63], v[204:205], v[150:151]
	v_pk_fma_f32 v[148:149], v[60:61], v[206:207], v[148:149]
	v_pk_fma_f32 v[144:145], v[56:57], v[200:201], v[144:145]
	global_store_dwordx4 v[182:183], v[148:151], off sc1
	global_store_dwordx4 v[182:183], v[144:147], off offset:16 sc1
	s_cbranch_vccnz .LBB0_395
	v_pk_mul_f32 v[182:183], v[194:195], v[150:151]
	v_pk_mul_f32 v[208:209], v[186:187], v[148:149]
	v_pk_mul_f32 v[212:213], v[198:199], v[146:147]
	v_pk_mul_f32 v[210:211], v[196:197], v[144:145]
	v_cvt_pk_bf16_f32 v208, v208, v209
	v_cvt_pk_bf16_f32 v209, v182, v183
	v_lshl_add_u64 v[180:181], v[180:181], 1, s[34:35]
	v_pk_mul_f32 v[182:183], v[132:133], v[148:149]
	v_cvt_pk_bf16_f32 v210, v210, v211
	v_cvt_pk_bf16_f32 v211, v212, v213
	global_store_dwordx4 v[180:181], v[208:211], off sc1
	v_pk_mul_f32 v[180:181], v[134:135], v[150:151]
	v_mov_b32_e32 v213, v182
	v_mov_b32_e32 v182, v149
	v_mov_b32_e32 v212, v148
	v_pk_mul_f32 v[148:149], v[182:183], v[182:183]
	v_mov_b32_e32 v183, v180
	v_mov_b32_e32 v180, v151
	v_mov_b32_e32 v182, v150
	v_pk_mul_f32 v[150:151], v[180:181], v[180:181]
	v_pk_mul_f32 v[210:211], v[128:129], v[144:145]
	v_pk_fma_f32 v[148:149], v[212:213], v[212:213], v[148:149]
	v_pk_fma_f32 v[150:151], v[182:183], v[182:183], v[150:151]
	v_pk_mul_f32 v[208:209], v[130:131], v[146:147]
	v_pk_add_f32 v[148:149], v[148:149], v[150:151]
	v_mov_b32_e32 v151, v210
	v_mov_b32_e32 v210, v145
	v_mov_b32_e32 v150, v144
	v_pk_mul_f32 v[144:145], v[210:211], v[210:211]
	s_nop 0
	v_pk_fma_f32 v[144:145], v[150:151], v[150:151], v[144:145]
	v_mov_b32_e32 v151, v208
	v_mov_b32_e32 v208, v147
	v_mov_b32_e32 v150, v146
	v_pk_mul_f32 v[146:147], v[208:209], v[208:209]
	s_nop 0
	v_pk_fma_f32 v[146:147], v[150:151], v[150:151], v[146:147]
	s_nop 0
	v_pk_add_f32 v[144:145], v[144:145], v[146:147]
	s_nop 0
	v_pk_add_f32 v[180:181], v[148:149], v[144:145]
	s_branch .LBB0_396

;     static __device__ __forceinline__ void run(const f32x4 (&acc)[2][2][4][2], const Unit& u, int wr, int wc, int fr, int fq, const float* xin, float* xout, const float* gate, float gs, const float* lazy_ssq, const float* lazy_g, ...
;     ...
;                 gv[n] = *(const f32x4*)(gate + (b * 9216u + col + 4 * n)) * gs;
;                 lg[n] = (f32x4){1.f, 1.f, 1.f, 1.f}; if (LAZY) lg[n] = *(const f32x4*)(lazy_g + col + 4 * n);
;                 wv[n] = (f32x4){0.f, 0.f, 0.f, 0.f}; w2[n] = (f32x4){1.f, 1.f, 1.f, 1.f};
;                 if (aout) { wv[n] = *(const f32x4*)(wg + col + 4 * n) * (*(const f32x4*)(wsc + (b * 9216u + col + 4 * n)) + 1.0f); if (WG2) { w2[n] = *(const f32x4*)(wg2 + col + 4 * n); wv[n] = wv[n] * w2[n]; } }
;             }
;             f32x4 xq[2][2][2];
;     ...
;             constexpr bool DEEP = !LAZY && !WG2;
;             if (DEEP) RES_LD(0, 0);
; #pragma unroll
;             for (int pp = 0; pp < 4; ++pp) {
;                 if (DEEP) { if (pp < 3) RES_LD((pp + 1) & 1, pp + 1); } else RES_LD(pp & 1, pp);
; #pragma unroll
;                 for (int j = 0; j < 2; ++j) { const int i_ = 2 * pp + j, ai = i_ >> 2, m = i_ & 3; const unsigned off = (row0 + ai * HALF + m * 16) * 1024u + col;
;                     const f32x4 xi0 = xq[pp & 1][j][0], xi1 = xq[pp & 1][j][1];
;                     f32x4 xo0 = gv[0] * acc[ai][bj][m][0], xo1 = gv[1] * acc[ai][bj][m][1];
;                     if (LAZY) { xo0 = xo0 + xi0 * lg[0] * rl[ai][m]; xo1 = xo1 + xi1 * lg[1] * rl[ai][m]; } else { xo0 = xo0 + xi0; xo1 = xo1 + xi1; }
;                     *(f32x4*)(xout + off) = xo0; *(f32x4*)(xout + off + 4) = xo1;
;                     if (aout) { const f32x4 a0 = xo0 * wv[0], a1 = xo1 * wv[1]; u32x4 w; w.x = cvt_pk_bf16(a0[0], a0[1]); w.y = cvt_pk_bf16(a0[2], a0[3]); w.z = cvt_pk_bf16(a1[0], a1[1]); w.w = cvt_pk_bf16(a1[2], a1[3]);
;                         *(u32x4*)(aout + off) = w;
;                         sq[ai][m] += ((xo0[0] * xo0[0] + xo0[1] * xo0[1]) + (xo0[2] * xo0[2] + xo0[3] * xo0[3])) + ((xo1[0] * xo1[0] + xo1[1] * xo1[1]) + (xo1[2] * xo1[2] + xo1[3] * xo1[3]));
;                         if (WG2) { const f32x4 b0 = xo0 * w2[0], b1 = xo1 * w2[1]; sqb[ai][m] += ((b0[0] * b0[0] + b0[1] * b0[1]) + (b0[2] * b0[2] + b0[3] * b0[3])) + ((b1[0] * b1[0] + b1[1] * b1[1]) + (b1[2] * b1[2] + b1[3] * b1[3])); } } }
.LBB0_396:
	v_add_u32_e32 v144, 0x24000, v176
	v_mov_b32_e32 v145, v177
	s_waitcnt vmcnt(2)
	v_pk_fma_f32 v[142:143], v[46:47], v[204:205], v[142:143]
	v_pk_fma_f32 v[140:141], v[44:45], v[206:207], v[140:141]
	v_pk_fma_f32 v[138:139], v[42:43], v[202:203], v[138:139]
	v_pk_fma_f32 v[136:137], v[40:41], v[200:201], v[136:137]
	v_lshl_add_u64 v[146:147], v[144:145], 2, s[36:37]
	s_and_b64 vcc, exec, s[8:9]
	global_store_dwordx4 v[146:147], v[140:143], off sc1
	global_store_dwordx4 v[146:147], v[136:139], off offset:16 sc1
	s_cbranch_vccnz .LBB0_398
	v_pk_mul_f32 v[146:147], v[186:187], v[140:141]
	v_pk_mul_f32 v[148:149], v[194:195], v[142:143]
	v_cvt_pk_bf16_f32 v146, v146, v147
	v_lshl_add_u64 v[144:145], v[144:145], 1, s[34:35]
	v_cvt_pk_bf16_f32 v147, v148, v149
	v_pk_mul_f32 v[150:151], v[198:199], v[138:139]
	v_pk_mul_f32 v[182:183], v[196:197], v[136:137]
	s_nop 0
	v_cvt_pk_bf16_f32 v148, v182, v183
	v_cvt_pk_bf16_f32 v149, v150, v151
	global_store_dwordx4 v[144:145], v[146:149], off sc1
	v_pk_mul_f32 v[144:145], v[134:135], v[142:143]
	v_mov_b32_e32 v182, v140
	v_pk_mul_f32 v[146:147], v[132:133], v[140:141]
	v_pk_mul_f32 v[150:151], v[128:129], v[136:137]
	v_mov_b32_e32 v183, v146
	v_mov_b32_e32 v146, v141
	v_pk_mul_f32 v[140:141], v[146:147], v[146:147]
	v_mov_b32_e32 v147, v144
	v_mov_b32_e32 v144, v143
	v_mov_b32_e32 v146, v142
	v_pk_mul_f32 v[142:143], v[144:145], v[144:145]
	v_pk_fma_f32 v[140:141], v[182:183], v[182:183], v[140:141]
	v_pk_fma_f32 v[142:143], v[146:147], v[146:147], v[142:143]
	v_pk_mul_f32 v[148:149], v[130:131], v[138:139]
	v_pk_add_f32 v[140:141], v[140:141], v[142:143]
	v_mov_b32_e32 v143, v150
	v_mov_b32_e32 v150, v137
	v_mov_b32_e32 v142, v136
	v_pk_mul_f32 v[136:137], v[150:151], v[150:151]
	s_nop 0
	v_pk_fma_f32 v[136:137], v[142:143], v[142:143], v[136:137]
	v_mov_b32_e32 v143, v148
	v_mov_b32_e32 v148, v139
	v_mov_b32_e32 v142, v138
	v_pk_mul_f32 v[138:139], v[148:149], v[148:149]
	s_nop 0
	v_pk_fma_f32 v[138:139], v[142:143], v[142:143], v[138:139]
	s_nop 0
	v_pk_add_f32 v[136:137], v[136:137], v[138:139]
	s_nop 0
	v_pk_add_f32 v[182:183], v[140:141], v[136:137]
	s_branch .LBB0_399

;     static __device__ __forceinline__ void run(const f32x4 (&acc)[2][2][4][2], const Unit& u, int wr, int wc, int fr, int fq, const float* xin, float* xout, const float* gate, float gs, const float* lazy_ssq, const float* lazy_g, ...
;     ...
;                 gv[n] = *(const f32x4*)(gate + (b * 9216u + col + 4 * n)) * gs;
;                 lg[n] = (f32x4){1.f, 1.f, 1.f, 1.f}; if (LAZY) lg[n] = *(const f32x4*)(lazy_g + col + 4 * n);
;                 wv[n] = (f32x4){0.f, 0.f, 0.f, 0.f}; w2[n] = (f32x4){1.f, 1.f, 1.f, 1.f};
;                 if (aout) { wv[n] = *(const f32x4*)(wg + col + 4 * n) * (*(const f32x4*)(wsc + (b * 9216u + col + 4 * n)) + 1.0f); if (WG2) { w2[n] = *(const f32x4*)(wg2 + col + 4 * n); wv[n] = wv[n] * w2[n]; } }
;             }
;             f32x4 xq[2][2][2];
;     ...
;             constexpr bool DEEP = !LAZY && !WG2;
;             if (DEEP) RES_LD(0, 0);
; #pragma unroll
;             for (int pp = 0; pp < 4; ++pp) {
;                 if (DEEP) { if (pp < 3) RES_LD((pp + 1) & 1, pp + 1); } else RES_LD(pp & 1, pp);
; #pragma unroll
;                 for (int j = 0; j < 2; ++j) { const int i_ = 2 * pp + j, ai = i_ >> 2, m = i_ & 3; const unsigned off = (row0 + ai * HALF + m * 16) * 1024u + col;
;                     const f32x4 xi0 = xq[pp & 1][j][0], xi1 = xq[pp & 1][j][1];
;                     f32x4 xo0 = gv[0] * acc[ai][bj][m][0], xo1 = gv[1] * acc[ai][bj][m][1];
;                     if (LAZY) { xo0 = xo0 + xi0 * lg[0] * rl[ai][m]; xo1 = xo1 + xi1 * lg[1] * rl[ai][m]; } else { xo0 = xo0 + xi0; xo1 = xo1 + xi1; }
;                     *(f32x4*)(xout + off) = xo0; *(f32x4*)(xout + off + 4) = xo1;
;                     if (aout) { const f32x4 a0 = xo0 * wv[0], a1 = xo1 * wv[1]; u32x4 w; w.x = cvt_pk_bf16(a0[0], a0[1]); w.y = cvt_pk_bf16(a0[2], a0[3]); w.z = cvt_pk_bf16(a1[0], a1[1]); w.w = cvt_pk_bf16(a1[2], a1[3]);
;                         *(u32x4*)(aout + off) = w;
;                         sq[ai][m] += ((xo0[0] * xo0[0] + xo0[1] * xo0[1]) + (xo0[2] * xo0[2] + xo0[3] * xo0[3])) + ((xo1[0] * xo1[0] + xo1[1] * xo1[1]) + (xo1[2] * xo1[2] + xo1[3] * xo1[3]));
;                         if (WG2) { const f32x4 b0 = xo0 * w2[0], b1 = xo1 * w2[1]; sqb[ai][m] += ((b0[0] * b0[0] + b0[1] * b0[1]) + (b0[2] * b0[2] + b0[3] * b0[3])) + ((b1[0] * b1[0] + b1[1] * b1[1]) + (b1[2] * b1[2] + b1[3] * b1[3])); } } }
.LBB0_399:
	v_add_u32_e32 v136, 0x8000, v184
	v_mov_b32_e32 v137, v177
	v_lshl_add_u64 v[136:137], v[136:137], 2, s[38:39]
	global_load_dwordx4 v[144:147], v[136:137], off offset:16
	global_load_dwordx4 v[148:151], v[136:137], off
	v_add_u32_e32 v136, 0xc000, v184
	v_mov_b32_e32 v137, v177
	v_lshl_add_u64 v[140:141], v[136:137], 2, s[38:39]
	global_load_dwordx4 v[136:139], v[140:141], off offset:16
	s_nop 0
	global_load_dwordx4 v[140:143], v[140:141], off
	v_add_u32_e32 v184, 0x28000, v176
	v_mov_b32_e32 v185, v177
	v_lshl_add_u64 v[208:209], v[184:185], 2, s[36:37]
	s_and_b64 vcc, exec, s[8:9]
	s_waitcnt vmcnt(3)
	v_pk_fma_f32 v[146:147], v[26:27], v[202:203], v[146:147]
	s_waitcnt vmcnt(2)
	v_pk_fma_f32 v[150:151], v[30:31], v[204:205], v[150:151]
	v_pk_fma_f32 v[148:149], v[28:29], v[206:207], v[148:149]
	v_pk_fma_f32 v[144:145], v[24:25], v[200:201], v[144:145]
	global_store_dwordx4 v[208:209], v[148:151], off sc1
	global_store_dwordx4 v[208:209], v[144:147], off offset:16 sc1
	s_cbranch_vccnz .LBB0_401
	v_pk_mul_f32 v[208:209], v[186:187], v[148:149]
	v_pk_mul_f32 v[210:211], v[194:195], v[150:151]
	v_cvt_pk_bf16_f32 v208, v208, v209
	v_lshl_add_u64 v[184:185], v[184:185], 1, s[34:35]
	v_cvt_pk_bf16_f32 v209, v210, v211
	v_pk_mul_f32 v[212:213], v[198:199], v[146:147]
	v_pk_mul_f32 v[214:215], v[196:197], v[144:145]
	s_nop 0
	v_cvt_pk_bf16_f32 v210, v214, v215
	v_cvt_pk_bf16_f32 v211, v212, v213
	global_store_dwordx4 v[184:185], v[208:211], off sc1
	v_pk_mul_f32 v[184:185], v[134:135], v[150:151]
	v_mov_b32_e32 v214, v148
	v_pk_mul_f32 v[208:209], v[132:133], v[148:149]
	v_pk_mul_f32 v[212:213], v[128:129], v[144:145]
	v_mov_b32_e32 v215, v208
	v_mov_b32_e32 v208, v149
	v_pk_mul_f32 v[148:149], v[208:209], v[208:209]
	v_mov_b32_e32 v209, v184
	v_mov_b32_e32 v184, v151
	v_mov_b32_e32 v208, v150
	v_pk_mul_f32 v[150:151], v[184:185], v[184:185]
	v_pk_fma_f32 v[148:149], v[214:215], v[214:215], v[148:149]
	v_pk_fma_f32 v[150:151], v[208:209], v[208:209], v[150:151]
	v_pk_mul_f32 v[210:211], v[130:131], v[146:147]
	v_pk_add_f32 v[148:149], v[148:149], v[150:151]
	v_mov_b32_e32 v151, v212
	v_mov_b32_e32 v212, v145
	v_mov_b32_e32 v150, v144
	v_pk_mul_f32 v[144:145], v[212:213], v[212:213]
	s_nop 0
	v_pk_fma_f32 v[144:145], v[150:151], v[150:151], v[144:145]
	v_mov_b32_e32 v151, v210
	v_mov_b32_e32 v210, v147
	v_mov_b32_e32 v150, v146
	v_pk_mul_f32 v[146:147], v[210:211], v[210:211]
	s_nop 0
	v_pk_fma_f32 v[146:147], v[150:151], v[150:151], v[146:147]
	s_nop 0
	v_pk_add_f32 v[144:145], v[144:145], v[146:147]
	s_nop 0
	v_pk_add_f32 v[184:185], v[148:149], v[144:145]
	s_branch .LBB0_402

;     static __device__ __forceinline__ void run(const f32x4 (&acc)[2][2][4][2], const Unit& u, int wr, int wc, int fr, int fq, const float* xin, float* xout, const float* gate, float gs, const float* lazy_ssq, const float* lazy_g, ...
;     ...
;                 gv[n] = *(const f32x4*)(gate + (b * 9216u + col + 4 * n)) * gs;
;                 lg[n] = (f32x4){1.f, 1.f, 1.f, 1.f}; if (LAZY) lg[n] = *(const f32x4*)(lazy_g + col + 4 * n);
;                 wv[n] = (f32x4){0.f, 0.f, 0.f, 0.f}; w2[n] = (f32x4){1.f, 1.f, 1.f, 1.f};
;                 if (aout) { wv[n] = *(const f32x4*)(wg + col + 4 * n) * (*(const f32x4*)(wsc + (b * 9216u + col + 4 * n)) + 1.0f); if (WG2) { w2[n] = *(const f32x4*)(wg2 + col + 4 * n); wv[n] = wv[n] * w2[n]; } }
;             }
;             f32x4 xq[2][2][2];
;     ...
;             constexpr bool DEEP = !LAZY && !WG2;
;             if (DEEP) RES_LD(0, 0);
; #pragma unroll
;             for (int pp = 0; pp < 4; ++pp) {
;                 if (DEEP) { if (pp < 3) RES_LD((pp + 1) & 1, pp + 1); } else RES_LD(pp & 1, pp);
; #pragma unroll
;                 for (int j = 0; j < 2; ++j) { const int i_ = 2 * pp + j, ai = i_ >> 2, m = i_ & 3; const unsigned off = (row0 + ai * HALF + m * 16) * 1024u + col;
;                     const f32x4 xi0 = xq[pp & 1][j][0], xi1 = xq[pp & 1][j][1];
;                     f32x4 xo0 = gv[0] * acc[ai][bj][m][0], xo1 = gv[1] * acc[ai][bj][m][1];
;                     if (LAZY) { xo0 = xo0 + xi0 * lg[0] * rl[ai][m]; xo1 = xo1 + xi1 * lg[1] * rl[ai][m]; } else { xo0 = xo0 + xi0; xo1 = xo1 + xi1; }
;                     *(f32x4*)(xout + off) = xo0; *(f32x4*)(xout + off + 4) = xo1;
;                     if (aout) { const f32x4 a0 = xo0 * wv[0], a1 = xo1 * wv[1]; u32x4 w; w.x = cvt_pk_bf16(a0[0], a0[1]); w.y = cvt_pk_bf16(a0[2], a0[3]); w.z = cvt_pk_bf16(a1[0], a1[1]); w.w = cvt_pk_bf16(a1[2], a1[3]);
;                         *(u32x4*)(aout + off) = w;
;                         sq[ai][m] += ((xo0[0] * xo0[0] + xo0[1] * xo0[1]) + (xo0[2] * xo0[2] + xo0[3] * xo0[3])) + ((xo1[0] * xo1[0] + xo1[1] * xo1[1]) + (xo1[2] * xo1[2] + xo1[3] * xo1[3]));
;                         if (WG2) { const f32x4 b0 = xo0 * w2[0], b1 = xo1 * w2[1]; sqb[ai][m] += ((b0[0] * b0[0] + b0[1] * b0[1]) + (b0[2] * b0[2] + b0[3] * b0[3])) + ((b1[0] * b1[0] + b1[1] * b1[1]) + (b1[2] * b1[2] + b1[3] * b1[3])); } } }
.LBB0_402:
	v_add_u32_e32 v176, 0x2c000, v176
	s_waitcnt vmcnt(2)
	v_pk_fma_f32 v[142:143], v[14:15], v[204:205], v[142:143]
	v_pk_fma_f32 v[140:141], v[12:13], v[206:207], v[140:141]
	v_pk_fma_f32 v[138:139], v[10:11], v[202:203], v[138:139]
	v_pk_fma_f32 v[136:137], v[8:9], v[200:201], v[136:137]
	v_lshl_add_u64 v[144:145], v[176:177], 2, s[36:37]
	s_and_b64 vcc, exec, s[8:9]
	global_store_dwordx4 v[144:145], v[140:143], off sc1
	global_store_dwordx4 v[144:145], v[136:139], off offset:16 sc1
	s_cbranch_vccnz .LBB0_404
	v_pk_mul_f32 v[146:147], v[194:195], v[142:143]
	v_pk_mul_f32 v[144:145], v[186:187], v[140:141]
	v_pk_mul_f32 v[148:149], v[198:199], v[138:139]
	v_pk_mul_f32 v[150:151], v[196:197], v[136:137]
	v_cvt_pk_bf16_f32 v144, v144, v145
	v_cvt_pk_bf16_f32 v145, v146, v147
	v_pk_mul_f32 v[134:135], v[134:135], v[142:143]
	v_cvt_pk_bf16_f32 v146, v150, v151
	v_cvt_pk_bf16_f32 v147, v148, v149
	v_lshl_add_u64 v[148:149], v[176:177], 1, s[34:35]
	v_pk_mul_f32 v[132:133], v[132:133], v[140:141]
	global_store_dwordx4 v[148:149], v[144:147], off sc1
	v_pk_mul_f32 v[128:129], v[128:129], v[136:137]
	v_pk_mul_f32 v[130:131], v[130:131], v[138:139]
	v_mov_b32_e32 v145, v132
	v_mov_b32_e32 v132, v141
	v_mov_b32_e32 v141, v134
	v_mov_b32_e32 v134, v143
	v_mov_b32_e32 v144, v140
	v_pk_mul_f32 v[132:133], v[132:133], v[132:133]
	v_mov_b32_e32 v140, v142
	v_pk_mul_f32 v[134:135], v[134:135], v[134:135]
	v_pk_fma_f32 v[132:133], v[144:145], v[144:145], v[132:133]
	v_pk_fma_f32 v[134:135], v[140:141], v[140:141], v[134:135]
	s_nop 0
	v_pk_add_f32 v[132:133], v[132:133], v[134:135]
	v_mov_b32_e32 v135, v128
	v_mov_b32_e32 v128, v137
	v_mov_b32_e32 v134, v136
	v_pk_mul_f32 v[128:129], v[128:129], v[128:129]
	s_nop 0
	v_pk_fma_f32 v[128:129], v[134:135], v[134:135], v[128:129]
	v_mov_b32_e32 v135, v130
	v_mov_b32_e32 v130, v139
	v_mov_b32_e32 v134, v138
	v_pk_mul_f32 v[130:131], v[130:131], v[130:131]
	s_nop 0
	v_pk_fma_f32 v[130:131], v[134:135], v[134:135], v[130:131]
	s_nop 0
	v_pk_add_f32 v[128:129], v[128:129], v[130:131]
	s_nop 0
	v_pk_add_f32 v[186:187], v[132:133], v[128:129]
	s_branch .LBB0_405

;     static __device__ __forceinline__ void run(const f32x4 (&acc)[2][2][4][2], const Unit& u, int wr, int wc, int fr, int fq, const float* xin, float* xout, const float* gate, float gs, const float* lazy_ssq, const float* lazy_g, ...
;     ...
;                 gv[n] = *(const f32x4*)(gate + (b * 9216u + col + 4 * n)) * gs;
;                 lg[n] = (f32x4){1.f, 1.f, 1.f, 1.f}; if (LAZY) lg[n] = *(const f32x4*)(lazy_g + col + 4 * n);
;                 wv[n] = (f32x4){0.f, 0.f, 0.f, 0.f}; w2[n] = (f32x4){1.f, 1.f, 1.f, 1.f};
;                 if (aout) { wv[n] = *(const f32x4*)(wg + col + 4 * n) * (*(const f32x4*)(wsc + (b * 9216u + col + 4 * n)) + 1.0f); if (WG2) { w2[n] = *(const f32x4*)(wg2 + col + 4 * n); wv[n] = wv[n] * w2[n]; } }
;             }
;             f32x4 xq[2][2][2];
;     ...
;             constexpr bool DEEP = !LAZY && !WG2;
;             if (DEEP) RES_LD(0, 0);
; #pragma unroll
;             for (int pp = 0; pp < 4; ++pp) {
;                 if (DEEP) { if (pp < 3) RES_LD((pp + 1) & 1, pp + 1); } else RES_LD(pp & 1, pp);
; #pragma unroll
;                 for (int j = 0; j < 2; ++j) { const int i_ = 2 * pp + j, ai = i_ >> 2, m = i_ & 3; const unsigned off = (row0 + ai * HALF + m * 16) * 1024u + col;
;                     const f32x4 xi0 = xq[pp & 1][j][0], xi1 = xq[pp & 1][j][1];
;                     f32x4 xo0 = gv[0] * acc[ai][bj][m][0], xo1 = gv[1] * acc[ai][bj][m][1];
;                     if (LAZY) { xo0 = xo0 + xi0 * lg[0] * rl[ai][m]; xo1 = xo1 + xi1 * lg[1] * rl[ai][m]; } else { xo0 = xo0 + xi0; xo1 = xo1 + xi1; }
;                     *(f32x4*)(xout + off) = xo0; *(f32x4*)(xout + off + 4) = xo1;
;                     if (aout) { const f32x4 a0 = xo0 * wv[0], a1 = xo1 * wv[1]; u32x4 w; w.x = cvt_pk_bf16(a0[0], a0[1]); w.y = cvt_pk_bf16(a0[2], a0[3]); w.z = cvt_pk_bf16(a1[0], a1[1]); w.w = cvt_pk_bf16(a1[2], a1[3]);
;                         *(u32x4*)(aout + off) = w;
;                         sq[ai][m] += ((xo0[0] * xo0[0] + xo0[1] * xo0[1]) + (xo0[2] * xo0[2] + xo0[3] * xo0[3])) + ((xo1[0] * xo1[0] + xo1[1] * xo1[1]) + (xo1[2] * xo1[2] + xo1[3] * xo1[3]));
;                         if (WG2) { const f32x4 b0 = xo0 * w2[0], b1 = xo1 * w2[1]; sqb[ai][m] += ((b0[0] * b0[0] + b0[1] * b0[1]) + (b0[2] * b0[2] + b0[3] * b0[3])) + ((b1[0] * b1[0] + b1[1] * b1[1]) + (b1[2] * b1[2] + b1[3] * b1[3])); } } }
.LBB0_409:
	v_add_u32_e32 v176, v208, v153
	v_lshlrev_b64 v[206:207], 2, v[176:177]
	v_lshl_add_u64 v[144:145], s[38:39], 0, v[206:207]
	v_mov_b32_e32 v205, v177
	v_add_u32_e32 v204, 0x4000, v176
	global_load_dwordx4 v[210:213], v[144:145], off
	global_load_dwordx4 v[232:235], v[144:145], off offset:16
	v_lshl_add_u64 v[148:149], v[204:205], 2, s[38:39]
	global_load_dwordx4 v[144:147], v[148:149], off offset:16
	s_nop 0
	global_load_dwordx4 v[148:151], v[148:149], off
	s_mov_b32 s41, s40
	s_mov_b32 s42, s40
	s_mov_b32 s43, s40
	s_waitcnt vmcnt(4)
	v_pk_mul_f32 v[190:191], s[42:43], v[142:143]
	v_pk_mul_f32 v[188:189], s[40:41], v[140:141]
	v_pk_mul_f32 v[200:201], s[42:43], v[138:139]
	v_pk_mul_f32 v[202:203], s[40:41], v[136:137]
	s_and_b64 vcc, exec, s[8:9]
	v_lshl_add_u64 v[206:207], s[36:37], 0, v[206:207]
	s_waitcnt vmcnt(3)
	v_pk_fma_f32 v[142:143], v[118:119], v[200:201], v[212:213]
	v_pk_fma_f32 v[140:141], v[116:117], v[202:203], v[210:211]
	s_waitcnt vmcnt(2)
	v_pk_fma_f32 v[138:139], v[114:115], v[190:191], v[234:235]
	v_pk_fma_f32 v[136:137], v[112:113], v[188:189], v[232:233]
	global_store_dwordx4 v[206:207], v[140:143], off sc1
	global_store_dwordx4 v[206:207], v[136:139], off offset:16 sc1
	s_cbranch_vccnz .LBB0_411
	v_pk_mul_f32 v[206:207], v[196:197], v[142:143]
	v_pk_mul_f32 v[210:211], v[194:195], v[140:141]
	v_pk_mul_f32 v[212:213], v[192:193], v[136:137]
	v_cvt_pk_bf16_f32 v210, v210, v211
	v_cvt_pk_bf16_f32 v211, v206, v207
	v_lshl_add_u64 v[206:207], v[176:177], 1, s[34:35]
	v_pk_mul_f32 v[214:215], v[198:199], v[138:139]
	v_cvt_pk_bf16_f32 v212, v212, v213
	v_mov_b32_e32 v232, v140
	v_cvt_pk_bf16_f32 v213, v214, v215
	global_store_dwordx4 v[206:207], v[210:213], off sc1
	v_pk_mul_f32 v[206:207], v[134:135], v[142:143]
	v_pk_mul_f32 v[214:215], v[128:129], v[136:137]
	v_pk_mul_f32 v[210:211], v[132:133], v[140:141]
	v_pk_mul_f32 v[212:213], v[130:131], v[138:139]
	v_mov_b32_e32 v233, v210
	v_mov_b32_e32 v210, v141
	v_pk_mul_f32 v[140:141], v[210:211], v[210:211]
	v_mov_b32_e32 v211, v206
	v_mov_b32_e32 v206, v143
	v_mov_b32_e32 v210, v142
	v_pk_mul_f32 v[142:143], v[206:207], v[206:207]
	v_pk_fma_f32 v[140:141], v[232:233], v[232:233], v[140:141]
	v_pk_fma_f32 v[142:143], v[210:211], v[210:211], v[142:143]
	s_nop 0
	v_pk_add_f32 v[140:141], v[140:141], v[142:143]
	v_mov_b32_e32 v143, v214
	v_mov_b32_e32 v214, v137
	v_mov_b32_e32 v142, v136
	v_pk_mul_f32 v[136:137], v[214:215], v[214:215]
	s_nop 0
	v_pk_fma_f32 v[136:137], v[142:143], v[142:143], v[136:137]
	v_mov_b32_e32 v143, v212
	v_mov_b32_e32 v212, v139
	v_mov_b32_e32 v142, v138
	v_pk_mul_f32 v[138:139], v[212:213], v[212:213]
	s_nop 0
	v_pk_fma_f32 v[138:139], v[142:143], v[142:143], v[138:139]
	s_nop 0
	v_pk_add_f32 v[136:137], v[136:137], v[138:139]
	s_nop 0
	v_pk_add_f32 v[136:137], v[140:141], v[136:137]
	s_nop 0
	v_pk_add_f32 v[154:155], v[154:155], v[136:137]
.LBB0_411:
	s_waitcnt vmcnt(2)
	v_pk_fma_f32 v[142:143], v[102:103], v[200:201], v[150:151]
	v_pk_fma_f32 v[140:141], v[100:101], v[202:203], v[148:149]
	v_pk_fma_f32 v[138:139], v[98:99], v[190:191], v[146:147]
	v_pk_fma_f32 v[136:137], v[96:97], v[188:189], v[144:145]
	v_lshl_add_u64 v[144:145], v[204:205], 2, s[36:37]
	s_and_b64 vcc, exec, s[8:9]
	global_store_dwordx4 v[144:145], v[140:143], off sc1
	global_store_dwordx4 v[144:145], v[136:139], off offset:16 sc1
	s_cbranch_vccnz .LBB0_413
	v_pk_mul_f32 v[146:147], v[196:197], v[142:143]
	v_pk_mul_f32 v[144:145], v[194:195], v[140:141]
	v_pk_mul_f32 v[148:149], v[198:199], v[138:139]
	v_pk_mul_f32 v[150:151], v[192:193], v[136:137]
	v_cvt_pk_bf16_f32 v144, v144, v145
	v_cvt_pk_bf16_f32 v145, v146, v147
	s_nop 0
	v_cvt_pk_bf16_f32 v146, v150, v151
	v_cvt_pk_bf16_f32 v147, v148, v149
	v_lshl_add_u64 v[148:149], v[204:205], 1, s[34:35]
	global_store_dwordx4 v[148:149], v[144:147], off sc1
	v_mov_b32_e32 v204, v140
	v_pk_mul_f32 v[150:151], v[128:129], v[136:137]
	v_pk_mul_f32 v[146:147], v[132:133], v[140:141]
	v_pk_mul_f32 v[144:145], v[134:135], v[142:143]
	v_mov_b32_e32 v205, v146
	v_mov_b32_e32 v146, v141
	v_pk_mul_f32 v[140:141], v[146:147], v[146:147]
	v_mov_b32_e32 v147, v144
	v_mov_b32_e32 v144, v143
	v_mov_b32_e32 v146, v142
	v_pk_mul_f32 v[142:143], v[144:145], v[144:145]
	v_pk_fma_f32 v[140:141], v[204:205], v[204:205], v[140:141]
	v_pk_fma_f32 v[142:143], v[146:147], v[146:147], v[142:143]
	v_pk_mul_f32 v[148:149], v[130:131], v[138:139]
	v_pk_add_f32 v[140:141], v[140:141], v[142:143]
	v_mov_b32_e32 v143, v150
	v_mov_b32_e32 v150, v137
	v_mov_b32_e32 v142, v136
	v_pk_mul_f32 v[136:137], v[150:151], v[150:151]
	s_nop 0
	v_pk_fma_f32 v[136:137], v[142:143], v[142:143], v[136:137]
	v_mov_b32_e32 v143, v148
	v_mov_b32_e32 v148, v139
	v_mov_b32_e32 v142, v138
	v_pk_mul_f32 v[138:139], v[148:149], v[148:149]
	s_nop 0
	v_pk_fma_f32 v[138:139], v[142:143], v[142:143], v[138:139]
	s_nop 0
	v_pk_add_f32 v[136:137], v[136:137], v[138:139]
	s_nop 0
	v_pk_add_f32 v[136:137], v[140:141], v[136:137]
	s_nop 0
	v_pk_add_f32 v[156:157], v[156:157], v[136:137]
;     static __device__ __forceinline__ void run(const f32x4 (&acc)[2][2][4][2], const Unit& u, int wr, int wc, int fr, int fq, const float* xin, float* xout, const float* gate, float gs, const float* lazy_ssq, const float* lazy_g, ...
;     ...
;                 gv[n] = *(const f32x4*)(gate + (b * 9216u + col + 4 * n)) * gs;
;                 lg[n] = (f32x4){1.f, 1.f, 1.f, 1.f}; if (LAZY) lg[n] = *(const f32x4*)(lazy_g + col + 4 * n);
;                 wv[n] = (f32x4){0.f, 0.f, 0.f, 0.f}; w2[n] = (f32x4){1.f, 1.f, 1.f, 1.f};
;                 if (aout) { wv[n] = *(const f32x4*)(wg + col + 4 * n) * (*(const f32x4*)(wsc + (b * 9216u + col + 4 * n)) + 1.0f); if (WG2) { w2[n] = *(const f32x4*)(wg2 + col + 4 * n); wv[n] = wv[n] * w2[n]; } }
;             }
;             f32x4 xq[2][2][2];
;     ...
;             constexpr bool DEEP = !LAZY && !WG2;
;             if (DEEP) RES_LD(0, 0);
; #pragma unroll
;             for (int pp = 0; pp < 4; ++pp) {
;                 if (DEEP) { if (pp < 3) RES_LD((pp + 1) & 1, pp + 1); } else RES_LD(pp & 1, pp);
; #pragma unroll
;                 for (int j = 0; j < 2; ++j) { const int i_ = 2 * pp + j, ai = i_ >> 2, m = i_ & 3; const unsigned off = (row0 + ai * HALF + m * 16) * 1024u + col;
;                     const f32x4 xi0 = xq[pp & 1][j][0], xi1 = xq[pp & 1][j][1];
;                     f32x4 xo0 = gv[0] * acc[ai][bj][m][0], xo1 = gv[1] * acc[ai][bj][m][1];
;                     if (LAZY) { xo0 = xo0 + xi0 * lg[0] * rl[ai][m]; xo1 = xo1 + xi1 * lg[1] * rl[ai][m]; } else { xo0 = xo0 + xi0; xo1 = xo1 + xi1; }
;                     *(f32x4*)(xout + off) = xo0; *(f32x4*)(xout + off + 4) = xo1;
;                     if (aout) { const f32x4 a0 = xo0 * wv[0], a1 = xo1 * wv[1]; u32x4 w; w.x = cvt_pk_bf16(a0[0], a0[1]); w.y = cvt_pk_bf16(a0[2], a0[3]); w.z = cvt_pk_bf16(a1[0], a1[1]); w.w = cvt_pk_bf16(a1[2], a1[3]);
;                         *(u32x4*)(aout + off) = w;
;                         sq[ai][m] += ((xo0[0] * xo0[0] + xo0[1] * xo0[1]) + (xo0[2] * xo0[2] + xo0[3] * xo0[3])) + ((xo1[0] * xo1[0] + xo1[1] * xo1[1]) + (xo1[2] * xo1[2] + xo1[3] * xo1[3]));
;                         if (WG2) { const f32x4 b0 = xo0 * w2[0], b1 = xo1 * w2[1]; sqb[ai][m] += ((b0[0] * b0[0] + b0[1] * b0[1]) + (b0[2] * b0[2] + b0[3] * b0[3])) + ((b1[0] * b1[0] + b1[1] * b1[1]) + (b1[2] * b1[2] + b1[3] * b1[3])); } } }
.LBB0_413:
	v_add_u32_e32 v206, 0x8000, v176
	v_mov_b32_e32 v207, v177
	v_lshlrev_b64 v[148:149], 2, v[206:207]
	v_lshl_add_u64 v[136:137], s[38:39], 0, v[148:149]
	v_add_u32_e32 v204, 0xc000, v176
	v_mov_b32_e32 v205, v177
	global_load_dwordx4 v[144:147], v[136:137], off
	global_load_dwordx4 v[210:213], v[136:137], off offset:16
	v_lshl_add_u64 v[140:141], v[204:205], 2, s[38:39]
	global_load_dwordx4 v[136:139], v[140:141], off offset:16
	s_nop 0
	global_load_dwordx4 v[140:143], v[140:141], off
	s_and_b64 vcc, exec, s[8:9]
	v_lshl_add_u64 v[214:215], s[36:37], 0, v[148:149]
	s_waitcnt vmcnt(3)
	v_pk_fma_f32 v[150:151], v[86:87], v[200:201], v[146:147]
	v_pk_fma_f32 v[148:149], v[84:85], v[202:203], v[144:145]
	s_waitcnt vmcnt(2)
	v_pk_fma_f32 v[146:147], v[82:83], v[190:191], v[212:213]
	v_pk_fma_f32 v[144:145], v[80:81], v[188:189], v[210:211]
	global_store_dwordx4 v[214:215], v[148:151], off sc1
	global_store_dwordx4 v[214:215], v[144:147], off offset:16 sc1
	s_cbranch_vccnz .LBB0_415
	v_pk_mul_f32 v[210:211], v[194:195], v[148:149]
	v_pk_mul_f32 v[212:213], v[196:197], v[150:151]
	v_cvt_pk_bf16_f32 v210, v210, v211
	v_lshl_add_u64 v[206:207], v[206:207], 1, s[34:35]
	v_cvt_pk_bf16_f32 v211, v212, v213
	v_pk_mul_f32 v[214:215], v[198:199], v[146:147]
	v_pk_mul_f32 v[232:233], v[192:193], v[144:145]
	s_nop 0
	v_cvt_pk_bf16_f32 v212, v232, v233
	v_cvt_pk_bf16_f32 v213, v214, v215
	global_store_dwordx4 v[206:207], v[210:213], off sc1
	v_pk_mul_f32 v[206:207], v[134:135], v[150:151]
	v_mov_b32_e32 v232, v148
	v_pk_mul_f32 v[210:211], v[132:133], v[148:149]
	v_pk_mul_f32 v[214:215], v[128:129], v[144:145]
	v_mov_b32_e32 v233, v210
	v_mov_b32_e32 v210, v149
	v_pk_mul_f32 v[148:149], v[210:211], v[210:211]
	v_mov_b32_e32 v211, v206
	v_mov_b32_e32 v206, v151
	v_mov_b32_e32 v210, v150
	v_pk_mul_f32 v[150:151], v[206:207], v[206:207]
	v_pk_fma_f32 v[148:149], v[232:233], v[232:233], v[148:149]
	v_pk_fma_f32 v[150:151], v[210:211], v[210:211], v[150:151]
	v_pk_mul_f32 v[212:213], v[130:131], v[146:147]
	v_pk_add_f32 v[148:149], v[148:149], v[150:151]
	v_mov_b32_e32 v151, v214
	v_mov_b32_e32 v214, v145
	v_mov_b32_e32 v150, v144
	v_pk_mul_f32 v[144:145], v[214:215], v[214:215]
	s_nop 0
	v_pk_fma_f32 v[144:145], v[150:151], v[150:151], v[144:145]
	v_mov_b32_e32 v151, v212
	v_mov_b32_e32 v212, v147
	v_mov_b32_e32 v150, v146
	v_pk_mul_f32 v[146:147], v[212:213], v[212:213]
	s_nop 0
	v_pk_fma_f32 v[146:147], v[150:151], v[150:151], v[146:147]
	s_nop 0
	v_pk_add_f32 v[144:145], v[144:145], v[146:147]
	s_nop 0
	v_pk_add_f32 v[144:145], v[148:149], v[144:145]
	s_nop 0
	v_pk_add_f32 v[158:159], v[158:159], v[144:145]
.LBB0_415:
	s_waitcnt vmcnt(2)
	v_pk_fma_f32 v[142:143], v[70:71], v[200:201], v[142:143]
	v_pk_fma_f32 v[140:141], v[68:69], v[202:203], v[140:141]
	v_pk_fma_f32 v[138:139], v[66:67], v[190:191], v[138:139]
	v_pk_fma_f32 v[136:137], v[64:65], v[188:189], v[136:137]
	v_lshl_add_u64 v[144:145], v[204:205], 2, s[36:37]
	s_and_b64 vcc, exec, s[8:9]
	global_store_dwordx4 v[144:145], v[140:143], off sc1
	global_store_dwordx4 v[144:145], v[136:139], off offset:16 sc1
	s_cbranch_vccnz .LBB0_417
	v_pk_mul_f32 v[146:147], v[196:197], v[142:143]
	v_pk_mul_f32 v[144:145], v[194:195], v[140:141]
	v_pk_mul_f32 v[148:149], v[198:199], v[138:139]
	v_pk_mul_f32 v[150:151], v[192:193], v[136:137]
	v_cvt_pk_bf16_f32 v144, v144, v145
	v_cvt_pk_bf16_f32 v145, v146, v147
	s_nop 0
	v_cvt_pk_bf16_f32 v146, v150, v151
	v_cvt_pk_bf16_f32 v147, v148, v149
	v_lshl_add_u64 v[148:149], v[204:205], 1, s[34:35]
	global_store_dwordx4 v[148:149], v[144:147], off sc1
	v_mov_b32_e32 v204, v140
	v_pk_mul_f32 v[150:151], v[128:129], v[136:137]
	v_pk_mul_f32 v[146:147], v[132:133], v[140:141]
	v_pk_mul_f32 v[144:145], v[134:135], v[142:143]
	v_mov_b32_e32 v205, v146
	v_mov_b32_e32 v146, v141
	v_pk_mul_f32 v[140:141], v[146:147], v[146:147]
	v_mov_b32_e32 v147, v144
	v_mov_b32_e32 v144, v143
	v_mov_b32_e32 v146, v142
	v_pk_mul_f32 v[142:143], v[144:145], v[144:145]
	v_pk_fma_f32 v[140:141], v[204:205], v[204:205], v[140:141]
	v_pk_fma_f32 v[142:143], v[146:147], v[146:147], v[142:143]
	v_pk_mul_f32 v[148:149], v[130:131], v[138:139]
	v_pk_add_f32 v[140:141], v[140:141], v[142:143]
	v_mov_b32_e32 v143, v150
	v_mov_b32_e32 v150, v137
	v_mov_b32_e32 v142, v136
	v_pk_mul_f32 v[136:137], v[150:151], v[150:151]
	s_nop 0
	v_pk_fma_f32 v[136:137], v[142:143], v[142:143], v[136:137]
	v_mov_b32_e32 v143, v148
	v_mov_b32_e32 v148, v139
	v_mov_b32_e32 v142, v138
	v_pk_mul_f32 v[138:139], v[148:149], v[148:149]
	s_nop 0
	v_pk_fma_f32 v[138:139], v[142:143], v[142:143], v[138:139]
	s_nop 0
	v_pk_add_f32 v[136:137], v[136:137], v[138:139]
	s_nop 0
	v_pk_add_f32 v[136:137], v[140:141], v[136:137]
	s_nop 0
	v_pk_add_f32 v[174:175], v[174:175], v[136:137]
;     static __device__ __forceinline__ void run(const f32x4 (&acc)[2][2][4][2], const Unit& u, int wr, int wc, int fr, int fq, const float* xin, float* xout, const float* gate, float gs, const float* lazy_ssq, const float* lazy_g, ...
;     ...
;                 gv[n] = *(const f32x4*)(gate + (b * 9216u + col + 4 * n)) * gs;
;                 lg[n] = (f32x4){1.f, 1.f, 1.f, 1.f}; if (LAZY) lg[n] = *(const f32x4*)(lazy_g + col + 4 * n);
;                 wv[n] = (f32x4){0.f, 0.f, 0.f, 0.f}; w2[n] = (f32x4){1.f, 1.f, 1.f, 1.f};
;                 if (aout) { wv[n] = *(const f32x4*)(wg + col + 4 * n) * (*(const f32x4*)(wsc + (b * 9216u + col + 4 * n)) + 1.0f); if (WG2) { w2[n] = *(const f32x4*)(wg2 + col + 4 * n); wv[n] = wv[n] * w2[n]; } }
;             }
;             f32x4 xq[2][2][2];
;     ...
;             constexpr bool DEEP = !LAZY && !WG2;
;             if (DEEP) RES_LD(0, 0);
; #pragma unroll
;             for (int pp = 0; pp < 4; ++pp) {
;                 if (DEEP) { if (pp < 3) RES_LD((pp + 1) & 1, pp + 1); } else RES_LD(pp & 1, pp);
; #pragma unroll
;                 for (int j = 0; j < 2; ++j) { const int i_ = 2 * pp + j, ai = i_ >> 2, m = i_ & 3; const unsigned off = (row0 + ai * HALF + m * 16) * 1024u + col;
;                     const f32x4 xi0 = xq[pp & 1][j][0], xi1 = xq[pp & 1][j][1];
;                     f32x4 xo0 = gv[0] * acc[ai][bj][m][0], xo1 = gv[1] * acc[ai][bj][m][1];
;                     if (LAZY) { xo0 = xo0 + xi0 * lg[0] * rl[ai][m]; xo1 = xo1 + xi1 * lg[1] * rl[ai][m]; } else { xo0 = xo0 + xi0; xo1 = xo1 + xi1; }
;                     *(f32x4*)(xout + off) = xo0; *(f32x4*)(xout + off + 4) = xo1;
;                     if (aout) { const f32x4 a0 = xo0 * wv[0], a1 = xo1 * wv[1]; u32x4 w; w.x = cvt_pk_bf16(a0[0], a0[1]); w.y = cvt_pk_bf16(a0[2], a0[3]); w.z = cvt_pk_bf16(a1[0], a1[1]); w.w = cvt_pk_bf16(a1[2], a1[3]);
;                         *(u32x4*)(aout + off) = w;
;                         sq[ai][m] += ((xo0[0] * xo0[0] + xo0[1] * xo0[1]) + (xo0[2] * xo0[2] + xo0[3] * xo0[3])) + ((xo1[0] * xo1[0] + xo1[1] * xo1[1]) + (xo1[2] * xo1[2] + xo1[3] * xo1[3]));
;                         if (WG2) { const f32x4 b0 = xo0 * w2[0], b1 = xo1 * w2[1]; sqb[ai][m] += ((b0[0] * b0[0] + b0[1] * b0[1]) + (b0[2] * b0[2] + b0[3] * b0[3])) + ((b1[0] * b1[0] + b1[1] * b1[1]) + (b1[2] * b1[2] + b1[3] * b1[3])); } } }
.LBB0_417:
	v_add_u32_e32 v204, v173, v208
	v_mov_b32_e32 v205, v177
	v_lshl_add_u64 v[136:137], v[204:205], 2, s[38:39]
	global_load_dwordx4 v[144:147], v[136:137], off offset:16
	global_load_dwordx4 v[148:151], v[136:137], off
	v_add_u32_e32 v136, 0x4000, v204
	v_mov_b32_e32 v137, v177
	v_lshl_add_u64 v[140:141], v[136:137], 2, s[38:39]
	global_load_dwordx4 v[136:139], v[140:141], off offset:16
	s_nop 0
	global_load_dwordx4 v[140:143], v[140:141], off
	v_add_u32_e32 v206, 0x20000, v176
	v_mov_b32_e32 v207, v177
	v_lshl_add_u64 v[208:209], v[206:207], 2, s[36:37]
	s_and_b64 vcc, exec, s[8:9]
	s_waitcnt vmcnt(3)
	v_pk_fma_f32 v[146:147], v[50:51], v[190:191], v[146:147]
	s_waitcnt vmcnt(2)
	v_pk_fma_f32 v[150:151], v[54:55], v[200:201], v[150:151]
	v_pk_fma_f32 v[148:149], v[52:53], v[202:203], v[148:149]
	v_pk_fma_f32 v[144:145], v[48:49], v[188:189], v[144:145]
	global_store_dwordx4 v[208:209], v[148:151], off sc1
	global_store_dwordx4 v[208:209], v[144:147], off offset:16 sc1
	s_cbranch_vccnz .LBB0_419
	v_pk_mul_f32 v[208:209], v[194:195], v[148:149]
	v_pk_mul_f32 v[210:211], v[196:197], v[150:151]
	v_cvt_pk_bf16_f32 v208, v208, v209
	v_lshl_add_u64 v[206:207], v[206:207], 1, s[34:35]
	v_cvt_pk_bf16_f32 v209, v210, v211
	v_pk_mul_f32 v[212:213], v[198:199], v[146:147]
	v_pk_mul_f32 v[214:215], v[192:193], v[144:145]
	s_nop 0
	v_cvt_pk_bf16_f32 v210, v214, v215
	v_cvt_pk_bf16_f32 v211, v212, v213
	global_store_dwordx4 v[206:207], v[208:211], off sc1
	v_pk_mul_f32 v[206:207], v[134:135], v[150:151]
	v_mov_b32_e32 v214, v148
	v_pk_mul_f32 v[208:209], v[132:133], v[148:149]
	v_pk_mul_f32 v[212:213], v[128:129], v[144:145]
	v_mov_b32_e32 v215, v208
	v_mov_b32_e32 v208, v149
	v_pk_mul_f32 v[148:149], v[208:209], v[208:209]
	v_mov_b32_e32 v209, v206
	v_mov_b32_e32 v206, v151
	v_mov_b32_e32 v208, v150
	v_pk_mul_f32 v[150:151], v[206:207], v[206:207]
	v_pk_fma_f32 v[148:149], v[214:215], v[214:215], v[148:149]
	v_pk_fma_f32 v[150:151], v[208:209], v[208:209], v[150:151]
	v_pk_mul_f32 v[210:211], v[130:131], v[146:147]
	v_pk_add_f32 v[148:149], v[148:149], v[150:151]
	v_mov_b32_e32 v151, v212
	v_mov_b32_e32 v212, v145
	v_mov_b32_e32 v150, v144
	v_pk_mul_f32 v[144:145], v[212:213], v[212:213]
	s_nop 0
	v_pk_fma_f32 v[144:145], v[150:151], v[150:151], v[144:145]
	v_mov_b32_e32 v151, v210
	v_mov_b32_e32 v210, v147
	v_mov_b32_e32 v150, v146
	v_pk_mul_f32 v[146:147], v[210:211], v[210:211]
	s_nop 0
	v_pk_fma_f32 v[146:147], v[150:151], v[150:151], v[146:147]
	s_nop 0
	v_pk_add_f32 v[144:145], v[144:145], v[146:147]
	s_nop 0
	v_pk_add_f32 v[144:145], v[148:149], v[144:145]
	s_nop 0
	v_pk_add_f32 v[180:181], v[180:181], v[144:145]
.LBB0_419:
	s_nop 0
	v_add_u32_e32 v144, 0x24000, v176
	v_mov_b32_e32 v145, v177
	s_waitcnt vmcnt(2)
	v_pk_fma_f32 v[142:143], v[38:39], v[200:201], v[142:143]
	v_pk_fma_f32 v[140:141], v[36:37], v[202:203], v[140:141]
	v_pk_fma_f32 v[138:139], v[34:35], v[190:191], v[138:139]
	v_pk_fma_f32 v[136:137], v[32:33], v[188:189], v[136:137]
	v_lshl_add_u64 v[146:147], v[144:145], 2, s[36:37]
	s_and_b64 vcc, exec, s[8:9]
	global_store_dwordx4 v[146:147], v[140:143], off sc1
	global_store_dwordx4 v[146:147], v[136:139], off offset:16 sc1
	s_cbranch_vccnz .LBB0_421
	v_pk_mul_f32 v[146:147], v[194:195], v[140:141]
	v_pk_mul_f32 v[148:149], v[196:197], v[142:143]
	v_cvt_pk_bf16_f32 v146, v146, v147
	v_lshl_add_u64 v[144:145], v[144:145], 1, s[34:35]
	v_cvt_pk_bf16_f32 v147, v148, v149
	v_pk_mul_f32 v[150:151], v[198:199], v[138:139]
	v_pk_mul_f32 v[206:207], v[192:193], v[136:137]
	s_nop 0
	v_cvt_pk_bf16_f32 v148, v206, v207
	v_cvt_pk_bf16_f32 v149, v150, v151
	global_store_dwordx4 v[144:145], v[146:149], off sc1
	v_pk_mul_f32 v[144:145], v[134:135], v[142:143]
	v_mov_b32_e32 v206, v140
	v_pk_mul_f32 v[146:147], v[132:133], v[140:141]
	v_pk_mul_f32 v[150:151], v[128:129], v[136:137]
	v_mov_b32_e32 v207, v146
	v_mov_b32_e32 v146, v141
	v_pk_mul_f32 v[140:141], v[146:147], v[146:147]
	v_mov_b32_e32 v147, v144
	v_mov_b32_e32 v144, v143
	v_mov_b32_e32 v146, v142
	v_pk_mul_f32 v[142:143], v[144:145], v[144:145]
	v_pk_fma_f32 v[140:141], v[206:207], v[206:207], v[140:141]
	v_pk_fma_f32 v[142:143], v[146:147], v[146:147], v[142:143]
	v_pk_mul_f32 v[148:149], v[130:131], v[138:139]
	v_pk_add_f32 v[140:141], v[140:141], v[142:143]
	v_mov_b32_e32 v143, v150
	v_mov_b32_e32 v150, v137
	v_mov_b32_e32 v142, v136
	v_pk_mul_f32 v[136:137], v[150:151], v[150:151]
	s_nop 0
	v_pk_fma_f32 v[136:137], v[142:143], v[142:143], v[136:137]
	v_mov_b32_e32 v143, v148
	v_mov_b32_e32 v148, v139
	v_mov_b32_e32 v142, v138
	v_pk_mul_f32 v[138:139], v[148:149], v[148:149]
	s_nop 0
	v_pk_fma_f32 v[138:139], v[142:143], v[142:143], v[138:139]
	s_nop 0
	v_pk_add_f32 v[136:137], v[136:137], v[138:139]
	s_nop 0
	v_pk_add_f32 v[136:137], v[140:141], v[136:137]
	s_nop 0
	v_pk_add_f32 v[182:183], v[182:183], v[136:137]
;     static __device__ __forceinline__ void run(const f32x4 (&acc)[2][2][4][2], const Unit& u, int wr, int wc, int fr, int fq, const float* xin, float* xout, const float* gate, float gs, const float* lazy_ssq, const float* lazy_g, ...
;     ...
;                 gv[n] = *(const f32x4*)(gate + (b * 9216u + col + 4 * n)) * gs;
;                 lg[n] = (f32x4){1.f, 1.f, 1.f, 1.f}; if (LAZY) lg[n] = *(const f32x4*)(lazy_g + col + 4 * n);
;                 wv[n] = (f32x4){0.f, 0.f, 0.f, 0.f}; w2[n] = (f32x4){1.f, 1.f, 1.f, 1.f};
;                 if (aout) { wv[n] = *(const f32x4*)(wg + col + 4 * n) * (*(const f32x4*)(wsc + (b * 9216u + col + 4 * n)) + 1.0f); if (WG2) { w2[n] = *(const f32x4*)(wg2 + col + 4 * n); wv[n] = wv[n] * w2[n]; } }
;             }
;             f32x4 xq[2][2][2];
;     ...
;             constexpr bool DEEP = !LAZY && !WG2;
;             if (DEEP) RES_LD(0, 0);
; #pragma unroll
;             for (int pp = 0; pp < 4; ++pp) {
;                 if (DEEP) { if (pp < 3) RES_LD((pp + 1) & 1, pp + 1); } else RES_LD(pp & 1, pp);
; #pragma unroll
;                 for (int j = 0; j < 2; ++j) { const int i_ = 2 * pp + j, ai = i_ >> 2, m = i_ & 3; const unsigned off = (row0 + ai * HALF + m * 16) * 1024u + col;
;                     const f32x4 xi0 = xq[pp & 1][j][0], xi1 = xq[pp & 1][j][1];
;                     f32x4 xo0 = gv[0] * acc[ai][bj][m][0], xo1 = gv[1] * acc[ai][bj][m][1];
;                     if (LAZY) { xo0 = xo0 + xi0 * lg[0] * rl[ai][m]; xo1 = xo1 + xi1 * lg[1] * rl[ai][m]; } else { xo0 = xo0 + xi0; xo1 = xo1 + xi1; }
;                     *(f32x4*)(xout + off) = xo0; *(f32x4*)(xout + off + 4) = xo1;
;                     if (aout) { const f32x4 a0 = xo0 * wv[0], a1 = xo1 * wv[1]; u32x4 w; w.x = cvt_pk_bf16(a0[0], a0[1]); w.y = cvt_pk_bf16(a0[2], a0[3]); w.z = cvt_pk_bf16(a1[0], a1[1]); w.w = cvt_pk_bf16(a1[2], a1[3]);
;                         *(u32x4*)(aout + off) = w;
;                         sq[ai][m] += ((xo0[0] * xo0[0] + xo0[1] * xo0[1]) + (xo0[2] * xo0[2] + xo0[3] * xo0[3])) + ((xo1[0] * xo1[0] + xo1[1] * xo1[1]) + (xo1[2] * xo1[2] + xo1[3] * xo1[3]));
;                         if (WG2) { const f32x4 b0 = xo0 * w2[0], b1 = xo1 * w2[1]; sqb[ai][m] += ((b0[0] * b0[0] + b0[1] * b0[1]) + (b0[2] * b0[2] + b0[3] * b0[3])) + ((b1[0] * b1[0] + b1[1] * b1[1]) + (b1[2] * b1[2] + b1[3] * b1[3])); } } }
.LBB0_421:
	s_nop 0
	v_add_u32_e32 v136, 0x8000, v204
	v_mov_b32_e32 v137, v177
	v_lshl_add_u64 v[136:137], v[136:137], 2, s[38:39]
	global_load_dwordx4 v[144:147], v[136:137], off offset:16
	global_load_dwordx4 v[148:151], v[136:137], off
	v_add_u32_e32 v136, 0xc000, v204
	v_mov_b32_e32 v137, v177
	v_lshl_add_u64 v[140:141], v[136:137], 2, s[38:39]
	global_load_dwordx4 v[136:139], v[140:141], off offset:16
	s_nop 0
	global_load_dwordx4 v[140:143], v[140:141], off
	v_add_u32_e32 v204, 0x28000, v176
	v_mov_b32_e32 v205, v177
	v_lshl_add_u64 v[206:207], v[204:205], 2, s[36:37]
	s_and_b64 vcc, exec, s[8:9]
	s_waitcnt vmcnt(3)
	v_pk_fma_f32 v[146:147], v[18:19], v[190:191], v[146:147]
	s_waitcnt vmcnt(2)
	v_pk_fma_f32 v[150:151], v[22:23], v[200:201], v[150:151]
	v_pk_fma_f32 v[148:149], v[20:21], v[202:203], v[148:149]
	v_pk_fma_f32 v[144:145], v[16:17], v[188:189], v[144:145]
	global_store_dwordx4 v[206:207], v[148:151], off sc1
	global_store_dwordx4 v[206:207], v[144:147], off offset:16 sc1
	s_cbranch_vccnz .LBB0_423
	v_pk_mul_f32 v[206:207], v[194:195], v[148:149]
	v_pk_mul_f32 v[208:209], v[196:197], v[150:151]
	v_cvt_pk_bf16_f32 v206, v206, v207
	v_lshl_add_u64 v[204:205], v[204:205], 1, s[34:35]
	v_cvt_pk_bf16_f32 v207, v208, v209
	v_pk_mul_f32 v[210:211], v[198:199], v[146:147]
	v_pk_mul_f32 v[212:213], v[192:193], v[144:145]
	s_nop 0
	v_cvt_pk_bf16_f32 v208, v212, v213
	v_cvt_pk_bf16_f32 v209, v210, v211
	global_store_dwordx4 v[204:205], v[206:209], off sc1
	v_pk_mul_f32 v[204:205], v[134:135], v[150:151]
	v_mov_b32_e32 v212, v148
	v_pk_mul_f32 v[206:207], v[132:133], v[148:149]
	v_pk_mul_f32 v[210:211], v[128:129], v[144:145]
	v_mov_b32_e32 v213, v206
	v_mov_b32_e32 v206, v149
	v_pk_mul_f32 v[148:149], v[206:207], v[206:207]
	v_mov_b32_e32 v207, v204
	v_mov_b32_e32 v204, v151
	v_mov_b32_e32 v206, v150
	v_pk_mul_f32 v[150:151], v[204:205], v[204:205]
	v_pk_fma_f32 v[148:149], v[212:213], v[212:213], v[148:149]
	v_pk_fma_f32 v[150:151], v[206:207], v[206:207], v[150:151]
	v_pk_mul_f32 v[208:209], v[130:131], v[146:147]
	v_pk_add_f32 v[148:149], v[148:149], v[150:151]
	v_mov_b32_e32 v151, v210
	v_mov_b32_e32 v210, v145
	v_mov_b32_e32 v150, v144
	v_pk_mul_f32 v[144:145], v[210:211], v[210:211]
	s_nop 0
	v_pk_fma_f32 v[144:145], v[150:151], v[150:151], v[144:145]
	v_mov_b32_e32 v151, v208
	v_mov_b32_e32 v208, v147
	v_mov_b32_e32 v150, v146
	v_pk_mul_f32 v[146:147], v[208:209], v[208:209]
	s_nop 0
	v_pk_fma_f32 v[146:147], v[150:151], v[150:151], v[146:147]
	s_nop 0
	v_pk_add_f32 v[144:145], v[144:145], v[146:147]
	s_nop 0
	v_pk_add_f32 v[144:145], v[148:149], v[144:145]
	s_nop 0
	v_pk_add_f32 v[184:185], v[184:185], v[144:145]
.LBB0_423:
	v_add_u32_e32 v176, 0x2c000, v176
	s_waitcnt vmcnt(2)
	v_pk_fma_f32 v[142:143], v[6:7], v[200:201], v[142:143]
	v_pk_fma_f32 v[140:141], v[4:5], v[202:203], v[140:141]
	v_pk_fma_f32 v[138:139], v[2:3], v[190:191], v[138:139]
	v_pk_fma_f32 v[136:137], v[0:1], v[188:189], v[136:137]
	v_lshl_add_u64 v[144:145], v[176:177], 2, s[36:37]
	s_and_b64 vcc, exec, s[8:9]
	global_store_dwordx4 v[144:145], v[140:143], off sc1
	global_store_dwordx4 v[144:145], v[136:139], off offset:16 sc1
	s_cbranch_vccnz .LBB0_425
	v_pk_mul_f32 v[146:147], v[196:197], v[142:143]
	v_pk_mul_f32 v[144:145], v[194:195], v[140:141]
	v_pk_mul_f32 v[148:149], v[198:199], v[138:139]
	v_pk_mul_f32 v[150:151], v[192:193], v[136:137]
	v_cvt_pk_bf16_f32 v144, v144, v145
	v_cvt_pk_bf16_f32 v145, v146, v147
	v_pk_mul_f32 v[134:135], v[134:135], v[142:143]
	v_cvt_pk_bf16_f32 v146, v150, v151
	v_cvt_pk_bf16_f32 v147, v148, v149
	v_lshl_add_u64 v[148:149], v[176:177], 1, s[34:35]
	v_pk_mul_f32 v[132:133], v[132:133], v[140:141]
	global_store_dwordx4 v[148:149], v[144:147], off sc1
	v_pk_mul_f32 v[128:129], v[128:129], v[136:137]
	v_pk_mul_f32 v[130:131], v[130:131], v[138:139]
	v_mov_b32_e32 v145, v132
	v_mov_b32_e32 v132, v141
	v_mov_b32_e32 v141, v134
	v_mov_b32_e32 v134, v143
	v_mov_b32_e32 v144, v140
	v_pk_mul_f32 v[132:133], v[132:133], v[132:133]
	v_mov_b32_e32 v140, v142
	v_pk_mul_f32 v[134:135], v[134:135], v[134:135]
	v_pk_fma_f32 v[132:133], v[144:145], v[144:145], v[132:133]
	v_pk_fma_f32 v[134:135], v[140:141], v[140:141], v[134:135]
	s_nop 0
	v_pk_add_f32 v[132:133], v[132:133], v[134:135]
	v_mov_b32_e32 v135, v128
	v_mov_b32_e32 v128, v137
	v_mov_b32_e32 v134, v136
	v_pk_mul_f32 v[128:129], v[128:129], v[128:129]
	s_nop 0
	v_pk_fma_f32 v[128:129], v[134:135], v[134:135], v[128:129]
	v_mov_b32_e32 v135, v130
	v_mov_b32_e32 v130, v139
	v_mov_b32_e32 v134, v138
	v_pk_mul_f32 v[130:131], v[130:131], v[130:131]
	s_nop 0
	v_pk_fma_f32 v[130:131], v[134:135], v[134:135], v[130:131]
	s_nop 0
	v_pk_add_f32 v[128:129], v[128:129], v[130:131]
	s_nop 0
	v_pk_add_f32 v[128:129], v[132:133], v[128:129]
	s_nop 0
	v_pk_add_f32 v[186:187], v[186:187], v[128:129]

;     static __device__ __forceinline__ void run(const f32x4 (&acc)[2][2][4][2], const Unit& u, int wr, int wc, int fr, int fq, const float* xin, float* xout, const float* gate, float gs, const float* lazy_ssq, const float* lazy_g, ...
;     ...
;                 gv[n] = *(const f32x4*)(gate + (b * 9216u + col + 4 * n)) * gs;
;                 lg[n] = (f32x4){1.f, 1.f, 1.f, 1.f}; if (LAZY) lg[n] = *(const f32x4*)(lazy_g + col + 4 * n);
;                 wv[n] = (f32x4){0.f, 0.f, 0.f, 0.f}; w2[n] = (f32x4){1.f, 1.f, 1.f, 1.f};
;                 if (aout) { wv[n] = *(const f32x4*)(wg + col + 4 * n) * (*(const f32x4*)(wsc + (b * 9216u + col + 4 * n)) + 1.0f); if (WG2) { w2[n] = *(const f32x4*)(wg2 + col + 4 * n); wv[n] = wv[n] * w2[n]; } }
;             }
;             f32x4 xq[2][2][2];
;     ...
;             constexpr bool DEEP = !LAZY && !WG2;
;             if (DEEP) RES_LD(0, 0);
; #pragma unroll
;             for (int pp = 0; pp < 4; ++pp) {
;                 if (DEEP) { if (pp < 3) RES_LD((pp + 1) & 1, pp + 1); } else RES_LD(pp & 1, pp);
; #pragma unroll
;                 for (int j = 0; j < 2; ++j) { const int i_ = 2 * pp + j, ai = i_ >> 2, m = i_ & 3; const unsigned off = (row0 + ai * HALF + m * 16) * 1024u + col;
;                     const f32x4 xi0 = xq[pp & 1][j][0], xi1 = xq[pp & 1][j][1];
;                     f32x4 xo0 = gv[0] * acc[ai][bj][m][0], xo1 = gv[1] * acc[ai][bj][m][1];
;                     if (LAZY) { xo0 = xo0 + xi0 * lg[0] * rl[ai][m]; xo1 = xo1 + xi1 * lg[1] * rl[ai][m]; } else { xo0 = xo0 + xi0; xo1 = xo1 + xi1; }
;                     *(f32x4*)(xout + off) = xo0; *(f32x4*)(xout + off + 4) = xo1;
;                     if (aout) { const f32x4 a0 = xo0 * wv[0], a1 = xo1 * wv[1]; u32x4 w; w.x = cvt_pk_bf16(a0[0], a0[1]); w.y = cvt_pk_bf16(a0[2], a0[3]); w.z = cvt_pk_bf16(a1[0], a1[1]); w.w = cvt_pk_bf16(a1[2], a1[3]);
;                         *(u32x4*)(aout + off) = w;
;                         sq[ai][m] += ((xo0[0] * xo0[0] + xo0[1] * xo0[1]) + (xo0[2] * xo0[2] + xo0[3] * xo0[3])) + ((xo1[0] * xo1[0] + xo1[1] * xo1[1]) + (xo1[2] * xo1[2] + xo1[3] * xo1[3]));
;                         if (WG2) { const f32x4 b0 = xo0 * w2[0], b1 = xo1 * w2[1]; sqb[ai][m] += ((b0[0] * b0[0] + b0[1] * b0[1]) + (b0[2] * b0[2] + b0[3] * b0[3])) + ((b1[0] * b1[0] + b1[1] * b1[1]) + (b1[2] * b1[2] + b1[3] * b1[3])); } } }
.LBB0_487:
	s_lshl_b32 s42, s63, 8
	s_lshl_b32 s43, s65, 6
	s_add_i32 s43, s43, s42
	v_or_b32_e32 v172, s43, v230
	v_lshlrev_b32_e32 v207, 10, v172
	v_add_u32_e32 v176, v180, v207
	v_lshlrev_b64 v[204:205], 2, v[176:177]
	s_waitcnt vmcnt(0)
	v_pk_mul_f32 v[196:197], s[36:37], v[128:129] op_sel_hi:[0,1]
	v_lshl_add_u64 v[128:129], s[34:35], 0, v[204:205]
	v_add_u32_e32 v202, 0x4000, v176
	v_mov_b32_e32 v203, v177
	global_load_dwordx4 v[152:155], v[128:129], off offset:16
	global_load_dwordx4 v[156:159], v[128:129], off
	v_lshl_add_u64 v[128:129], v[202:203], 2, s[34:35]
	v_add_u32_e32 v200, 0x8000, v176
	v_mov_b32_e32 v201, v177
	v_add_u32_e32 v198, 0xc000, v176
	v_mov_b32_e32 v199, v177
	v_pk_mul_f32 v[190:191], s[36:37], v[132:133] op_sel_hi:[0,1]
	global_load_dwordx4 v[136:139], v[128:129], off offset:16
	global_load_dwordx4 v[144:147], v[128:129], off
	v_lshl_add_u64 v[128:129], v[200:201], 2, s[34:35]
	v_lshl_add_u64 v[132:133], v[198:199], 2, s[34:35]
	v_pk_mul_f32 v[192:193], s[36:37], v[134:135] op_sel_hi:[0,1]
	v_pk_mul_f32 v[194:195], s[36:37], v[130:131] op_sel_hi:[0,1]
	global_load_dwordx4 v[140:143], v[128:129], off offset:16
	global_load_dwordx4 v[148:151], v[128:129], off
	s_nop 0
	global_load_dwordx4 v[128:131], v[132:133], off offset:16
	s_nop 0
	global_load_dwordx4 v[132:135], v[132:133], off
	v_lshl_add_u64 v[204:205], s[28:29], 0, v[204:205]
	s_and_b64 vcc, exec, s[8:9]
	v_mov_b32_e32 v173, 0
	s_waitcnt vmcnt(0)
	v_pk_fma_f32 v[154:155], v[122:123], v[192:193], v[154:155]
	s_waitcnt vmcnt(0)
	v_pk_fma_f32 v[158:159], v[126:127], v[194:195], v[158:159]
	v_pk_fma_f32 v[156:157], v[124:125], v[196:197], v[156:157]
	v_pk_fma_f32 v[152:153], v[120:121], v[190:191], v[152:153]
	global_store_dwordx4 v[204:205], v[156:159], off sc1
	global_store_dwordx4 v[204:205], v[152:155], off offset:16 sc1
	v_mov_b32_e32 v204, 0
	s_cbranch_vccnz .LBB0_489
	v_pk_mul_f32 v[210:211], v[184:185], v[158:159]
	v_pk_mul_f32 v[208:209], v[182:183], v[156:157]
	v_pk_mul_f32 v[212:213], v[188:189], v[154:155]
	v_pk_mul_f32 v[214:215], v[186:187], v[152:153]
	v_cvt_pk_bf16_f32 v208, v208, v209
	v_cvt_pk_bf16_f32 v209, v210, v211
	s_nop 0
	v_cvt_pk_bf16_f32 v210, v214, v215
	v_cvt_pk_bf16_f32 v211, v212, v213
	v_lshl_add_u64 v[212:213], v[176:177], 1, s[26:27]
	global_store_dwordx4 v[212:213], v[208:211], off sc1
	s_nop 1
	v_mov_b32_e32 v209, v152
	v_mov_b32_e32 v152, v157
	v_mov_b32_e32 v157, v154
	v_mov_b32_e32 v154, v159
	v_mov_b32_e32 v208, v156
	v_pk_mul_f32 v[152:153], v[152:153], v[152:153]
	v_mov_b32_e32 v156, v158
	v_pk_mul_f32 v[154:155], v[154:155], v[154:155]
	v_pk_fma_f32 v[152:153], v[208:209], v[208:209], v[152:153]
	v_pk_fma_f32 v[154:155], v[156:157], v[156:157], v[154:155]
	s_nop 0
	v_pk_add_f32 v[152:153], v[152:153], v[154:155]
	s_nop 0
	v_add_f32_e32 v173, v152, v153
.LBB0_489:
	s_waitcnt vmcnt(0)
	v_pk_fma_f32 v[146:147], v[110:111], v[194:195], v[146:147]
	v_pk_fma_f32 v[144:145], v[108:109], v[196:197], v[144:145]
	v_pk_fma_f32 v[138:139], v[106:107], v[192:193], v[138:139]
	v_pk_fma_f32 v[136:137], v[104:105], v[190:191], v[136:137]
	v_lshl_add_u64 v[152:153], v[202:203], 2, s[28:29]
	s_and_b64 vcc, exec, s[8:9]
	global_store_dwordx4 v[152:153], v[144:147], off sc1
	global_store_dwordx4 v[152:153], v[136:139], off offset:16 sc1
	s_cbranch_vccnz .LBB0_491
	v_pk_mul_f32 v[154:155], v[184:185], v[146:147]
	v_pk_mul_f32 v[152:153], v[182:183], v[144:145]
	v_pk_mul_f32 v[156:157], v[188:189], v[138:139]
	v_pk_mul_f32 v[158:159], v[186:187], v[136:137]
	v_cvt_pk_bf16_f32 v152, v152, v153
	v_cvt_pk_bf16_f32 v153, v154, v155
	s_nop 0
	v_cvt_pk_bf16_f32 v154, v158, v159
	v_cvt_pk_bf16_f32 v155, v156, v157
	v_lshl_add_u64 v[156:157], v[202:203], 1, s[26:27]
	global_store_dwordx4 v[156:157], v[152:155], off sc1
	s_nop 1
	v_mov_b32_e32 v153, v136
	v_mov_b32_e32 v136, v145
	v_mov_b32_e32 v145, v138
	v_mov_b32_e32 v138, v147
	v_mov_b32_e32 v152, v144
	v_pk_mul_f32 v[136:137], v[136:137], v[136:137]
	v_mov_b32_e32 v144, v146
	v_pk_mul_f32 v[138:139], v[138:139], v[138:139]
	v_pk_fma_f32 v[136:137], v[152:153], v[152:153], v[136:137]
	v_pk_fma_f32 v[138:139], v[144:145], v[144:145], v[138:139]
	s_nop 0
	v_pk_add_f32 v[136:137], v[136:137], v[138:139]
	s_nop 0
	v_add_f32_e32 v204, v136, v137
.LBB0_491:
	v_add_u32_e32 v208, 0x20000, v207
	v_add_u32_e32 v202, v208, v180
	v_mov_b32_e32 v203, v177
	v_lshl_add_u64 v[136:137], v[202:203], 2, s[34:35]
	global_load_dwordx4 v[152:155], v[136:137], off offset:16
	global_load_dwordx4 v[156:159], v[136:137], off
	v_add_u32_e32 v136, 0x4000, v202
	v_mov_b32_e32 v137, v177
	v_lshl_add_u64 v[144:145], v[136:137], 2, s[34:35]
	global_load_dwordx4 v[136:139], v[144:145], off offset:16
	s_nop 0
	global_load_dwordx4 v[144:147], v[144:145], off
	s_waitcnt vmcnt(0)
	v_pk_fma_f32 v[150:151], v[94:95], v[194:195], v[150:151]
	v_pk_fma_f32 v[148:149], v[92:93], v[196:197], v[148:149]
	v_pk_fma_f32 v[142:143], v[90:91], v[192:193], v[142:143]
	v_pk_fma_f32 v[140:141], v[88:89], v[190:191], v[140:141]
	v_lshl_add_u64 v[210:211], v[200:201], 2, s[28:29]
	v_mov_b32_e32 v203, 0
	s_and_b64 vcc, exec, s[8:9]
	v_mov_b32_e32 v205, 0
	global_store_dwordx4 v[210:211], v[148:151], off sc1
	global_store_dwordx4 v[210:211], v[140:143], off offset:16 sc1
	s_cbranch_vccnz .LBB0_493
	v_pk_mul_f32 v[212:213], v[184:185], v[150:151]
	v_pk_mul_f32 v[210:211], v[182:183], v[148:149]
	v_lshl_add_u64 v[200:201], v[200:201], 1, s[26:27]
	v_pk_mul_f32 v[214:215], v[188:189], v[142:143]
	v_pk_mul_f32 v[232:233], v[186:187], v[140:141]
	v_cvt_pk_bf16_f32 v210, v210, v211
	v_cvt_pk_bf16_f32 v211, v212, v213
	s_nop 0
	v_cvt_pk_bf16_f32 v212, v232, v233
	v_cvt_pk_bf16_f32 v213, v214, v215
	global_store_dwordx4 v[200:201], v[210:213], off sc1
	v_mov_b32_e32 v201, v140
	v_mov_b32_e32 v140, v149
	v_mov_b32_e32 v149, v142
	v_mov_b32_e32 v142, v151
	v_mov_b32_e32 v200, v148
	v_pk_mul_f32 v[140:141], v[140:141], v[140:141]
	v_mov_b32_e32 v148, v150
	v_pk_mul_f32 v[142:143], v[142:143], v[142:143]
	v_pk_fma_f32 v[140:141], v[200:201], v[200:201], v[140:141]
	v_pk_fma_f32 v[142:143], v[148:149], v[148:149], v[142:143]
	s_nop 0
	v_pk_add_f32 v[140:141], v[140:141], v[142:143]
	s_nop 0
	v_add_f32_e32 v205, v140, v141
;     static __device__ __forceinline__ void run(const f32x4 (&acc)[2][2][4][2], const Unit& u, int wr, int wc, int fr, int fq, const float* xin, float* xout, const float* gate, float gs, const float* lazy_ssq, const float* lazy_g, ...
;     ...
;                 gv[n] = *(const f32x4*)(gate + (b * 9216u + col + 4 * n)) * gs;
;                 lg[n] = (f32x4){1.f, 1.f, 1.f, 1.f}; if (LAZY) lg[n] = *(const f32x4*)(lazy_g + col + 4 * n);
;                 wv[n] = (f32x4){0.f, 0.f, 0.f, 0.f}; w2[n] = (f32x4){1.f, 1.f, 1.f, 1.f};
;                 if (aout) { wv[n] = *(const f32x4*)(wg + col + 4 * n) * (*(const f32x4*)(wsc + (b * 9216u + col + 4 * n)) + 1.0f); if (WG2) { w2[n] = *(const f32x4*)(wg2 + col + 4 * n); wv[n] = wv[n] * w2[n]; } }
;             }
;             f32x4 xq[2][2][2];
;     ...
;             constexpr bool DEEP = !LAZY && !WG2;
;             if (DEEP) RES_LD(0, 0);
; #pragma unroll
;             for (int pp = 0; pp < 4; ++pp) {
;                 if (DEEP) { if (pp < 3) RES_LD((pp + 1) & 1, pp + 1); } else RES_LD(pp & 1, pp);
; #pragma unroll
;                 for (int j = 0; j < 2; ++j) { const int i_ = 2 * pp + j, ai = i_ >> 2, m = i_ & 3; const unsigned off = (row0 + ai * HALF + m * 16) * 1024u + col;
;                     const f32x4 xi0 = xq[pp & 1][j][0], xi1 = xq[pp & 1][j][1];
;                     f32x4 xo0 = gv[0] * acc[ai][bj][m][0], xo1 = gv[1] * acc[ai][bj][m][1];
;                     if (LAZY) { xo0 = xo0 + xi0 * lg[0] * rl[ai][m]; xo1 = xo1 + xi1 * lg[1] * rl[ai][m]; } else { xo0 = xo0 + xi0; xo1 = xo1 + xi1; }
;                     *(f32x4*)(xout + off) = xo0; *(f32x4*)(xout + off + 4) = xo1;
;                     if (aout) { const f32x4 a0 = xo0 * wv[0], a1 = xo1 * wv[1]; u32x4 w; w.x = cvt_pk_bf16(a0[0], a0[1]); w.y = cvt_pk_bf16(a0[2], a0[3]); w.z = cvt_pk_bf16(a1[0], a1[1]); w.w = cvt_pk_bf16(a1[2], a1[3]);
;                         *(u32x4*)(aout + off) = w;
;                         sq[ai][m] += ((xo0[0] * xo0[0] + xo0[1] * xo0[1]) + (xo0[2] * xo0[2] + xo0[3] * xo0[3])) + ((xo1[0] * xo1[0] + xo1[1] * xo1[1]) + (xo1[2] * xo1[2] + xo1[3] * xo1[3]));
;                         if (WG2) { const f32x4 b0 = xo0 * w2[0], b1 = xo1 * w2[1]; sqb[ai][m] += ((b0[0] * b0[0] + b0[1] * b0[1]) + (b0[2] * b0[2] + b0[3] * b0[3])) + ((b1[0] * b1[0] + b1[1] * b1[1]) + (b1[2] * b1[2] + b1[3] * b1[3])); } } }
.LBB0_493:
	s_waitcnt vmcnt(0)
	v_pk_fma_f32 v[134:135], v[78:79], v[194:195], v[134:135]
	v_pk_fma_f32 v[132:133], v[76:77], v[196:197], v[132:133]
	v_pk_fma_f32 v[130:131], v[74:75], v[192:193], v[130:131]
	v_pk_fma_f32 v[128:129], v[72:73], v[190:191], v[128:129]
	v_lshl_add_u64 v[140:141], v[198:199], 2, s[28:29]
	s_and_b64 vcc, exec, s[8:9]
	global_store_dwordx4 v[140:141], v[132:135], off sc1
	global_store_dwordx4 v[140:141], v[128:131], off offset:16 sc1
	s_cbranch_vccnz .LBB0_495
	v_pk_mul_f32 v[142:143], v[184:185], v[134:135]
	v_pk_mul_f32 v[140:141], v[182:183], v[132:133]
	v_pk_mul_f32 v[148:149], v[188:189], v[130:131]
	v_pk_mul_f32 v[150:151], v[186:187], v[128:129]
	v_cvt_pk_bf16_f32 v140, v140, v141
	v_cvt_pk_bf16_f32 v141, v142, v143
	s_nop 0
	v_cvt_pk_bf16_f32 v142, v150, v151
	v_cvt_pk_bf16_f32 v143, v148, v149
	v_lshl_add_u64 v[148:149], v[198:199], 1, s[26:27]
	global_store_dwordx4 v[148:149], v[140:143], off sc1
	s_nop 1
	v_mov_b32_e32 v141, v128
	v_mov_b32_e32 v128, v133
	v_mov_b32_e32 v133, v130
	v_mov_b32_e32 v130, v135
	v_mov_b32_e32 v140, v132
	v_pk_mul_f32 v[128:129], v[128:129], v[128:129]
	v_mov_b32_e32 v132, v134
	v_pk_mul_f32 v[130:131], v[130:131], v[130:131]
	v_pk_fma_f32 v[128:129], v[140:141], v[140:141], v[128:129]
	v_pk_fma_f32 v[130:131], v[132:133], v[132:133], v[130:131]
	s_nop 0
	v_pk_add_f32 v[128:129], v[128:129], v[130:131]
	s_nop 0
	v_add_f32_e32 v203, v128, v129
.LBB0_495:
	s_nop 0
	v_add_u32_e32 v128, 0x8000, v202
	v_mov_b32_e32 v129, v177
	v_lshl_add_u64 v[128:129], v[128:129], 2, s[34:35]
	global_load_dwordx4 v[140:143], v[128:129], off offset:16
	global_load_dwordx4 v[148:151], v[128:129], off
	v_add_u32_e32 v128, 0xc000, v202
	v_mov_b32_e32 v129, v177
	v_lshl_add_u64 v[132:133], v[128:129], 2, s[34:35]
	global_load_dwordx4 v[128:131], v[132:133], off offset:16
	s_nop 0
	global_load_dwordx4 v[132:135], v[132:133], off
	v_add_u32_e32 v198, 0x20000, v176
	v_mov_b32_e32 v199, v177
	s_waitcnt vmcnt(0)
	v_pk_fma_f32 v[158:159], v[62:63], v[194:195], v[158:159]
	v_pk_fma_f32 v[156:157], v[60:61], v[196:197], v[156:157]
	v_lshl_add_u64 v[200:201], v[198:199], 2, s[28:29]
	v_pk_fma_f32 v[154:155], v[58:59], v[192:193], v[154:155]
	v_pk_fma_f32 v[152:153], v[56:57], v[190:191], v[152:153]
	global_store_dwordx4 v[200:201], v[156:159], off sc1
	global_store_dwordx4 v[200:201], v[152:155], off offset:16 sc1
	v_mov_b32_e32 v200, 0
	s_and_b64 vcc, exec, s[8:9]
	v_mov_b32_e32 v201, 0
	s_cbranch_vccnz .LBB0_497
	v_pk_mul_f32 v[212:213], v[184:185], v[158:159]
	v_pk_mul_f32 v[210:211], v[182:183], v[156:157]
	v_lshl_add_u64 v[198:199], v[198:199], 1, s[26:27]
	v_pk_mul_f32 v[214:215], v[188:189], v[154:155]
	v_pk_mul_f32 v[232:233], v[186:187], v[152:153]
	v_cvt_pk_bf16_f32 v210, v210, v211
	v_cvt_pk_bf16_f32 v211, v212, v213
	s_nop 0
	v_cvt_pk_bf16_f32 v212, v232, v233
	v_cvt_pk_bf16_f32 v213, v214, v215
	global_store_dwordx4 v[198:199], v[210:213], off sc1
	v_mov_b32_e32 v199, v152
	v_mov_b32_e32 v152, v157
	v_mov_b32_e32 v157, v154
	v_mov_b32_e32 v154, v159
	v_mov_b32_e32 v198, v156
	v_pk_mul_f32 v[152:153], v[152:153], v[152:153]
	v_mov_b32_e32 v156, v158
	v_pk_mul_f32 v[154:155], v[154:155], v[154:155]
	v_pk_fma_f32 v[152:153], v[198:199], v[198:199], v[152:153]
	v_pk_fma_f32 v[154:155], v[156:157], v[156:157], v[154:155]
	s_nop 0
	v_pk_add_f32 v[152:153], v[152:153], v[154:155]
	s_nop 0
	v_add_f32_e32 v201, v152, v153
;     static __device__ __forceinline__ void run(const f32x4 (&acc)[2][2][4][2], const Unit& u, int wr, int wc, int fr, int fq, const float* xin, float* xout, const float* gate, float gs, const float* lazy_ssq, const float* lazy_g, ...
;     ...
;                 gv[n] = *(const f32x4*)(gate + (b * 9216u + col + 4 * n)) * gs;
;                 lg[n] = (f32x4){1.f, 1.f, 1.f, 1.f}; if (LAZY) lg[n] = *(const f32x4*)(lazy_g + col + 4 * n);
;                 wv[n] = (f32x4){0.f, 0.f, 0.f, 0.f}; w2[n] = (f32x4){1.f, 1.f, 1.f, 1.f};
;                 if (aout) { wv[n] = *(const f32x4*)(wg + col + 4 * n) * (*(const f32x4*)(wsc + (b * 9216u + col + 4 * n)) + 1.0f); if (WG2) { w2[n] = *(const f32x4*)(wg2 + col + 4 * n); wv[n] = wv[n] * w2[n]; } }
;             }
;             f32x4 xq[2][2][2];
;     ...
;             constexpr bool DEEP = !LAZY && !WG2;
;             if (DEEP) RES_LD(0, 0);
; #pragma unroll
;             for (int pp = 0; pp < 4; ++pp) {
;                 if (DEEP) { if (pp < 3) RES_LD((pp + 1) & 1, pp + 1); } else RES_LD(pp & 1, pp);
; #pragma unroll
;                 for (int j = 0; j < 2; ++j) { const int i_ = 2 * pp + j, ai = i_ >> 2, m = i_ & 3; const unsigned off = (row0 + ai * HALF + m * 16) * 1024u + col;
;                     const f32x4 xi0 = xq[pp & 1][j][0], xi1 = xq[pp & 1][j][1];
;                     f32x4 xo0 = gv[0] * acc[ai][bj][m][0], xo1 = gv[1] * acc[ai][bj][m][1];
;                     if (LAZY) { xo0 = xo0 + xi0 * lg[0] * rl[ai][m]; xo1 = xo1 + xi1 * lg[1] * rl[ai][m]; } else { xo0 = xo0 + xi0; xo1 = xo1 + xi1; }
;                     *(f32x4*)(xout + off) = xo0; *(f32x4*)(xout + off + 4) = xo1;
;                     if (aout) { const f32x4 a0 = xo0 * wv[0], a1 = xo1 * wv[1]; u32x4 w; w.x = cvt_pk_bf16(a0[0], a0[1]); w.y = cvt_pk_bf16(a0[2], a0[3]); w.z = cvt_pk_bf16(a1[0], a1[1]); w.w = cvt_pk_bf16(a1[2], a1[3]);
;                         *(u32x4*)(aout + off) = w;
;                         sq[ai][m] += ((xo0[0] * xo0[0] + xo0[1] * xo0[1]) + (xo0[2] * xo0[2] + xo0[3] * xo0[3])) + ((xo1[0] * xo1[0] + xo1[1] * xo1[1]) + (xo1[2] * xo1[2] + xo1[3] * xo1[3]));
;                         if (WG2) { const f32x4 b0 = xo0 * w2[0], b1 = xo1 * w2[1]; sqb[ai][m] += ((b0[0] * b0[0] + b0[1] * b0[1]) + (b0[2] * b0[2] + b0[3] * b0[3])) + ((b1[0] * b1[0] + b1[1] * b1[1]) + (b1[2] * b1[2] + b1[3] * b1[3])); } } }
.LBB0_497:
	v_add_u32_e32 v152, 0x24000, v176
	v_mov_b32_e32 v153, v177
	s_waitcnt vmcnt(0)
	v_pk_fma_f32 v[146:147], v[46:47], v[194:195], v[146:147]
	v_pk_fma_f32 v[144:145], v[44:45], v[196:197], v[144:145]
	v_pk_fma_f32 v[138:139], v[42:43], v[192:193], v[138:139]
	v_pk_fma_f32 v[136:137], v[40:41], v[190:191], v[136:137]
	v_lshl_add_u64 v[154:155], v[152:153], 2, s[28:29]
	s_and_b64 vcc, exec, s[8:9]
	global_store_dwordx4 v[154:155], v[144:147], off sc1
	global_store_dwordx4 v[154:155], v[136:139], off offset:16 sc1
	s_cbranch_vccnz .LBB0_499
	v_pk_mul_f32 v[156:157], v[184:185], v[146:147]
	v_pk_mul_f32 v[154:155], v[182:183], v[144:145]
	v_lshl_add_u64 v[152:153], v[152:153], 1, s[26:27]
	v_pk_mul_f32 v[158:159], v[188:189], v[138:139]
	v_pk_mul_f32 v[198:199], v[186:187], v[136:137]
	v_cvt_pk_bf16_f32 v154, v154, v155
	v_cvt_pk_bf16_f32 v155, v156, v157
	s_nop 0
	v_cvt_pk_bf16_f32 v156, v198, v199
	v_cvt_pk_bf16_f32 v157, v158, v159
	global_store_dwordx4 v[152:153], v[154:157], off sc1
	v_mov_b32_e32 v153, v136
	v_mov_b32_e32 v136, v145
	v_mov_b32_e32 v145, v138
	v_mov_b32_e32 v138, v147
	v_mov_b32_e32 v152, v144
	v_pk_mul_f32 v[136:137], v[136:137], v[136:137]
	v_mov_b32_e32 v144, v146
	v_pk_mul_f32 v[138:139], v[138:139], v[138:139]
	v_pk_fma_f32 v[136:137], v[152:153], v[152:153], v[136:137]
	v_pk_fma_f32 v[138:139], v[144:145], v[144:145], v[138:139]
	s_nop 0
	v_pk_add_f32 v[136:137], v[136:137], v[138:139]
	s_nop 0
	v_add_f32_e32 v200, v136, v137
.LBB0_499:
	v_add_u32_e32 v144, 0x28000, v176
	v_mov_b32_e32 v145, v177
	s_waitcnt vmcnt(0)
	v_pk_fma_f32 v[138:139], v[30:31], v[194:195], v[150:151]
	v_pk_fma_f32 v[136:137], v[28:29], v[196:197], v[148:149]
	v_pk_fma_f32 v[142:143], v[26:27], v[192:193], v[142:143]
	v_pk_fma_f32 v[140:141], v[24:25], v[190:191], v[140:141]
	v_lshl_add_u64 v[146:147], v[144:145], 2, s[28:29]
	v_mov_b32_e32 v202, 0
	s_and_b64 vcc, exec, s[8:9]
	v_mov_b32_e32 v206, 0
	global_store_dwordx4 v[146:147], v[136:139], off sc1
	global_store_dwordx4 v[146:147], v[140:143], off offset:16 sc1
	s_cbranch_vccnz .LBB0_501
	v_pk_mul_f32 v[148:149], v[184:185], v[138:139]
	v_pk_mul_f32 v[146:147], v[182:183], v[136:137]
	v_lshl_add_u64 v[144:145], v[144:145], 1, s[26:27]
	v_pk_mul_f32 v[150:151], v[188:189], v[142:143]
	v_pk_mul_f32 v[152:153], v[186:187], v[140:141]
	v_cvt_pk_bf16_f32 v146, v146, v147
	v_cvt_pk_bf16_f32 v147, v148, v149
	s_nop 0
	v_cvt_pk_bf16_f32 v148, v152, v153
	v_cvt_pk_bf16_f32 v149, v150, v151
	global_store_dwordx4 v[144:145], v[146:149], off sc1
	v_mov_b32_e32 v145, v140
	v_mov_b32_e32 v140, v137
	v_mov_b32_e32 v144, v136
	v_pk_mul_f32 v[136:137], v[140:141], v[140:141]
	v_mov_b32_e32 v141, v142
	v_mov_b32_e32 v142, v139
	v_mov_b32_e32 v140, v138
	v_pk_mul_f32 v[138:139], v[142:143], v[142:143]
	v_pk_fma_f32 v[136:137], v[144:145], v[144:145], v[136:137]
	v_pk_fma_f32 v[138:139], v[140:141], v[140:141], v[138:139]
	s_nop 0
	v_pk_add_f32 v[136:137], v[136:137], v[138:139]
	s_nop 0
	v_add_f32_e32 v206, v136, v137
.LBB0_501:
	v_add_u32_e32 v176, 0x2c000, v176
	s_waitcnt vmcnt(0)
	v_pk_fma_f32 v[134:135], v[14:15], v[194:195], v[134:135]
	v_pk_fma_f32 v[132:133], v[12:13], v[196:197], v[132:133]
	v_pk_fma_f32 v[130:131], v[10:11], v[192:193], v[130:131]
	v_pk_fma_f32 v[128:129], v[8:9], v[190:191], v[128:129]
	v_lshl_add_u64 v[136:137], v[176:177], 2, s[28:29]
	s_and_b64 vcc, exec, s[8:9]
	global_store_dwordx4 v[136:137], v[132:135], off sc1
	global_store_dwordx4 v[136:137], v[128:131], off offset:16 sc1
	s_cbranch_vccnz .LBB0_503
	v_pk_mul_f32 v[138:139], v[184:185], v[134:135]
	v_pk_mul_f32 v[136:137], v[182:183], v[132:133]
	v_pk_mul_f32 v[140:141], v[188:189], v[130:131]
	v_pk_mul_f32 v[142:143], v[186:187], v[128:129]
	v_cvt_pk_bf16_f32 v136, v136, v137
	v_cvt_pk_bf16_f32 v137, v138, v139
	s_nop 0
	v_cvt_pk_bf16_f32 v138, v142, v143
	v_cvt_pk_bf16_f32 v139, v140, v141
	v_lshl_add_u64 v[140:141], v[176:177], 1, s[26:27]
	global_store_dwordx4 v[140:141], v[136:139], off sc1
	s_nop 1
	v_mov_b32_e32 v137, v128
	v_mov_b32_e32 v128, v133
	v_mov_b32_e32 v133, v130
	v_mov_b32_e32 v130, v135
	v_mov_b32_e32 v136, v132
	v_pk_mul_f32 v[128:129], v[128:129], v[128:129]
	v_mov_b32_e32 v132, v134
	v_pk_mul_f32 v[130:131], v[130:131], v[130:131]
	v_pk_fma_f32 v[128:129], v[136:137], v[136:137], v[128:129]
	v_pk_fma_f32 v[130:131], v[132:133], v[132:133], v[130:131]
	s_nop 0
	v_pk_add_f32 v[128:129], v[128:129], v[130:131]
	s_nop 0
	v_add_f32_e32 v202, v128, v129

;     static __device__ __forceinline__ void run(const f32x4 (&acc)[2][2][4][2], const Unit& u, int wr, int wc, int fr, int fq, const float* xin, float* xout, const float* gate, float gs, const float* lazy_ssq, const float* lazy_g, ...
;     ...
;                 gv[n] = *(const f32x4*)(gate + (b * 9216u + col + 4 * n)) * gs;
;                 lg[n] = (f32x4){1.f, 1.f, 1.f, 1.f}; if (LAZY) lg[n] = *(const f32x4*)(lazy_g + col + 4 * n);
;                 wv[n] = (f32x4){0.f, 0.f, 0.f, 0.f}; w2[n] = (f32x4){1.f, 1.f, 1.f, 1.f};
;                 if (aout) { wv[n] = *(const f32x4*)(wg + col + 4 * n) * (*(const f32x4*)(wsc + (b * 9216u + col + 4 * n)) + 1.0f); if (WG2) { w2[n] = *(const f32x4*)(wg2 + col + 4 * n); wv[n] = wv[n] * w2[n]; } }
;             }
;             f32x4 xq[2][2][2];
;     ...
;             constexpr bool DEEP = !LAZY && !WG2;
;             if (DEEP) RES_LD(0, 0);
; #pragma unroll
;             for (int pp = 0; pp < 4; ++pp) {
;                 if (DEEP) { if (pp < 3) RES_LD((pp + 1) & 1, pp + 1); } else RES_LD(pp & 1, pp);
; #pragma unroll
;                 for (int j = 0; j < 2; ++j) { const int i_ = 2 * pp + j, ai = i_ >> 2, m = i_ & 3; const unsigned off = (row0 + ai * HALF + m * 16) * 1024u + col;
;                     const f32x4 xi0 = xq[pp & 1][j][0], xi1 = xq[pp & 1][j][1];
;                     f32x4 xo0 = gv[0] * acc[ai][bj][m][0], xo1 = gv[1] * acc[ai][bj][m][1];
;                     if (LAZY) { xo0 = xo0 + xi0 * lg[0] * rl[ai][m]; xo1 = xo1 + xi1 * lg[1] * rl[ai][m]; } else { xo0 = xo0 + xi0; xo1 = xo1 + xi1; }
;                     *(f32x4*)(xout + off) = xo0; *(f32x4*)(xout + off + 4) = xo1;
;                     if (aout) { const f32x4 a0 = xo0 * wv[0], a1 = xo1 * wv[1]; u32x4 w; w.x = cvt_pk_bf16(a0[0], a0[1]); w.y = cvt_pk_bf16(a0[2], a0[3]); w.z = cvt_pk_bf16(a1[0], a1[1]); w.w = cvt_pk_bf16(a1[2], a1[3]);
;                         *(u32x4*)(aout + off) = w;
;                         sq[ai][m] += ((xo0[0] * xo0[0] + xo0[1] * xo0[1]) + (xo0[2] * xo0[2] + xo0[3] * xo0[3])) + ((xo1[0] * xo1[0] + xo1[1] * xo1[1]) + (xo1[2] * xo1[2] + xo1[3] * xo1[3]));
;                         if (WG2) { const f32x4 b0 = xo0 * w2[0], b1 = xo1 * w2[1]; sqb[ai][m] += ((b0[0] * b0[0] + b0[1] * b0[1]) + (b0[2] * b0[2] + b0[3] * b0[3])) + ((b1[0] * b1[0] + b1[1] * b1[1]) + (b1[2] * b1[2] + b1[3] * b1[3])); } } }
.LBB0_507:
	v_add_u32_e32 v176, v209, v207
	v_lshlrev_b64 v[214:215], 2, v[176:177]
	v_lshl_add_u64 v[128:129], s[34:35], 0, v[214:215]
	v_add_u32_e32 v198, 0x4000, v176
	v_mov_b32_e32 v199, v177
	global_load_dwordx4 v[210:213], v[128:129], off offset:16
	global_load_dwordx4 v[232:235], v[128:129], off
	v_lshl_add_u64 v[128:129], v[198:199], 2, s[34:35]
	v_add_u32_e32 v196, 0x8000, v176
	v_mov_b32_e32 v197, v177
	v_add_u32_e32 v194, 0xc000, v176
	v_mov_b32_e32 v195, v177
	global_load_dwordx4 v[132:135], v[128:129], off offset:16
	global_load_dwordx4 v[152:155], v[128:129], off
	v_lshl_add_u64 v[128:129], v[196:197], 2, s[34:35]
	v_lshl_add_u64 v[136:137], v[194:195], 2, s[34:35]
	global_load_dwordx4 v[144:147], v[128:129], off offset:16
	global_load_dwordx4 v[148:151], v[128:129], off
	s_nop 0
	global_load_dwordx4 v[128:131], v[136:137], off offset:16
	s_nop 0
	global_load_dwordx4 v[136:139], v[136:137], off
	s_mov_b32 s37, s36
	s_mov_b32 s38, s36
	s_mov_b32 s39, s36
	s_waitcnt vmcnt(8)
	v_pk_mul_f32 v[188:189], s[38:39], v[158:159]
	v_pk_mul_f32 v[174:175], s[36:37], v[156:157]
	v_pk_mul_f32 v[190:191], s[38:39], v[142:143]
	v_pk_mul_f32 v[192:193], s[36:37], v[140:141]
	s_and_b64 vcc, exec, s[8:9]
	v_lshl_add_u64 v[214:215], s[28:29], 0, v[214:215]
	s_waitcnt vmcnt(0)
	v_pk_fma_f32 v[142:143], v[114:115], v[188:189], v[212:213]
	s_waitcnt vmcnt(0)
	v_pk_fma_f32 v[158:159], v[118:119], v[190:191], v[234:235]
	v_pk_fma_f32 v[156:157], v[116:117], v[192:193], v[232:233]
	v_pk_fma_f32 v[140:141], v[112:113], v[174:175], v[210:211]
	global_store_dwordx4 v[214:215], v[156:159], off sc1
	global_store_dwordx4 v[214:215], v[140:143], off offset:16 sc1
	s_cbranch_vccnz .LBB0_509
	v_pk_mul_f32 v[212:213], v[184:185], v[158:159]
	v_pk_mul_f32 v[210:211], v[182:183], v[156:157]
	v_pk_mul_f32 v[214:215], v[186:187], v[142:143]
	v_pk_mul_f32 v[232:233], v[180:181], v[140:141]
	v_cvt_pk_bf16_f32 v210, v210, v211
	v_cvt_pk_bf16_f32 v211, v212, v213
	s_nop 0
	v_cvt_pk_bf16_f32 v212, v232, v233
	v_cvt_pk_bf16_f32 v213, v214, v215
	v_lshl_add_u64 v[214:215], v[176:177], 1, s[26:27]
	global_store_dwordx4 v[214:215], v[210:213], off sc1
	s_nop 1
	v_mov_b32_e32 v211, v140
	v_mov_b32_e32 v140, v157
	v_mov_b32_e32 v157, v142
	v_mov_b32_e32 v142, v159
	v_mov_b32_e32 v210, v156
	v_pk_mul_f32 v[140:141], v[140:141], v[140:141]
	v_mov_b32_e32 v156, v158
	v_pk_mul_f32 v[142:143], v[142:143], v[142:143]
	v_pk_fma_f32 v[140:141], v[210:211], v[210:211], v[140:141]
	v_pk_fma_f32 v[142:143], v[156:157], v[156:157], v[142:143]
	s_nop 0
	v_pk_add_f32 v[140:141], v[140:141], v[142:143]
	s_nop 0
	v_add_f32_e32 v140, v140, v141
	v_add_f32_e32 v173, v173, v140
.LBB0_509:
	s_waitcnt vmcnt(0)
	v_pk_fma_f32 v[142:143], v[102:103], v[190:191], v[154:155]
	v_pk_fma_f32 v[140:141], v[100:101], v[192:193], v[152:153]
	v_pk_fma_f32 v[134:135], v[98:99], v[188:189], v[134:135]
	v_pk_fma_f32 v[132:133], v[96:97], v[174:175], v[132:133]
	v_lshl_add_u64 v[152:153], v[198:199], 2, s[28:29]
	s_and_b64 vcc, exec, s[8:9]
	global_store_dwordx4 v[152:153], v[140:143], off sc1
	global_store_dwordx4 v[152:153], v[132:135], off offset:16 sc1
	s_cbranch_vccnz .LBB0_511
	v_pk_mul_f32 v[154:155], v[184:185], v[142:143]
	v_pk_mul_f32 v[152:153], v[182:183], v[140:141]
	v_pk_mul_f32 v[156:157], v[186:187], v[134:135]
	v_pk_mul_f32 v[158:159], v[180:181], v[132:133]
	v_cvt_pk_bf16_f32 v152, v152, v153
	v_cvt_pk_bf16_f32 v153, v154, v155
	s_nop 0
	v_cvt_pk_bf16_f32 v154, v158, v159
	v_cvt_pk_bf16_f32 v155, v156, v157
	v_lshl_add_u64 v[156:157], v[198:199], 1, s[26:27]
	global_store_dwordx4 v[156:157], v[152:155], off sc1
	s_nop 1
	v_mov_b32_e32 v153, v132
	v_mov_b32_e32 v132, v141
	v_mov_b32_e32 v141, v134
	v_mov_b32_e32 v134, v143
	v_mov_b32_e32 v152, v140
	v_pk_mul_f32 v[132:133], v[132:133], v[132:133]
	v_mov_b32_e32 v140, v142
	v_pk_mul_f32 v[134:135], v[134:135], v[134:135]
	v_pk_fma_f32 v[132:133], v[152:153], v[152:153], v[132:133]
	v_pk_fma_f32 v[134:135], v[140:141], v[140:141], v[134:135]
	s_nop 0
	v_pk_add_f32 v[132:133], v[132:133], v[134:135]
	s_nop 0
	v_add_f32_e32 v132, v132, v133
	v_add_f32_e32 v204, v204, v132
.LBB0_511:
	v_add_u32_e32 v198, v208, v209
	v_mov_b32_e32 v199, v177
	v_lshl_add_u64 v[132:133], v[198:199], 2, s[34:35]
	global_load_dwordx4 v[152:155], v[132:133], off offset:16
	global_load_dwordx4 v[156:159], v[132:133], off
	v_add_u32_e32 v132, 0x4000, v198
	v_mov_b32_e32 v133, v177
	v_lshl_add_u64 v[140:141], v[132:133], 2, s[34:35]
	global_load_dwordx4 v[132:135], v[140:141], off offset:16
	s_nop 0
	global_load_dwordx4 v[140:143], v[140:141], off
	s_waitcnt vmcnt(0)
	v_pk_fma_f32 v[150:151], v[86:87], v[190:191], v[150:151]
	v_pk_fma_f32 v[148:149], v[84:85], v[192:193], v[148:149]
	v_pk_fma_f32 v[146:147], v[82:83], v[188:189], v[146:147]
	v_pk_fma_f32 v[144:145], v[80:81], v[174:175], v[144:145]
	v_lshl_add_u64 v[208:209], v[196:197], 2, s[28:29]
	s_and_b64 vcc, exec, s[8:9]
	global_store_dwordx4 v[208:209], v[148:151], off sc1
	global_store_dwordx4 v[208:209], v[144:147], off offset:16 sc1
	s_cbranch_vccnz .LBB0_513
	v_pk_mul_f32 v[210:211], v[184:185], v[150:151]
	v_pk_mul_f32 v[208:209], v[182:183], v[148:149]
	v_lshl_add_u64 v[196:197], v[196:197], 1, s[26:27]
	v_pk_mul_f32 v[212:213], v[186:187], v[146:147]
	v_pk_mul_f32 v[214:215], v[180:181], v[144:145]
	v_cvt_pk_bf16_f32 v208, v208, v209
	v_cvt_pk_bf16_f32 v209, v210, v211
	s_nop 0
	v_cvt_pk_bf16_f32 v210, v214, v215
	v_cvt_pk_bf16_f32 v211, v212, v213
	global_store_dwordx4 v[196:197], v[208:211], off sc1
	v_mov_b32_e32 v197, v144
	v_mov_b32_e32 v144, v149
	v_mov_b32_e32 v149, v146
	v_mov_b32_e32 v146, v151
	v_mov_b32_e32 v196, v148
	v_pk_mul_f32 v[144:145], v[144:145], v[144:145]
	v_mov_b32_e32 v148, v150
	v_pk_mul_f32 v[146:147], v[146:147], v[146:147]
	v_pk_fma_f32 v[144:145], v[196:197], v[196:197], v[144:145]
	v_pk_fma_f32 v[146:147], v[148:149], v[148:149], v[146:147]
	s_nop 0
	v_pk_add_f32 v[144:145], v[144:145], v[146:147]
	s_nop 0
	v_add_f32_e32 v144, v144, v145
	v_add_f32_e32 v205, v205, v144
;     static __device__ __forceinline__ void run(const f32x4 (&acc)[2][2][4][2], const Unit& u, int wr, int wc, int fr, int fq, const float* xin, float* xout, const float* gate, float gs, const float* lazy_ssq, const float* lazy_g, ...
;     ...
;                 gv[n] = *(const f32x4*)(gate + (b * 9216u + col + 4 * n)) * gs;
;                 lg[n] = (f32x4){1.f, 1.f, 1.f, 1.f}; if (LAZY) lg[n] = *(const f32x4*)(lazy_g + col + 4 * n);
;                 wv[n] = (f32x4){0.f, 0.f, 0.f, 0.f}; w2[n] = (f32x4){1.f, 1.f, 1.f, 1.f};
;                 if (aout) { wv[n] = *(const f32x4*)(wg + col + 4 * n) * (*(const f32x4*)(wsc + (b * 9216u + col + 4 * n)) + 1.0f); if (WG2) { w2[n] = *(const f32x4*)(wg2 + col + 4 * n); wv[n] = wv[n] * w2[n]; } }
;             }
;             f32x4 xq[2][2][2];
;     ...
;             constexpr bool DEEP = !LAZY && !WG2;
;             if (DEEP) RES_LD(0, 0);
; #pragma unroll
;             for (int pp = 0; pp < 4; ++pp) {
;                 if (DEEP) { if (pp < 3) RES_LD((pp + 1) & 1, pp + 1); } else RES_LD(pp & 1, pp);
; #pragma unroll
;                 for (int j = 0; j < 2; ++j) { const int i_ = 2 * pp + j, ai = i_ >> 2, m = i_ & 3; const unsigned off = (row0 + ai * HALF + m * 16) * 1024u + col;
;                     const f32x4 xi0 = xq[pp & 1][j][0], xi1 = xq[pp & 1][j][1];
;                     f32x4 xo0 = gv[0] * acc[ai][bj][m][0], xo1 = gv[1] * acc[ai][bj][m][1];
;                     if (LAZY) { xo0 = xo0 + xi0 * lg[0] * rl[ai][m]; xo1 = xo1 + xi1 * lg[1] * rl[ai][m]; } else { xo0 = xo0 + xi0; xo1 = xo1 + xi1; }
;                     *(f32x4*)(xout + off) = xo0; *(f32x4*)(xout + off + 4) = xo1;
;                     if (aout) { const f32x4 a0 = xo0 * wv[0], a1 = xo1 * wv[1]; u32x4 w; w.x = cvt_pk_bf16(a0[0], a0[1]); w.y = cvt_pk_bf16(a0[2], a0[3]); w.z = cvt_pk_bf16(a1[0], a1[1]); w.w = cvt_pk_bf16(a1[2], a1[3]);
;                         *(u32x4*)(aout + off) = w;
;                         sq[ai][m] += ((xo0[0] * xo0[0] + xo0[1] * xo0[1]) + (xo0[2] * xo0[2] + xo0[3] * xo0[3])) + ((xo1[0] * xo1[0] + xo1[1] * xo1[1]) + (xo1[2] * xo1[2] + xo1[3] * xo1[3]));
;                         if (WG2) { const f32x4 b0 = xo0 * w2[0], b1 = xo1 * w2[1]; sqb[ai][m] += ((b0[0] * b0[0] + b0[1] * b0[1]) + (b0[2] * b0[2] + b0[3] * b0[3])) + ((b1[0] * b1[0] + b1[1] * b1[1]) + (b1[2] * b1[2] + b1[3] * b1[3])); } } }
.LBB0_513:
	s_waitcnt vmcnt(0)
	v_pk_fma_f32 v[138:139], v[70:71], v[190:191], v[138:139]
	v_pk_fma_f32 v[136:137], v[68:69], v[192:193], v[136:137]
	v_pk_fma_f32 v[130:131], v[66:67], v[188:189], v[130:131]
	v_pk_fma_f32 v[128:129], v[64:65], v[174:175], v[128:129]
	v_lshl_add_u64 v[144:145], v[194:195], 2, s[28:29]
	s_and_b64 vcc, exec, s[8:9]
	global_store_dwordx4 v[144:145], v[136:139], off sc1
	global_store_dwordx4 v[144:145], v[128:131], off offset:16 sc1
	s_cbranch_vccnz .LBB0_515
	v_pk_mul_f32 v[146:147], v[184:185], v[138:139]
	v_pk_mul_f32 v[144:145], v[182:183], v[136:137]
	v_pk_mul_f32 v[148:149], v[186:187], v[130:131]
	v_pk_mul_f32 v[150:151], v[180:181], v[128:129]
	v_cvt_pk_bf16_f32 v144, v144, v145
	v_cvt_pk_bf16_f32 v145, v146, v147
	s_nop 0
	v_cvt_pk_bf16_f32 v146, v150, v151
	v_cvt_pk_bf16_f32 v147, v148, v149
	v_lshl_add_u64 v[148:149], v[194:195], 1, s[26:27]
	global_store_dwordx4 v[148:149], v[144:147], off sc1
	s_nop 1
	v_mov_b32_e32 v145, v128
	v_mov_b32_e32 v128, v137
	v_mov_b32_e32 v137, v130
	v_mov_b32_e32 v130, v139
	v_mov_b32_e32 v144, v136
	v_pk_mul_f32 v[128:129], v[128:129], v[128:129]
	v_mov_b32_e32 v136, v138
	v_pk_mul_f32 v[130:131], v[130:131], v[130:131]
	v_pk_fma_f32 v[128:129], v[144:145], v[144:145], v[128:129]
	v_pk_fma_f32 v[130:131], v[136:137], v[136:137], v[130:131]
	s_nop 0
	v_pk_add_f32 v[128:129], v[128:129], v[130:131]
	s_nop 0
	v_add_f32_e32 v128, v128, v129
	v_add_f32_e32 v203, v203, v128
.LBB0_515:
	s_nop 0
	v_add_u32_e32 v128, 0x8000, v198
	v_mov_b32_e32 v129, v177
	v_lshl_add_u64 v[128:129], v[128:129], 2, s[34:35]
	global_load_dwordx4 v[144:147], v[128:129], off offset:16
	global_load_dwordx4 v[148:151], v[128:129], off
	v_add_u32_e32 v128, 0xc000, v198
	v_mov_b32_e32 v129, v177
	v_lshl_add_u64 v[136:137], v[128:129], 2, s[34:35]
	global_load_dwordx4 v[128:131], v[136:137], off offset:16
	s_nop 0
	global_load_dwordx4 v[136:139], v[136:137], off
	v_add_u32_e32 v194, 0x20000, v176
	v_mov_b32_e32 v195, v177
	s_waitcnt vmcnt(0)
	v_pk_fma_f32 v[158:159], v[54:55], v[190:191], v[158:159]
	v_pk_fma_f32 v[156:157], v[52:53], v[192:193], v[156:157]
	v_pk_fma_f32 v[154:155], v[50:51], v[188:189], v[154:155]
	v_pk_fma_f32 v[152:153], v[48:49], v[174:175], v[152:153]
	v_lshl_add_u64 v[196:197], v[194:195], 2, s[28:29]
	s_and_b64 vcc, exec, s[8:9]
	global_store_dwordx4 v[196:197], v[156:159], off sc1
	global_store_dwordx4 v[196:197], v[152:155], off offset:16 sc1
	s_cbranch_vccnz .LBB0_517
	v_pk_mul_f32 v[198:199], v[184:185], v[158:159]
	v_pk_mul_f32 v[196:197], v[182:183], v[156:157]
	v_lshl_add_u64 v[194:195], v[194:195], 1, s[26:27]
	v_pk_mul_f32 v[208:209], v[186:187], v[154:155]
	v_pk_mul_f32 v[210:211], v[180:181], v[152:153]
	v_cvt_pk_bf16_f32 v196, v196, v197
	v_cvt_pk_bf16_f32 v197, v198, v199
	s_nop 0
	v_cvt_pk_bf16_f32 v198, v210, v211
	v_cvt_pk_bf16_f32 v199, v208, v209
	global_store_dwordx4 v[194:195], v[196:199], off sc1
	v_mov_b32_e32 v195, v152
	v_mov_b32_e32 v152, v157
	v_mov_b32_e32 v157, v154
	v_mov_b32_e32 v154, v159
	v_mov_b32_e32 v194, v156
	v_pk_mul_f32 v[152:153], v[152:153], v[152:153]
	v_mov_b32_e32 v156, v158
	v_pk_mul_f32 v[154:155], v[154:155], v[154:155]
	v_pk_fma_f32 v[152:153], v[194:195], v[194:195], v[152:153]
	v_pk_fma_f32 v[154:155], v[156:157], v[156:157], v[154:155]
	s_nop 0
	v_pk_add_f32 v[152:153], v[152:153], v[154:155]
	s_nop 0
	v_add_f32_e32 v152, v152, v153
	v_add_f32_e32 v201, v201, v152
; __device__ __forceinline__ unsigned cvt_pk_bf16(float lo, float hi) { unsigned r; asm volatile("v_cvt_pk_bf16_f32 %0, %1, %2" : "=v"(r) : "v"(lo), "v"(hi)); return r; }
;     static __device__ __forceinline__ void run(const f32x4 (&acc)[2][2][4][2], const Unit& u, int wr, int wc, int fr, int fq, const float* xin, float* xout, const float* gate, float gs, const float* lazy_ssq, const float* lazy_g, ...
;     ...
;                 for (int j = 0; j < 2; ++j) { const int i_ = 2 * pp + j, ai = i_ >> 2, m = i_ & 3; const unsigned off = (row0 + ai * HALF + m * 16) * 1024u + col;
;                     const f32x4 xi0 = xq[pp & 1][j][0], xi1 = xq[pp & 1][j][1];
;                     f32x4 xo0 = gv[0] * acc[ai][bj][m][0], xo1 = gv[1] * acc[ai][bj][m][1];
;                     if (LAZY) { xo0 = xo0 + xi0 * lg[0] * rl[ai][m]; xo1 = xo1 + xi1 * lg[1] * rl[ai][m]; } else { xo0 = xo0 + xi0; xo1 = xo1 + xi1; }
;                     *(f32x4*)(xout + off) = xo0; *(f32x4*)(xout + off + 4) = xo1;
;                     if (aout) { const f32x4 a0 = xo0 * wv[0], a1 = xo1 * wv[1]; u32x4 w; w.x = cvt_pk_bf16(a0[0], a0[1]); w.y = cvt_pk_bf16(a0[2], a0[3]); w.z = cvt_pk_bf16(a1[0], a1[1]); w.w = cvt_pk_bf16(a1[2], a1[3]);
;                         *(u32x4*)(aout + off) = w;
;                         sq[ai][m] += ((xo0[0] * xo0[0] + xo0[1] * xo0[1]) + (xo0[2] * xo0[2] + xo0[3] * xo0[3])) + ((xo1[0] * xo1[0] + xo1[1] * xo1[1]) + (xo1[2] * xo1[2] + xo1[3] * xo1[3]));
;                         if (WG2) { const f32x4 b0 = xo0 * w2[0], b1 = xo1 * w2[1]; sqb[ai][m] += ((b0[0] * b0[0] + b0[1] * b0[1]) + (b0[2] * b0[2] + b0[3] * b0[3])) + ((b1[0] * b1[0] + b1[1] * b1[1]) + (b1[2] * b1[2] + b1[3] * b1[3])); } } }
.LBB0_517:
	s_nop 0
	v_add_u32_e32 v152, 0x24000, v176
	v_mov_b32_e32 v153, v177
	s_waitcnt vmcnt(0)
	v_pk_fma_f32 v[142:143], v[38:39], v[190:191], v[142:143]
	v_pk_fma_f32 v[140:141], v[36:37], v[192:193], v[140:141]
	v_pk_fma_f32 v[134:135], v[34:35], v[188:189], v[134:135]
	v_pk_fma_f32 v[132:133], v[32:33], v[174:175], v[132:133]
	v_lshl_add_u64 v[154:155], v[152:153], 2, s[28:29]
	s_and_b64 vcc, exec, s[8:9]
	global_store_dwordx4 v[154:155], v[140:143], off sc1
	global_store_dwordx4 v[154:155], v[132:135], off offset:16 sc1
	s_cbranch_vccnz .LBB0_519
	v_pk_mul_f32 v[156:157], v[184:185], v[142:143]
	v_pk_mul_f32 v[154:155], v[182:183], v[140:141]
	v_lshl_add_u64 v[152:153], v[152:153], 1, s[26:27]
	v_pk_mul_f32 v[158:159], v[186:187], v[134:135]
	v_pk_mul_f32 v[194:195], v[180:181], v[132:133]
	v_cvt_pk_bf16_f32 v154, v154, v155
	v_cvt_pk_bf16_f32 v155, v156, v157
	s_nop 0
	v_cvt_pk_bf16_f32 v156, v194, v195
	v_cvt_pk_bf16_f32 v157, v158, v159
	global_store_dwordx4 v[152:153], v[154:157], off sc1
	v_mov_b32_e32 v153, v132
	v_mov_b32_e32 v132, v141
	v_mov_b32_e32 v141, v134
	v_mov_b32_e32 v134, v143
	v_mov_b32_e32 v152, v140
	v_pk_mul_f32 v[132:133], v[132:133], v[132:133]
	v_mov_b32_e32 v140, v142
	v_pk_mul_f32 v[134:135], v[134:135], v[134:135]
	v_pk_fma_f32 v[132:133], v[152:153], v[152:153], v[132:133]
	v_pk_fma_f32 v[134:135], v[140:141], v[140:141], v[134:135]
	s_nop 0
	v_pk_add_f32 v[132:133], v[132:133], v[134:135]
	s_nop 0
	v_add_f32_e32 v132, v132, v133
	v_add_f32_e32 v200, v200, v132
.LBB0_519:
	v_add_u32_e32 v152, 0x28000, v176
	v_mov_b32_e32 v153, v177
	s_waitcnt vmcnt(0)
	v_pk_fma_f32 v[134:135], v[22:23], v[190:191], v[150:151]
	v_pk_fma_f32 v[132:133], v[20:21], v[192:193], v[148:149]
	v_pk_fma_f32 v[142:143], v[18:19], v[188:189], v[146:147]
	v_pk_fma_f32 v[140:141], v[16:17], v[174:175], v[144:145]
	v_lshl_add_u64 v[144:145], v[152:153], 2, s[28:29]
	s_and_b64 vcc, exec, s[8:9]
	global_store_dwordx4 v[144:145], v[132:135], off sc1
	global_store_dwordx4 v[144:145], v[140:143], off offset:16 sc1
	s_cbranch_vccnz .LBB0_521
	v_pk_mul_f32 v[146:147], v[184:185], v[134:135]
	v_pk_mul_f32 v[144:145], v[182:183], v[132:133]
	v_pk_mul_f32 v[148:149], v[186:187], v[142:143]
	v_pk_mul_f32 v[150:151], v[180:181], v[140:141]
	v_cvt_pk_bf16_f32 v144, v144, v145
	v_cvt_pk_bf16_f32 v145, v146, v147
	s_nop 0
	v_cvt_pk_bf16_f32 v146, v150, v151
	v_cvt_pk_bf16_f32 v147, v148, v149
	v_lshl_add_u64 v[148:149], v[152:153], 1, s[26:27]
	global_store_dwordx4 v[148:149], v[144:147], off sc1
	s_nop 1
	v_mov_b32_e32 v145, v140
	v_mov_b32_e32 v140, v133
	v_mov_b32_e32 v144, v132
	v_pk_mul_f32 v[132:133], v[140:141], v[140:141]
	v_mov_b32_e32 v141, v142
	v_mov_b32_e32 v142, v135
	v_mov_b32_e32 v140, v134
	v_pk_mul_f32 v[134:135], v[142:143], v[142:143]
	v_pk_fma_f32 v[132:133], v[144:145], v[144:145], v[132:133]
	v_pk_fma_f32 v[134:135], v[140:141], v[140:141], v[134:135]
	s_nop 0
	v_pk_add_f32 v[132:133], v[132:133], v[134:135]
	s_nop 0
	v_add_f32_e32 v132, v132, v133
	v_add_f32_e32 v206, v206, v132
.LBB0_521:
	v_add_u32_e32 v176, 0x2c000, v176
	s_waitcnt vmcnt(0)
	v_pk_fma_f32 v[134:135], v[6:7], v[190:191], v[138:139]
	v_pk_fma_f32 v[132:133], v[4:5], v[192:193], v[136:137]
	v_pk_fma_f32 v[130:131], v[2:3], v[188:189], v[130:131]
	v_pk_fma_f32 v[128:129], v[0:1], v[174:175], v[128:129]
	v_lshl_add_u64 v[136:137], v[176:177], 2, s[28:29]
	s_and_b64 vcc, exec, s[8:9]
	global_store_dwordx4 v[136:137], v[132:135], off sc1
	global_store_dwordx4 v[136:137], v[128:131], off offset:16 sc1
	s_cbranch_vccnz .LBB0_523
	v_pk_mul_f32 v[138:139], v[184:185], v[134:135]
	v_pk_mul_f32 v[136:137], v[182:183], v[132:133]
	v_pk_mul_f32 v[140:141], v[186:187], v[130:131]
	v_pk_mul_f32 v[142:143], v[180:181], v[128:129]
	v_cvt_pk_bf16_f32 v136, v136, v137
	v_cvt_pk_bf16_f32 v137, v138, v139
	s_nop 0
	v_cvt_pk_bf16_f32 v138, v142, v143
	v_cvt_pk_bf16_f32 v139, v140, v141
	v_lshl_add_u64 v[140:141], v[176:177], 1, s[26:27]
	global_store_dwordx4 v[140:141], v[136:139], off sc1
	s_nop 1
	v_mov_b32_e32 v137, v128
	v_mov_b32_e32 v128, v133
	v_mov_b32_e32 v133, v130
	v_mov_b32_e32 v130, v135
	v_mov_b32_e32 v136, v132
	v_pk_mul_f32 v[128:129], v[128:129], v[128:129]
	v_mov_b32_e32 v132, v134
	v_pk_mul_f32 v[130:131], v[130:131], v[130:131]
	v_pk_fma_f32 v[128:129], v[136:137], v[136:137], v[128:129]
	v_pk_fma_f32 v[130:131], v[132:133], v[132:133], v[130:131]
	s_nop 0
	v_pk_add_f32 v[128:129], v[128:129], v[130:131]
	s_nop 0
	v_add_f32_e32 v128, v128, v129
	v_add_f32_e32 v202, v202, v128
